# k6b
# speedup vs baseline: 1.0552x; 1.0552x over previous
.LBB0_5:
	s_cmpk_lt_i32 s72, 0x200
	s_cselect_b64 s[2:3], -1, 0
	v_writelane_b32 v254, s2, 38
	s_add_u32 s0, s0, 0x88
	s_addc_u32 s1, s1, 0
	v_writelane_b32 v254, s3, 39
	v_writelane_b32 v254, s0, 40
	s_cmpk_lt_i32 s72, 0x800
	v_mov_b32_e32 v253, 0
	v_writelane_b32 v254, s1, 41
	s_cselect_b64 s[0:1], -1, 0
	v_writelane_b32 v254, s0, 42
	s_movk_i32 s74, 0xe000
	s_movk_i32 s61, 0xff00
	v_writelane_b32 v254, s1, 43
	s_lshl_b32 s0, s72, 4
	s_cmpk_lt_i32 s72, 0x400
	v_writelane_b32 v254, s0, 44
	s_cselect_b64 s[0:1], -1, 0
	v_writelane_b32 v254, s0, 45
	s_mov_b32 s94, 0x1ffff80
	s_movk_i32 s95, 0x410
	v_writelane_b32 v254, s1, 46
	s_lshl_b32 s0, s72, 2
	v_writelane_b32 v254, s0, 47
	s_lshl_b32 s0, s72, 5
	s_cmpk_lt_i32 s72, 0x100
	v_writelane_b32 v254, s0, 48
	s_cselect_b64 s[0:1], -1, 0
	v_writelane_b32 v254, s0, 49
	s_cmpk_lt_i32 s72, 0xc00
	v_mov_b32_e32 v251, 0x3727c5ac
	v_writelane_b32 v254, s1, 50
	s_cselect_b64 s[0:1], -1, 0
	v_writelane_b32 v254, s0, 51
	s_movk_i32 s27, 0x90
	s_movk_i32 s23, 0x110
	v_writelane_b32 v254, s1, 52
	s_movk_i32 s33, 0xff80
	v_readlane_b32 s0, v254, 1
	v_readlane_b32 s14, v254, 15
	v_readlane_b32 s1, v254, 2
	v_readlane_b32 s15, v254, 16
	s_add_u32 s0, s14, 0x4031200
	s_addc_u32 s1, s15, 0
	s_add_u32 s30, s14, 0x4031400
	s_addc_u32 s31, s15, 0
	s_add_u32 s40, s14, 0x4031500
	s_addc_u32 s41, s15, 0
	s_add_u32 s66, s14, 0x4031600
	s_addc_u32 s67, s15, 0
	s_add_u32 s68, s14, 0x4031700
	s_addc_u32 s69, s15, 0
	s_add_u32 s70, s14, 0x4031800
	s_addc_u32 s71, s15, 0
	s_add_u32 s76, s14, 0x4031900
	s_addc_u32 s77, s15, 0
	s_add_u32 s78, s14, 0x4031a00
	s_addc_u32 s79, s15, 0
	s_add_u32 s80, s14, 0x4031b00
	s_addc_u32 s81, s15, 0
	s_add_u32 s82, s14, 0x4031c00
	s_addc_u32 s83, s15, 0
	s_add_u32 s84, s14, 0x4031d00
	s_addc_u32 s85, s15, 0
	s_add_u32 s86, s14, 0x4031e00
	s_addc_u32 s87, s15, 0
	s_add_u32 s88, s14, 0x4031f00
	s_addc_u32 s89, s15, 0
	s_add_u32 s90, s14, 0x4032000
	s_addc_u32 s91, s15, 0
	s_add_u32 s92, s14, 0x4032100
	v_readlane_b32 s2, v254, 3
	v_readlane_b32 s3, v254, 4
	v_readlane_b32 s4, v254, 5
	v_readlane_b32 s5, v254, 6
	v_readlane_b32 s6, v254, 7
	v_readlane_b32 s7, v254, 8
	v_readlane_b32 s8, v254, 9
	v_readlane_b32 s9, v254, 10
	v_readlane_b32 s10, v254, 11
	v_readlane_b32 s11, v254, 12
	v_readlane_b32 s12, v254, 13
	v_readlane_b32 s13, v254, 14
	v_writelane_b32 v254, s0, 53
	s_addc_u32 s93, s15, 0
	s_movk_i32 s25, 0x210
	v_writelane_b32 v254, s1, 54
	s_add_u32 s0, s14, 0x4032200
	s_addc_u32 s1, s15, 0
	v_writelane_b32 v254, s0, 55
	s_mov_b32 s43, 0x43e00000
	s_movk_i32 s37, 0x3fff
	v_writelane_b32 v254, s1, 56
	s_add_u32 s0, s14, 0x4032300
	s_addc_u32 s1, s15, 0
	v_writelane_b32 v254, s0, 57
	s_movk_i32 s63, 0x7fff
	s_brev_b32 s75, 1
	v_writelane_b32 v254, s1, 58
	s_add_u32 s0, s14, 0x4034400
	s_addc_u32 s1, s15, 0
	v_writelane_b32 v254, s0, 59
	s_mov_b32 s59, 0x15000
	s_mov_b32 s36, 0x1a100000
	v_writelane_b32 v254, s1, 60
	s_add_u32 s0, s14, 0x4034500
	s_addc_u32 s1, s15, 0
	v_writelane_b32 v254, s0, 61
	s_mov_b32 s35, 0
	s_mov_b64 s[48:49], 0x2418080
	v_writelane_b32 v254, s1, 62
	s_add_u32 s0, s4, 0xc00303c
	s_addc_u32 s1, s5, 0
	v_writelane_b32 v254, s0, 63
	s_mov_b64 s[28:29], 0x241c080
	s_mov_b32 s24, 0x3fd744fd
	v_writelane_b32 v255, s1, 0
	s_add_u32 s0, s14, 0x4100800
	s_addc_u32 s1, s15, 0
	v_writelane_b32 v255, s0, 1
	s_mov_b64 s[38:39], 0x8100080
	s_mov_b64 s[44:45], 0x8104080
	v_writelane_b32 v255, s1, 2
	s_add_u32 s0, s6, 0xc00303c
	s_addc_u32 s1, s7, 0
	v_writelane_b32 v255, s0, 3
	s_mov_b64 s[2:3], 0x8108080
	s_mov_b64 s[46:47], 0x810c080
	v_writelane_b32 v255, s1, 4
	s_add_u32 s0, s14, 0x6100800
	s_addc_u32 s1, s15, 0
	v_writelane_b32 v255, s0, 5
	s_mov_b64 s[50:51], 0x8110080
	s_mov_b64 s[52:53], 0x8114080
	v_writelane_b32 v255, s1, 6
	s_add_u32 s0, s4, 0x800303c
	s_addc_u32 s1, s5, 0
	v_writelane_b32 v255, s0, 7
	s_mov_b64 s[54:55], 0x8118080
	s_mov_b64 s[56:57], 0x811c080
	v_writelane_b32 v255, s1, 8
	s_add_u32 s0, s6, 0x800303c
	s_addc_u32 s1, s7, 0
	v_writelane_b32 v255, s0, 9
	s_mov_b32 s58, 0x3e38aa3b
	s_nop 0
	v_writelane_b32 v255, s1, 10
	s_add_u32 s0, s4, 0x303c
	s_addc_u32 s1, s5, 0
	v_writelane_b32 v255, s0, 11
	s_nop 1
	v_writelane_b32 v255, s1, 12
	s_add_u32 s0, s6, 0x303c
	s_addc_u32 s1, s7, 0
	v_writelane_b32 v255, s0, 13
	s_nop 1
	v_writelane_b32 v255, s1, 14
	v_writelane_b32 v255, s72, 15
	v_writelane_b32 v255, 0, 63
	s_nop 1
	v_writelane_b32 v255, s73, 16
	v_writelane_b32 v255, s30, 17
	s_nop 1
	v_writelane_b32 v255, s31, 18
	v_writelane_b32 v255, s40, 19
	s_nop 1
	v_writelane_b32 v255, s41, 20
	v_writelane_b32 v255, s66, 21
	s_nop 1
	v_writelane_b32 v255, s67, 22
	v_writelane_b32 v255, s68, 23
	s_nop 1
	v_writelane_b32 v255, s69, 24
	v_writelane_b32 v255, s70, 25
	s_nop 1
	v_writelane_b32 v255, s71, 26
	v_writelane_b32 v255, s76, 27
	s_nop 1
	v_writelane_b32 v255, s77, 28
	v_writelane_b32 v255, s78, 29
	s_nop 1
	v_writelane_b32 v255, s79, 30
	v_writelane_b32 v255, s80, 31
	s_nop 1
	v_writelane_b32 v255, s81, 32
	v_writelane_b32 v255, s82, 33
	s_nop 1
	v_writelane_b32 v255, s83, 34
	v_writelane_b32 v255, s84, 35
	s_nop 1
	v_writelane_b32 v255, s85, 36
	v_writelane_b32 v255, s86, 37
	s_nop 1
	v_writelane_b32 v255, s87, 38
	v_writelane_b32 v255, s88, 39
	s_nop 1
	v_writelane_b32 v255, s89, 40
	v_writelane_b32 v255, s90, 41
	s_nop 1
	v_writelane_b32 v255, s91, 42
	v_writelane_b32 v255, s92, 43
	s_nop 1
	v_writelane_b32 v255, s93, 44
	s_branch .LBB0_9

.LBB0_57:
	s_movk_i32 s6, 0xcfc4
	v_add_co_u32_e32 v2, vcc, 0xffffd000, v72
	s_mov_b32 s7, -1
	s_nop 0
	v_addc_co_u32_e32 v3, vcc, -1, v73, vcc
	v_lshl_add_u64 v[0:1], v[72:73], 0, s[6:7]
	global_load_dwordx4 v[60:63], v[2:3], off offset:-60
	global_load_dwordx4 v[48:51], v[0:1], off offset:48
	global_load_dwordx4 v[52:55], v[0:1], off offset:32
	global_load_dwordx4 v[56:59], v[0:1], off offset:16
	s_movk_i32 s6, 0xdfc4
	s_mov_b32 s7, -1
	v_lshl_add_u64 v[0:1], v[72:73], 0, s[6:7]
	v_add_co_u32_e32 v2, vcc, s74, v72
	s_movk_i32 s6, 0xefc4
	s_nop 0
	v_addc_co_u32_e32 v3, vcc, -1, v73, vcc
	s_mov_b32 s7, -1
	global_load_dwordx4 v[44:47], v[2:3], off offset:-60
	global_load_dwordx4 v[32:35], v[0:1], off offset:48
	global_load_dwordx4 v[36:39], v[0:1], off offset:32
	global_load_dwordx4 v[40:43], v[0:1], off offset:16
	v_lshl_add_u64 v[0:1], v[72:73], 0, s[6:7]
	s_movk_i32 s6, 0xf000
	v_add_co_u32_e32 v2, vcc, s6, v72
	s_mov_b32 s6, s35
	s_nop 0
	v_addc_co_u32_e32 v3, vcc, -1, v73, vcc
	global_load_dwordx4 v[28:31], v[2:3], off offset:-60
	global_load_dwordx4 v[16:19], v[0:1], off offset:48
	global_load_dwordx4 v[20:23], v[0:1], off offset:32
	global_load_dwordx4 v[24:27], v[0:1], off offset:16
	s_nop 0
	global_load_dwordx4 v[0:3], v[72:73], off offset:-12
	global_load_dwordx4 v[4:7], v[72:73], off offset:-28
	global_load_dwordx4 v[8:11], v[72:73], off offset:-44
	global_load_dwordx4 v[12:15], v[72:73], off offset:-60
	s_waitcnt vmcnt(15)
	v_max_f32_e64 v78, |v63|, |v63|
	v_max_f32_e64 v79, |v62|, |v62|
	v_max_f32_e32 v78, v79, v78
	s_waitcnt vmcnt(12)
	v_max_f32_e64 v79, |v59|, |v59|
	v_max_f32_e64 v80, |v58|, |v58|
	v_max_f32_e32 v79, v80, v79
	v_max_f32_e64 v80, |v53|, |v53|
	v_max_f32_e64 v81, |v52|, |v52|
	v_max_f32_e32 v80, v81, v80
	v_max_f32_e64 v81, |v55|, |v55|
	v_max_f32_e64 v82, |v54|, |v54|
	v_max_f32_e32 v81, v82, v81
	v_max_f32_e64 v82, |v51|, |v51|
	v_max_f32_e64 v83, |v50|, |v50|
	v_max_f32_e32 v82, v83, v82
	v_max3_f32 v82, |v48|, |v49|, v82
	v_max3_f32 v78, |v60|, |v61|, v78
	v_max3_f32 v79, |v56|, |v57|, v79
	v_max3_f32 v80, v80, v81, v82
	v_max3_f32 v78, v78, v79, v80
	v_mbcnt_lo_u32_b32 v79, -1, s6
	v_mbcnt_hi_u32_b32 v79, -1, v79
	v_lshlrev_b32_e32 v79, 2, v79
	v_xor_b32_e32 v80, 4, v79
	ds_bpermute_b32 v80, v80, v78
	s_waitcnt lgkmcnt(0)
	v_max_f32_e32 v80, v80, v80
	v_max_f32_e32 v78, v78, v80
	v_xor_b32_e32 v80, 8, v79
	ds_bpermute_b32 v80, v80, v78
	s_waitcnt lgkmcnt(0)
	v_max_f32_e32 v80, v80, v80
	v_max_f32_e32 v78, v78, v80
	v_xor_b32_e32 v80, 16, v79
	ds_bpermute_b32 v80, v80, v78
	s_waitcnt lgkmcnt(0)
	v_max_f32_e32 v80, v80, v80
	v_max_f32_e32 v78, v78, v80
	v_xor_b32_e32 v80, 32, v79
	ds_bpermute_b32 v80, v80, v78
	s_waitcnt lgkmcnt(0)
	v_max_f32_e32 v80, v80, v80
	v_max_f32_e32 v78, v78, v80
	v_xor_b32_e32 v80, 64, v79
	ds_bpermute_b32 v80, v80, v78
	v_xor_b32_e32 v79, 0x80, v79
	s_waitcnt lgkmcnt(0)
	v_max_f32_e32 v80, v80, v80
	v_max_f32_e32 v78, v78, v80
	ds_bpermute_b32 v79, v79, v78
	s_waitcnt lgkmcnt(0)
	v_max_f32_e32 v79, v79, v79
	v_max_f32_e32 v78, v78, v79
	v_div_scale_f32 v79, s[14:15], v78, v78, s43
	v_rcp_f32_e32 v80, v79
	v_cmp_lt_f32_e64 s[6:7], 0, v78
	v_fma_f32 v81, -v79, v80, 1.0
	v_fmac_f32_e32 v80, v81, v80
	v_div_scale_f32 v81, vcc, s43, v78, s43
	v_mul_f32_e32 v82, v81, v80
	v_fma_f32 v83, -v79, v82, v81
	v_fmac_f32_e32 v82, v83, v80
	v_fma_f32 v79, -v79, v82, v81
	v_div_fmas_f32 v79, v79, v80, v82
	v_div_fixup_f32 v79, v79, v78, s43
	v_cndmask_b32_e64 v79, 1.0, v79, s[6:7]
	v_mul_f32_e32 v80, v60, v79
	v_mul_f32_e32 v61, v61, v79
	v_mov_b32_e32 v60, v253
	v_cvt_pk_fp8_f32 v60, v80, v61
	v_mul_f32_e32 v61, v62, v79
	v_mul_f32_e32 v62, v63, v79
	v_mul_f32_e32 v56, v56, v79
	v_cvt_pk_fp8_f32 v60, v61, v62 op_sel:[0,0,1]
	v_mul_f32_e32 v57, v57, v79
	v_mov_b32_e32 v61, v253
	v_mul_f32_e32 v52, v52, v79
	v_mul_f32_e32 v53, v53, v79
	v_mov_b32_e32 v62, v253
	v_mul_f32_e32 v48, v48, v79
	v_mul_f32_e32 v49, v49, v79
	v_mov_b32_e32 v63, v253
	v_cvt_pk_fp8_f32 v61, v56, v57
	v_cvt_pk_fp8_f32 v62, v52, v53
	v_cvt_pk_fp8_f32 v63, v48, v49
	v_mul_f32_e32 v56, v58, v79
	v_mul_f32_e32 v57, v59, v79
	v_mul_f32_e32 v52, v54, v79
	v_mul_f32_e32 v53, v55, v79
	v_mul_f32_e32 v48, v50, v79
	v_mul_f32_e32 v49, v51, v79
	v_cvt_pk_fp8_f32 v61, v56, v57 op_sel:[0,0,1]
	v_cvt_pk_fp8_f32 v62, v52, v53 op_sel:[0,0,1]
	v_cvt_pk_fp8_f32 v63, v48, v49 op_sel:[0,0,1]
	v_lshl_add_u64 v[50:51], v[74:75], 0, s[96:97]
	v_lshl_add_u64 v[48:49], v[76:77], 0, s[96:97]
	s_add_u32 s98, s92, 0x4100000
	s_addc_u32 s99, s93, 0
	v_subrev_u32_e32 v100, s98, v50
	v_lshrrev_b32_e32 v100, 10, v100
	v_mbcnt_lo_u32_b32 v101, -1, 0
	v_mbcnt_hi_u32_b32 v101, -1, v101
	v_and_b32_e32 v102, 7, v101
	v_lshrrev_b32_e32 v101, 3, v101
	v_lshlrev_b32_e32 v101, 21, v101
	v_lshl_or_b32 v101, v102, 4, v101
	v_lshl_add_u32 v100, v100, 7, v101
	global_store_dwordx4 v100, v[60:63], s[98:99] offset:-256
	s_and_saveexec_b64 s[14:15], s[0:1]
	s_cbranch_execz .LBB0_59
	v_mul_f32_e32 v52, 0x3b124925, v78
	v_cndmask_b32_e64 v54, 1.0, v52, s[6:7]
	v_add_co_u32_e32 v52, vcc, 0x4040000, v48
	s_nop 1
	v_addc_co_u32_e32 v53, vcc, 0, v49, vcc
	global_store_dword v[52:53], v54, off
.LBB0_59:
	s_or_b64 exec, exec, s[14:15]
	s_waitcnt vmcnt(12)
	v_max_f32_e64 v52, |v47|, |v47|
	v_max_f32_e64 v53, |v46|, |v46|
	v_max_f32_e32 v52, v53, v52
	s_waitcnt vmcnt(9)
	v_max_f32_e64 v53, |v43|, |v43|
	v_max_f32_e64 v54, |v42|, |v42|
	v_max_f32_e32 v53, v54, v53
	v_max_f32_e64 v54, |v37|, |v37|
	v_max_f32_e64 v55, |v36|, |v36|
	v_max_f32_e32 v54, v55, v54
	v_max_f32_e64 v55, |v39|, |v39|
	v_max_f32_e64 v56, |v38|, |v38|
	v_max_f32_e32 v55, v56, v55
	v_max_f32_e64 v56, |v35|, |v35|
	v_max_f32_e64 v57, |v34|, |v34|
	v_max_f32_e32 v56, v57, v56
	v_max3_f32 v56, |v32|, |v33|, v56
	v_max3_f32 v52, |v44|, |v45|, v52
	v_max3_f32 v53, |v40|, |v41|, v53
	v_max3_f32 v54, v54, v55, v56
	s_mov_b32 s6, s35
	v_max3_f32 v52, v52, v53, v54
	s_nop 0
	v_mbcnt_lo_u32_b32 v53, -1, s6
	v_mbcnt_hi_u32_b32 v53, -1, v53
	v_lshlrev_b32_e32 v53, 2, v53
	v_xor_b32_e32 v54, 4, v53
	ds_bpermute_b32 v54, v54, v52
	s_waitcnt lgkmcnt(0)
	v_max_f32_e32 v54, v54, v54
	v_max_f32_e32 v52, v52, v54
	v_xor_b32_e32 v54, 8, v53
	ds_bpermute_b32 v54, v54, v52
	s_waitcnt lgkmcnt(0)
	v_max_f32_e32 v54, v54, v54
	v_max_f32_e32 v52, v52, v54
	v_xor_b32_e32 v54, 16, v53
	ds_bpermute_b32 v54, v54, v52
	s_waitcnt lgkmcnt(0)
	v_max_f32_e32 v54, v54, v54
	v_max_f32_e32 v52, v52, v54
	v_xor_b32_e32 v54, 32, v53
	ds_bpermute_b32 v54, v54, v52
	s_waitcnt lgkmcnt(0)
	v_max_f32_e32 v54, v54, v54
	v_max_f32_e32 v52, v52, v54
	v_xor_b32_e32 v54, 64, v53
	ds_bpermute_b32 v54, v54, v52
	v_xor_b32_e32 v53, 0x80, v53
	s_waitcnt lgkmcnt(0)
	v_max_f32_e32 v54, v54, v54
	v_max_f32_e32 v52, v52, v54
	ds_bpermute_b32 v53, v53, v52
	s_waitcnt lgkmcnt(0)
	v_max_f32_e32 v53, v53, v53
	v_max_f32_e32 v52, v52, v53
	v_div_scale_f32 v53, s[6:7], v52, v52, s43
	v_rcp_f32_e32 v54, v53
	s_nop 0
	v_fma_f32 v55, -v53, v54, 1.0
	v_fmac_f32_e32 v54, v55, v54
	v_div_scale_f32 v55, vcc, s43, v52, s43
	v_mul_f32_e32 v56, v55, v54
	v_fma_f32 v57, -v53, v56, v55
	v_fmac_f32_e32 v56, v57, v54
	v_fma_f32 v53, -v53, v56, v55
	v_div_fmas_f32 v53, v53, v54, v56
	v_div_fixup_f32 v53, v53, v52, s43
	v_cmp_lt_f32_e32 vcc, 0, v52
	s_nop 1
	v_cndmask_b32_e32 v53, 1.0, v53, vcc
	v_mul_f32_e32 v54, v44, v53
	v_mul_f32_e32 v45, v45, v53
	v_mov_b32_e32 v44, v253
	v_cvt_pk_fp8_f32 v44, v54, v45
	v_mul_f32_e32 v46, v46, v53
	v_mul_f32_e32 v47, v47, v53
	v_mul_f32_e32 v40, v40, v53
	v_mul_f32_e32 v41, v41, v53
	v_mov_b32_e32 v45, v253
	v_cvt_pk_fp8_f32 v44, v46, v47 op_sel:[0,0,1]
	v_mul_f32_e32 v36, v36, v53
	v_mul_f32_e32 v37, v37, v53
	v_mov_b32_e32 v46, v253
	v_mul_f32_e32 v32, v32, v53
	v_mul_f32_e32 v33, v33, v53
	v_mov_b32_e32 v47, v253
	v_cvt_pk_fp8_f32 v45, v40, v41
	v_cvt_pk_fp8_f32 v46, v36, v37
	v_cvt_pk_fp8_f32 v47, v32, v33
	v_mul_f32_e32 v40, v42, v53
	v_mul_f32_e32 v41, v43, v53
	v_mul_f32_e32 v36, v38, v53
	v_mul_f32_e32 v37, v39, v53
	v_mul_f32_e32 v32, v34, v53
	v_mul_f32_e32 v33, v35, v53
	v_cvt_pk_fp8_f32 v45, v40, v41 op_sel:[0,0,1]
	v_cvt_pk_fp8_f32 v46, v36, v37 op_sel:[0,0,1]
	v_cvt_pk_fp8_f32 v47, v32, v33 op_sel:[0,0,1]
	s_add_u32 s98, s92, 0x4100000
	s_addc_u32 s99, s93, 0
	v_subrev_u32_e32 v100, s98, v50
	v_lshrrev_b32_e32 v100, 10, v100
	v_mbcnt_lo_u32_b32 v101, -1, 0
	v_mbcnt_hi_u32_b32 v101, -1, v101
	v_and_b32_e32 v102, 7, v101
	v_lshrrev_b32_e32 v101, 3, v101
	v_lshlrev_b32_e32 v101, 21, v101
	v_lshl_or_b32 v101, v102, 4, v101
	v_lshl_add_u32 v100, v100, 7, v101
	global_store_dwordx4 v100, v[44:47], s[98:99] offset:-128
	s_and_saveexec_b64 s[6:7], s[0:1]
	s_cbranch_execz .LBB0_61
	v_mul_f32_e32 v32, 0x3b124925, v52
	v_cndmask_b32_e32 v34, 1.0, v32, vcc
	v_add_co_u32_e32 v32, vcc, 0x4040000, v48
	s_nop 1
	v_addc_co_u32_e32 v33, vcc, 0, v49, vcc
	global_store_dword v[32:33], v34, off offset:4
.LBB0_61:
	s_or_b64 exec, exec, s[6:7]
	s_waitcnt vmcnt(9)
	v_max_f32_e64 v32, |v31|, |v31|
	v_max_f32_e64 v33, |v30|, |v30|
	v_max_f32_e32 v32, v33, v32
	s_waitcnt vmcnt(6)
	v_max_f32_e64 v33, |v27|, |v27|
	v_max_f32_e64 v34, |v26|, |v26|
	v_max_f32_e32 v33, v34, v33
	v_max_f32_e64 v34, |v21|, |v21|
	v_max_f32_e64 v35, |v20|, |v20|
	v_max_f32_e32 v34, v35, v34
	v_max_f32_e64 v35, |v23|, |v23|
	v_max_f32_e64 v36, |v22|, |v22|
	v_max_f32_e32 v35, v36, v35
	v_max_f32_e64 v36, |v19|, |v19|
	v_max_f32_e64 v37, |v18|, |v18|
	v_max_f32_e32 v36, v37, v36
	v_max3_f32 v36, |v16|, |v17|, v36
	v_max3_f32 v32, |v28|, |v29|, v32
	v_max3_f32 v33, |v24|, |v25|, v33
	v_max3_f32 v34, v34, v35, v36
	s_mov_b32 s6, s35
	v_max3_f32 v32, v32, v33, v34
	s_nop 0
	v_mbcnt_lo_u32_b32 v33, -1, s6
	v_mbcnt_hi_u32_b32 v33, -1, v33
	v_lshlrev_b32_e32 v33, 2, v33
	v_xor_b32_e32 v34, 4, v33
	ds_bpermute_b32 v34, v34, v32
	s_waitcnt lgkmcnt(0)
	v_max_f32_e32 v34, v34, v34
	v_max_f32_e32 v32, v32, v34
	v_xor_b32_e32 v34, 8, v33
	ds_bpermute_b32 v34, v34, v32
	s_waitcnt lgkmcnt(0)
	v_max_f32_e32 v34, v34, v34
	v_max_f32_e32 v32, v32, v34
	v_xor_b32_e32 v34, 16, v33
	ds_bpermute_b32 v34, v34, v32
	s_waitcnt lgkmcnt(0)
	v_max_f32_e32 v34, v34, v34
	v_max_f32_e32 v32, v32, v34
	v_xor_b32_e32 v34, 32, v33
	ds_bpermute_b32 v34, v34, v32
	s_waitcnt lgkmcnt(0)
	v_max_f32_e32 v34, v34, v34
	v_max_f32_e32 v32, v32, v34
	v_xor_b32_e32 v34, 64, v33
	ds_bpermute_b32 v34, v34, v32
	v_xor_b32_e32 v33, 0x80, v33
	s_waitcnt lgkmcnt(0)
	v_max_f32_e32 v34, v34, v34
	v_max_f32_e32 v32, v32, v34
	ds_bpermute_b32 v33, v33, v32
	s_waitcnt lgkmcnt(0)
	v_max_f32_e32 v33, v33, v33
	v_max_f32_e32 v32, v32, v33
	v_div_scale_f32 v33, s[6:7], v32, v32, s43
	v_rcp_f32_e32 v34, v33
	s_nop 0
	v_fma_f32 v35, -v33, v34, 1.0
	v_fmac_f32_e32 v34, v35, v34
	v_div_scale_f32 v35, vcc, s43, v32, s43
	v_mul_f32_e32 v36, v35, v34
	v_fma_f32 v37, -v33, v36, v35
	v_fmac_f32_e32 v36, v37, v34
	v_fma_f32 v33, -v33, v36, v35
	v_div_fmas_f32 v33, v33, v34, v36
	v_div_fixup_f32 v33, v33, v32, s43
	v_cmp_lt_f32_e32 vcc, 0, v32
	s_nop 1
	v_cndmask_b32_e32 v33, 1.0, v33, vcc
	v_mul_f32_e32 v34, v28, v33
	v_mul_f32_e32 v29, v29, v33
	v_mov_b32_e32 v28, v253
	v_cvt_pk_fp8_f32 v28, v34, v29
	v_mul_f32_e32 v30, v30, v33
	v_mul_f32_e32 v31, v31, v33
	v_mul_f32_e32 v24, v24, v33
	v_mul_f32_e32 v25, v25, v33
	v_mov_b32_e32 v29, v253
	v_cvt_pk_fp8_f32 v28, v30, v31 op_sel:[0,0,1]
	v_mul_f32_e32 v20, v20, v33
	v_mul_f32_e32 v21, v21, v33
	v_mov_b32_e32 v30, v253
	v_mul_f32_e32 v16, v16, v33
	v_mul_f32_e32 v17, v17, v33
	v_mov_b32_e32 v31, v253
	v_cvt_pk_fp8_f32 v29, v24, v25
	v_cvt_pk_fp8_f32 v30, v20, v21
	v_cvt_pk_fp8_f32 v31, v16, v17
	v_mul_f32_e32 v24, v26, v33
	v_mul_f32_e32 v25, v27, v33
	v_mul_f32_e32 v20, v22, v33
	v_mul_f32_e32 v21, v23, v33
	v_mul_f32_e32 v16, v18, v33
	v_mul_f32_e32 v17, v19, v33
	v_cvt_pk_fp8_f32 v29, v24, v25 op_sel:[0,0,1]
	v_cvt_pk_fp8_f32 v30, v20, v21 op_sel:[0,0,1]
	v_cvt_pk_fp8_f32 v31, v16, v17 op_sel:[0,0,1]
	s_add_u32 s98, s92, 0x4100000
	s_addc_u32 s99, s93, 0
	v_subrev_u32_e32 v100, s98, v50
	v_lshrrev_b32_e32 v100, 10, v100
	v_mbcnt_lo_u32_b32 v101, -1, 0
	v_mbcnt_hi_u32_b32 v101, -1, v101
	v_and_b32_e32 v102, 7, v101
	v_lshrrev_b32_e32 v101, 3, v101
	v_lshlrev_b32_e32 v101, 21, v101
	v_lshl_or_b32 v101, v102, 4, v101
	v_lshl_add_u32 v100, v100, 7, v101
	global_store_dwordx4 v100, v[28:31], s[98:99]
	s_and_saveexec_b64 s[6:7], s[0:1]
	s_cbranch_execz .LBB0_63
	v_mul_f32_e32 v16, 0x3b124925, v32
	v_cndmask_b32_e32 v18, 1.0, v16, vcc
	v_add_co_u32_e32 v16, vcc, 0x4040000, v48
	s_nop 1
	v_addc_co_u32_e32 v17, vcc, 0, v49, vcc
	global_store_dword v[16:17], v18, off offset:8
.LBB0_63:
	s_or_b64 exec, exec, s[6:7]
	s_waitcnt vmcnt(3)
	v_max_f32_e64 v16, |v15|, |v15|
	v_max_f32_e64 v17, |v14|, |v14|
	v_max_f32_e32 v16, v17, v16
	v_max_f32_e64 v17, |v11|, |v11|
	v_max_f32_e64 v18, |v10|, |v10|
	v_max_f32_e32 v17, v18, v17
	v_max_f32_e64 v18, |v5|, |v5|
	v_max_f32_e64 v19, |v4|, |v4|
	v_max_f32_e32 v18, v19, v18
	v_max_f32_e64 v19, |v7|, |v7|
	v_max_f32_e64 v20, |v6|, |v6|
	v_max_f32_e32 v19, v20, v19
	v_max_f32_e64 v20, |v3|, |v3|
	v_max_f32_e64 v21, |v2|, |v2|
	v_max_f32_e32 v20, v21, v20
	v_max3_f32 v20, |v0|, |v1|, v20
	v_max3_f32 v16, |v12|, |v13|, v16
	v_max3_f32 v17, |v8|, |v9|, v17
	v_max3_f32 v18, v18, v19, v20
	s_mov_b32 s6, s35
	v_max3_f32 v16, v16, v17, v18
	s_nop 0
	v_mbcnt_lo_u32_b32 v17, -1, s6
	v_mbcnt_hi_u32_b32 v17, -1, v17
	v_lshlrev_b32_e32 v17, 2, v17
	v_xor_b32_e32 v18, 4, v17
	ds_bpermute_b32 v18, v18, v16
	s_waitcnt lgkmcnt(0)
	v_max_f32_e32 v18, v18, v18
	v_max_f32_e32 v16, v16, v18
	v_xor_b32_e32 v18, 8, v17
	ds_bpermute_b32 v18, v18, v16
	s_waitcnt lgkmcnt(0)
	v_max_f32_e32 v18, v18, v18
	v_max_f32_e32 v16, v16, v18
	v_xor_b32_e32 v18, 16, v17
	ds_bpermute_b32 v18, v18, v16
	s_waitcnt lgkmcnt(0)
	v_max_f32_e32 v18, v18, v18
	v_max_f32_e32 v16, v16, v18
	v_xor_b32_e32 v18, 32, v17
	ds_bpermute_b32 v18, v18, v16
	s_waitcnt lgkmcnt(0)
	v_max_f32_e32 v18, v18, v18
	v_max_f32_e32 v16, v16, v18
	v_xor_b32_e32 v18, 64, v17
	ds_bpermute_b32 v18, v18, v16
	v_xor_b32_e32 v17, 0x80, v17
	s_waitcnt lgkmcnt(0)
	v_max_f32_e32 v18, v18, v18
	v_max_f32_e32 v16, v16, v18
	ds_bpermute_b32 v17, v17, v16
	s_waitcnt lgkmcnt(0)
	v_max_f32_e32 v17, v17, v17
	v_max_f32_e32 v16, v16, v17
	v_div_scale_f32 v17, s[6:7], v16, v16, s43
	v_rcp_f32_e32 v18, v17
	s_nop 0
	v_fma_f32 v19, -v17, v18, 1.0
	v_fmac_f32_e32 v18, v19, v18
	v_div_scale_f32 v19, vcc, s43, v16, s43
	v_mul_f32_e32 v20, v19, v18
	v_fma_f32 v21, -v17, v20, v19
	v_fmac_f32_e32 v20, v21, v18
	v_fma_f32 v17, -v17, v20, v19
	v_div_fmas_f32 v17, v17, v18, v20
	v_div_fixup_f32 v17, v17, v16, s43
	v_cmp_lt_f32_e32 vcc, 0, v16
	s_nop 1
	v_cndmask_b32_e32 v17, 1.0, v17, vcc
	v_mul_f32_e32 v18, v12, v17
	v_mul_f32_e32 v13, v13, v17
	v_mov_b32_e32 v12, v253
	v_cvt_pk_fp8_f32 v12, v18, v13
	v_mul_f32_e32 v14, v14, v17
	v_mul_f32_e32 v15, v15, v17
	v_mul_f32_e32 v8, v8, v17
	v_mul_f32_e32 v9, v9, v17
	v_mov_b32_e32 v13, v253
	v_cvt_pk_fp8_f32 v12, v14, v15 op_sel:[0,0,1]
	v_mul_f32_e32 v4, v4, v17
	v_mul_f32_e32 v5, v5, v17
	v_mov_b32_e32 v14, v253
	v_mul_f32_e32 v0, v0, v17
	v_mul_f32_e32 v1, v1, v17
	v_mov_b32_e32 v15, v253
	v_cvt_pk_fp8_f32 v13, v8, v9
	v_cvt_pk_fp8_f32 v14, v4, v5
	v_cvt_pk_fp8_f32 v15, v0, v1
	v_mul_f32_e32 v8, v10, v17
	v_mul_f32_e32 v9, v11, v17
	v_mul_f32_e32 v4, v6, v17
	v_mul_f32_e32 v5, v7, v17
	v_mul_f32_e32 v0, v2, v17
	v_mul_f32_e32 v1, v3, v17
	v_cvt_pk_fp8_f32 v13, v8, v9 op_sel:[0,0,1]
	v_cvt_pk_fp8_f32 v14, v4, v5 op_sel:[0,0,1]
	v_cvt_pk_fp8_f32 v15, v0, v1 op_sel:[0,0,1]
	s_add_u32 s98, s92, 0x4100000
	s_addc_u32 s99, s93, 0
	v_subrev_u32_e32 v100, s98, v50
	v_lshrrev_b32_e32 v100, 10, v100
	v_mbcnt_lo_u32_b32 v101, -1, 0
	v_mbcnt_hi_u32_b32 v101, -1, v101
	v_and_b32_e32 v102, 7, v101
	v_lshrrev_b32_e32 v101, 3, v101
	v_lshlrev_b32_e32 v101, 21, v101
	v_lshl_or_b32 v101, v102, 4, v101
	v_lshl_add_u32 v100, v100, 7, v101
	global_store_dwordx4 v100, v[12:15], s[98:99] offset:128
	s_and_saveexec_b64 s[6:7], s[0:1]
	s_cbranch_execz .LBB0_56
	v_mul_f32_e32 v0, 0x3b124925, v16
	v_cndmask_b32_e32 v2, 1.0, v0, vcc
	v_add_co_u32_e32 v0, vcc, 0x4040000, v48
	s_nop 1
	v_addc_co_u32_e32 v1, vcc, 0, v49, vcc
	global_store_dword v[0:1], v2, off offset:12
	s_branch .LBB0_56

.LBB0_67:
	s_movk_i32 s6, 0xcfc4
	v_add_co_u32_e32 v2, vcc, 0xffffd000, v68
	s_mov_b32 s7, -1
	s_nop 0
	v_addc_co_u32_e32 v3, vcc, -1, v69, vcc
	v_lshl_add_u64 v[0:1], v[68:69], 0, s[6:7]
	global_load_dwordx4 v[60:63], v[2:3], off offset:-60
	global_load_dwordx4 v[48:51], v[0:1], off offset:48
	global_load_dwordx4 v[52:55], v[0:1], off offset:32
	global_load_dwordx4 v[56:59], v[0:1], off offset:16
	s_movk_i32 s6, 0xdfc4
	s_mov_b32 s7, -1
	v_lshl_add_u64 v[0:1], v[68:69], 0, s[6:7]
	v_add_co_u32_e32 v2, vcc, s74, v68
	s_movk_i32 s6, 0xefc4
	s_nop 0
	v_addc_co_u32_e32 v3, vcc, -1, v69, vcc
	s_mov_b32 s7, -1
	global_load_dwordx4 v[44:47], v[2:3], off offset:-60
	global_load_dwordx4 v[32:35], v[0:1], off offset:48
	global_load_dwordx4 v[36:39], v[0:1], off offset:32
	global_load_dwordx4 v[40:43], v[0:1], off offset:16
	v_lshl_add_u64 v[0:1], v[68:69], 0, s[6:7]
	s_movk_i32 s6, 0xf000
	v_add_co_u32_e32 v2, vcc, s6, v68
	s_mov_b32 s6, s35
	s_nop 0
	v_addc_co_u32_e32 v3, vcc, -1, v69, vcc
	global_load_dwordx4 v[28:31], v[2:3], off offset:-60
	global_load_dwordx4 v[16:19], v[0:1], off offset:48
	global_load_dwordx4 v[20:23], v[0:1], off offset:32
	global_load_dwordx4 v[24:27], v[0:1], off offset:16
	s_nop 0
	global_load_dwordx4 v[0:3], v[68:69], off offset:-12
	global_load_dwordx4 v[4:7], v[68:69], off offset:-28
	global_load_dwordx4 v[8:11], v[68:69], off offset:-44
	global_load_dwordx4 v[12:15], v[68:69], off offset:-60
	s_waitcnt vmcnt(15)
	v_max_f32_e64 v65, |v63|, |v63|
	v_max_f32_e64 v72, |v62|, |v62|
	v_max_f32_e32 v65, v72, v65
	s_waitcnt vmcnt(12)
	v_max_f32_e64 v72, |v59|, |v59|
	v_max_f32_e64 v73, |v58|, |v58|
	v_max_f32_e32 v72, v73, v72
	v_max_f32_e64 v73, |v53|, |v53|
	v_max_f32_e64 v74, |v52|, |v52|
	v_max_f32_e32 v73, v74, v73
	v_max_f32_e64 v74, |v55|, |v55|
	v_max_f32_e64 v75, |v54|, |v54|
	v_max_f32_e32 v74, v75, v74
	v_max_f32_e64 v75, |v51|, |v51|
	v_max_f32_e64 v76, |v50|, |v50|
	v_max_f32_e32 v75, v76, v75
	v_max3_f32 v75, |v48|, |v49|, v75
	v_max3_f32 v65, |v60|, |v61|, v65
	v_max3_f32 v72, |v56|, |v57|, v72
	v_max3_f32 v73, v73, v74, v75
	v_max3_f32 v65, v65, v72, v73
	v_mbcnt_lo_u32_b32 v72, -1, s6
	v_mbcnt_hi_u32_b32 v72, -1, v72
	v_lshlrev_b32_e32 v72, 2, v72
	v_xor_b32_e32 v73, 4, v72
	ds_bpermute_b32 v73, v73, v65
	s_waitcnt lgkmcnt(0)
	v_max_f32_e32 v73, v73, v73
	v_max_f32_e32 v65, v65, v73
	v_xor_b32_e32 v73, 8, v72
	ds_bpermute_b32 v73, v73, v65
	s_waitcnt lgkmcnt(0)
	v_max_f32_e32 v73, v73, v73
	v_max_f32_e32 v65, v65, v73
	v_xor_b32_e32 v73, 16, v72
	ds_bpermute_b32 v73, v73, v65
	s_waitcnt lgkmcnt(0)
	v_max_f32_e32 v73, v73, v73
	v_max_f32_e32 v65, v65, v73
	v_xor_b32_e32 v73, 32, v72
	ds_bpermute_b32 v73, v73, v65
	s_waitcnt lgkmcnt(0)
	v_max_f32_e32 v73, v73, v73
	v_max_f32_e32 v65, v65, v73
	v_xor_b32_e32 v73, 64, v72
	ds_bpermute_b32 v73, v73, v65
	v_xor_b32_e32 v72, 0x80, v72
	s_waitcnt lgkmcnt(0)
	v_max_f32_e32 v73, v73, v73
	v_max_f32_e32 v65, v65, v73
	ds_bpermute_b32 v72, v72, v65
	s_waitcnt lgkmcnt(0)
	v_max_f32_e32 v72, v72, v72
	v_max_f32_e32 v65, v65, v72
	v_div_scale_f32 v72, s[14:15], v65, v65, s43
	v_rcp_f32_e32 v73, v72
	v_cmp_lt_f32_e64 s[6:7], 0, v65
	v_fma_f32 v74, -v72, v73, 1.0
	v_fmac_f32_e32 v73, v74, v73
	v_div_scale_f32 v74, vcc, s43, v65, s43
	v_mul_f32_e32 v75, v74, v73
	v_fma_f32 v76, -v72, v75, v74
	v_fmac_f32_e32 v75, v76, v73
	v_fma_f32 v72, -v72, v75, v74
	v_div_fmas_f32 v72, v72, v73, v75
	v_div_fixup_f32 v72, v72, v65, s43
	v_cndmask_b32_e64 v72, 1.0, v72, s[6:7]
	v_mul_f32_e32 v73, v60, v72
	v_mul_f32_e32 v61, v61, v72
	v_mov_b32_e32 v60, v253
	v_cvt_pk_fp8_f32 v60, v73, v61
	v_mul_f32_e32 v61, v62, v72
	v_mul_f32_e32 v62, v63, v72
	v_mul_f32_e32 v56, v56, v72
	v_cvt_pk_fp8_f32 v60, v61, v62 op_sel:[0,0,1]
	v_mul_f32_e32 v57, v57, v72
	v_mov_b32_e32 v61, v253
	v_mul_f32_e32 v52, v52, v72
	v_mul_f32_e32 v53, v53, v72
	v_mov_b32_e32 v62, v253
	v_mul_f32_e32 v48, v48, v72
	v_mul_f32_e32 v49, v49, v72
	v_mov_b32_e32 v63, v253
	v_cvt_pk_fp8_f32 v61, v56, v57
	v_cvt_pk_fp8_f32 v62, v52, v53
	v_cvt_pk_fp8_f32 v63, v48, v49
	v_mul_f32_e32 v56, v58, v72
	v_mul_f32_e32 v57, v59, v72
	v_mul_f32_e32 v52, v54, v72
	v_mul_f32_e32 v53, v55, v72
	v_mul_f32_e32 v48, v50, v72
	v_mul_f32_e32 v49, v51, v72
	v_cvt_pk_fp8_f32 v61, v56, v57 op_sel:[0,0,1]
	v_cvt_pk_fp8_f32 v62, v52, v53 op_sel:[0,0,1]
	v_cvt_pk_fp8_f32 v63, v48, v49 op_sel:[0,0,1]
	v_lshl_add_u64 v[50:51], v[70:71], 0, s[96:97]
	v_lshl_add_u64 v[48:49], v[66:67], 0, s[96:97]
	s_add_u32 s98, s92, 0x6100000
	s_addc_u32 s99, s93, 0
	v_subrev_u32_e32 v100, s98, v50
	v_lshrrev_b32_e32 v100, 10, v100
	v_mbcnt_lo_u32_b32 v101, -1, 0
	v_mbcnt_hi_u32_b32 v101, -1, v101
	v_and_b32_e32 v102, 7, v101
	v_lshrrev_b32_e32 v101, 3, v101
	v_lshlrev_b32_e32 v101, 21, v101
	v_lshl_or_b32 v101, v102, 4, v101
	v_lshl_add_u32 v100, v100, 7, v101
	global_store_dwordx4 v100, v[60:63], s[98:99] offset:-256
	s_and_saveexec_b64 s[14:15], s[0:1]
	s_cbranch_execz .LBB0_69
	v_mul_f32_e32 v52, 0x3b124925, v65
	v_cndmask_b32_e64 v54, 1.0, v52, s[6:7]
	v_add_co_u32_e32 v52, vcc, 0x4080000, v48
	s_nop 1
	v_addc_co_u32_e32 v53, vcc, 0, v49, vcc
	global_store_dword v[52:53], v54, off
.LBB0_69:
	s_or_b64 exec, exec, s[14:15]
	s_waitcnt vmcnt(12)
	v_max_f32_e64 v52, |v47|, |v47|
	v_max_f32_e64 v53, |v46|, |v46|
	v_max_f32_e32 v52, v53, v52
	s_waitcnt vmcnt(9)
	v_max_f32_e64 v53, |v43|, |v43|
	v_max_f32_e64 v54, |v42|, |v42|
	v_max_f32_e32 v53, v54, v53
	v_max_f32_e64 v54, |v37|, |v37|
	v_max_f32_e64 v55, |v36|, |v36|
	v_max_f32_e32 v54, v55, v54
	v_max_f32_e64 v55, |v39|, |v39|
	v_max_f32_e64 v56, |v38|, |v38|
	v_max_f32_e32 v55, v56, v55
	v_max_f32_e64 v56, |v35|, |v35|
	v_max_f32_e64 v57, |v34|, |v34|
	v_max_f32_e32 v56, v57, v56
	v_max3_f32 v56, |v32|, |v33|, v56
	v_max3_f32 v52, |v44|, |v45|, v52
	v_max3_f32 v53, |v40|, |v41|, v53
	v_max3_f32 v54, v54, v55, v56
	s_mov_b32 s6, s35
	v_max3_f32 v52, v52, v53, v54
	s_nop 0
	v_mbcnt_lo_u32_b32 v53, -1, s6
	v_mbcnt_hi_u32_b32 v53, -1, v53
	v_lshlrev_b32_e32 v53, 2, v53
	v_xor_b32_e32 v54, 4, v53
	ds_bpermute_b32 v54, v54, v52
	s_waitcnt lgkmcnt(0)
	v_max_f32_e32 v54, v54, v54
	v_max_f32_e32 v52, v52, v54
	v_xor_b32_e32 v54, 8, v53
	ds_bpermute_b32 v54, v54, v52
	s_waitcnt lgkmcnt(0)
	v_max_f32_e32 v54, v54, v54
	v_max_f32_e32 v52, v52, v54
	v_xor_b32_e32 v54, 16, v53
	ds_bpermute_b32 v54, v54, v52
	s_waitcnt lgkmcnt(0)
	v_max_f32_e32 v54, v54, v54
	v_max_f32_e32 v52, v52, v54
	v_xor_b32_e32 v54, 32, v53
	ds_bpermute_b32 v54, v54, v52
	s_waitcnt lgkmcnt(0)
	v_max_f32_e32 v54, v54, v54
	v_max_f32_e32 v52, v52, v54
	v_xor_b32_e32 v54, 64, v53
	ds_bpermute_b32 v54, v54, v52
	v_xor_b32_e32 v53, 0x80, v53
	s_waitcnt lgkmcnt(0)
	v_max_f32_e32 v54, v54, v54
	v_max_f32_e32 v52, v52, v54
	ds_bpermute_b32 v53, v53, v52
	s_waitcnt lgkmcnt(0)
	v_max_f32_e32 v53, v53, v53
	v_max_f32_e32 v52, v52, v53
	v_div_scale_f32 v53, s[6:7], v52, v52, s43
	v_rcp_f32_e32 v54, v53
	s_nop 0
	v_fma_f32 v55, -v53, v54, 1.0
	v_fmac_f32_e32 v54, v55, v54
	v_div_scale_f32 v55, vcc, s43, v52, s43
	v_mul_f32_e32 v56, v55, v54
	v_fma_f32 v57, -v53, v56, v55
	v_fmac_f32_e32 v56, v57, v54
	v_fma_f32 v53, -v53, v56, v55
	v_div_fmas_f32 v53, v53, v54, v56
	v_div_fixup_f32 v53, v53, v52, s43
	v_cmp_lt_f32_e32 vcc, 0, v52
	s_nop 1
	v_cndmask_b32_e32 v53, 1.0, v53, vcc
	v_mul_f32_e32 v54, v44, v53
	v_mul_f32_e32 v45, v45, v53
	v_mov_b32_e32 v44, v253
	v_cvt_pk_fp8_f32 v44, v54, v45
	v_mul_f32_e32 v46, v46, v53
	v_mul_f32_e32 v47, v47, v53
	v_mul_f32_e32 v40, v40, v53
	v_mul_f32_e32 v41, v41, v53
	v_mov_b32_e32 v45, v253
	v_cvt_pk_fp8_f32 v44, v46, v47 op_sel:[0,0,1]
	v_mul_f32_e32 v36, v36, v53
	v_mul_f32_e32 v37, v37, v53
	v_mov_b32_e32 v46, v253
	v_mul_f32_e32 v32, v32, v53
	v_mul_f32_e32 v33, v33, v53
	v_mov_b32_e32 v47, v253
	v_cvt_pk_fp8_f32 v45, v40, v41
	v_cvt_pk_fp8_f32 v46, v36, v37
	v_cvt_pk_fp8_f32 v47, v32, v33
	v_mul_f32_e32 v40, v42, v53
	v_mul_f32_e32 v41, v43, v53
	v_mul_f32_e32 v36, v38, v53
	v_mul_f32_e32 v37, v39, v53
	v_mul_f32_e32 v32, v34, v53
	v_mul_f32_e32 v33, v35, v53
	v_cvt_pk_fp8_f32 v45, v40, v41 op_sel:[0,0,1]
	v_cvt_pk_fp8_f32 v46, v36, v37 op_sel:[0,0,1]
	v_cvt_pk_fp8_f32 v47, v32, v33 op_sel:[0,0,1]
	s_add_u32 s98, s92, 0x6100000
	s_addc_u32 s99, s93, 0
	v_subrev_u32_e32 v100, s98, v50
	v_lshrrev_b32_e32 v100, 10, v100
	v_mbcnt_lo_u32_b32 v101, -1, 0
	v_mbcnt_hi_u32_b32 v101, -1, v101
	v_and_b32_e32 v102, 7, v101
	v_lshrrev_b32_e32 v101, 3, v101
	v_lshlrev_b32_e32 v101, 21, v101
	v_lshl_or_b32 v101, v102, 4, v101
	v_lshl_add_u32 v100, v100, 7, v101
	global_store_dwordx4 v100, v[44:47], s[98:99] offset:-128
	s_and_saveexec_b64 s[6:7], s[0:1]
	s_cbranch_execz .LBB0_71
	v_mul_f32_e32 v32, 0x3b124925, v52
	v_cndmask_b32_e32 v34, 1.0, v32, vcc
	v_add_co_u32_e32 v32, vcc, 0x4080000, v48
	s_nop 1
	v_addc_co_u32_e32 v33, vcc, 0, v49, vcc
	global_store_dword v[32:33], v34, off offset:4
.LBB0_71:
	s_or_b64 exec, exec, s[6:7]
	s_waitcnt vmcnt(9)
	v_max_f32_e64 v32, |v31|, |v31|
	v_max_f32_e64 v33, |v30|, |v30|
	v_max_f32_e32 v32, v33, v32
	s_waitcnt vmcnt(6)
	v_max_f32_e64 v33, |v27|, |v27|
	v_max_f32_e64 v34, |v26|, |v26|
	v_max_f32_e32 v33, v34, v33
	v_max_f32_e64 v34, |v21|, |v21|
	v_max_f32_e64 v35, |v20|, |v20|
	v_max_f32_e32 v34, v35, v34
	v_max_f32_e64 v35, |v23|, |v23|
	v_max_f32_e64 v36, |v22|, |v22|
	v_max_f32_e32 v35, v36, v35
	v_max_f32_e64 v36, |v19|, |v19|
	v_max_f32_e64 v37, |v18|, |v18|
	v_max_f32_e32 v36, v37, v36
	v_max3_f32 v36, |v16|, |v17|, v36
	v_max3_f32 v32, |v28|, |v29|, v32
	v_max3_f32 v33, |v24|, |v25|, v33
	v_max3_f32 v34, v34, v35, v36
	s_mov_b32 s6, s35
	v_max3_f32 v32, v32, v33, v34
	s_nop 0
	v_mbcnt_lo_u32_b32 v33, -1, s6
	v_mbcnt_hi_u32_b32 v33, -1, v33
	v_lshlrev_b32_e32 v33, 2, v33
	v_xor_b32_e32 v34, 4, v33
	ds_bpermute_b32 v34, v34, v32
	s_waitcnt lgkmcnt(0)
	v_max_f32_e32 v34, v34, v34
	v_max_f32_e32 v32, v32, v34
	v_xor_b32_e32 v34, 8, v33
	ds_bpermute_b32 v34, v34, v32
	s_waitcnt lgkmcnt(0)
	v_max_f32_e32 v34, v34, v34
	v_max_f32_e32 v32, v32, v34
	v_xor_b32_e32 v34, 16, v33
	ds_bpermute_b32 v34, v34, v32
	s_waitcnt lgkmcnt(0)
	v_max_f32_e32 v34, v34, v34
	v_max_f32_e32 v32, v32, v34
	v_xor_b32_e32 v34, 32, v33
	ds_bpermute_b32 v34, v34, v32
	s_waitcnt lgkmcnt(0)
	v_max_f32_e32 v34, v34, v34
	v_max_f32_e32 v32, v32, v34
	v_xor_b32_e32 v34, 64, v33
	ds_bpermute_b32 v34, v34, v32
	v_xor_b32_e32 v33, 0x80, v33
	s_waitcnt lgkmcnt(0)
	v_max_f32_e32 v34, v34, v34
	v_max_f32_e32 v32, v32, v34
	ds_bpermute_b32 v33, v33, v32
	s_waitcnt lgkmcnt(0)
	v_max_f32_e32 v33, v33, v33
	v_max_f32_e32 v32, v32, v33
	v_div_scale_f32 v33, s[6:7], v32, v32, s43
	v_rcp_f32_e32 v34, v33
	s_nop 0
	v_fma_f32 v35, -v33, v34, 1.0
	v_fmac_f32_e32 v34, v35, v34
	v_div_scale_f32 v35, vcc, s43, v32, s43
	v_mul_f32_e32 v36, v35, v34
	v_fma_f32 v37, -v33, v36, v35
	v_fmac_f32_e32 v36, v37, v34
	v_fma_f32 v33, -v33, v36, v35
	v_div_fmas_f32 v33, v33, v34, v36
	v_div_fixup_f32 v33, v33, v32, s43
	v_cmp_lt_f32_e32 vcc, 0, v32
	s_nop 1
	v_cndmask_b32_e32 v33, 1.0, v33, vcc
	v_mul_f32_e32 v34, v28, v33
	v_mul_f32_e32 v29, v29, v33
	v_mov_b32_e32 v28, v253
	v_cvt_pk_fp8_f32 v28, v34, v29
	v_mul_f32_e32 v30, v30, v33
	v_mul_f32_e32 v31, v31, v33
	v_mul_f32_e32 v24, v24, v33
	v_mul_f32_e32 v25, v25, v33
	v_mov_b32_e32 v29, v253
	v_cvt_pk_fp8_f32 v28, v30, v31 op_sel:[0,0,1]
	v_mul_f32_e32 v20, v20, v33
	v_mul_f32_e32 v21, v21, v33
	v_mov_b32_e32 v30, v253
	v_mul_f32_e32 v16, v16, v33
	v_mul_f32_e32 v17, v17, v33
	v_mov_b32_e32 v31, v253
	v_cvt_pk_fp8_f32 v29, v24, v25
	v_cvt_pk_fp8_f32 v30, v20, v21
	v_cvt_pk_fp8_f32 v31, v16, v17
	v_mul_f32_e32 v24, v26, v33
	v_mul_f32_e32 v25, v27, v33
	v_mul_f32_e32 v20, v22, v33
	v_mul_f32_e32 v21, v23, v33
	v_mul_f32_e32 v16, v18, v33
	v_mul_f32_e32 v17, v19, v33
	v_cvt_pk_fp8_f32 v29, v24, v25 op_sel:[0,0,1]
	v_cvt_pk_fp8_f32 v30, v20, v21 op_sel:[0,0,1]
	v_cvt_pk_fp8_f32 v31, v16, v17 op_sel:[0,0,1]
	s_add_u32 s98, s92, 0x6100000
	s_addc_u32 s99, s93, 0
	v_subrev_u32_e32 v100, s98, v50
	v_lshrrev_b32_e32 v100, 10, v100
	v_mbcnt_lo_u32_b32 v101, -1, 0
	v_mbcnt_hi_u32_b32 v101, -1, v101
	v_and_b32_e32 v102, 7, v101
	v_lshrrev_b32_e32 v101, 3, v101
	v_lshlrev_b32_e32 v101, 21, v101
	v_lshl_or_b32 v101, v102, 4, v101
	v_lshl_add_u32 v100, v100, 7, v101
	global_store_dwordx4 v100, v[28:31], s[98:99]
	s_and_saveexec_b64 s[6:7], s[0:1]
	s_cbranch_execz .LBB0_73
	v_mul_f32_e32 v16, 0x3b124925, v32
	v_cndmask_b32_e32 v18, 1.0, v16, vcc
	v_add_co_u32_e32 v16, vcc, 0x4080000, v48
	s_nop 1
	v_addc_co_u32_e32 v17, vcc, 0, v49, vcc
	global_store_dword v[16:17], v18, off offset:8
.LBB0_73:
	s_or_b64 exec, exec, s[6:7]
	s_waitcnt vmcnt(3)
	v_max_f32_e64 v16, |v15|, |v15|
	v_max_f32_e64 v17, |v14|, |v14|
	v_max_f32_e32 v16, v17, v16
	v_max_f32_e64 v17, |v11|, |v11|
	v_max_f32_e64 v18, |v10|, |v10|
	v_max_f32_e32 v17, v18, v17
	v_max_f32_e64 v18, |v5|, |v5|
	v_max_f32_e64 v19, |v4|, |v4|
	v_max_f32_e32 v18, v19, v18
	v_max_f32_e64 v19, |v7|, |v7|
	v_max_f32_e64 v20, |v6|, |v6|
	v_max_f32_e32 v19, v20, v19
	v_max_f32_e64 v20, |v3|, |v3|
	v_max_f32_e64 v21, |v2|, |v2|
	v_max_f32_e32 v20, v21, v20
	v_max3_f32 v20, |v0|, |v1|, v20
	v_max3_f32 v16, |v12|, |v13|, v16
	v_max3_f32 v17, |v8|, |v9|, v17
	v_max3_f32 v18, v18, v19, v20
	s_mov_b32 s6, s35
	v_max3_f32 v16, v16, v17, v18
	s_nop 0
	v_mbcnt_lo_u32_b32 v17, -1, s6
	v_mbcnt_hi_u32_b32 v17, -1, v17
	v_lshlrev_b32_e32 v17, 2, v17
	v_xor_b32_e32 v18, 4, v17
	ds_bpermute_b32 v18, v18, v16
	s_waitcnt lgkmcnt(0)
	v_max_f32_e32 v18, v18, v18
	v_max_f32_e32 v16, v16, v18
	v_xor_b32_e32 v18, 8, v17
	ds_bpermute_b32 v18, v18, v16
	s_waitcnt lgkmcnt(0)
	v_max_f32_e32 v18, v18, v18
	v_max_f32_e32 v16, v16, v18
	v_xor_b32_e32 v18, 16, v17
	ds_bpermute_b32 v18, v18, v16
	s_waitcnt lgkmcnt(0)
	v_max_f32_e32 v18, v18, v18
	v_max_f32_e32 v16, v16, v18
	v_xor_b32_e32 v18, 32, v17
	ds_bpermute_b32 v18, v18, v16
	s_waitcnt lgkmcnt(0)
	v_max_f32_e32 v18, v18, v18
	v_max_f32_e32 v16, v16, v18
	v_xor_b32_e32 v18, 64, v17
	ds_bpermute_b32 v18, v18, v16
	v_xor_b32_e32 v17, 0x80, v17
	s_waitcnt lgkmcnt(0)
	v_max_f32_e32 v18, v18, v18
	v_max_f32_e32 v16, v16, v18
	ds_bpermute_b32 v17, v17, v16
	s_waitcnt lgkmcnt(0)
	v_max_f32_e32 v17, v17, v17
	v_max_f32_e32 v16, v16, v17
	v_div_scale_f32 v17, s[6:7], v16, v16, s43
	v_rcp_f32_e32 v18, v17
	s_nop 0
	v_fma_f32 v19, -v17, v18, 1.0
	v_fmac_f32_e32 v18, v19, v18
	v_div_scale_f32 v19, vcc, s43, v16, s43
	v_mul_f32_e32 v20, v19, v18
	v_fma_f32 v21, -v17, v20, v19
	v_fmac_f32_e32 v20, v21, v18
	v_fma_f32 v17, -v17, v20, v19
	v_div_fmas_f32 v17, v17, v18, v20
	v_div_fixup_f32 v17, v17, v16, s43
	v_cmp_lt_f32_e32 vcc, 0, v16
	s_nop 1
	v_cndmask_b32_e32 v17, 1.0, v17, vcc
	v_mul_f32_e32 v18, v12, v17
	v_mul_f32_e32 v13, v13, v17
	v_mov_b32_e32 v12, v253
	v_cvt_pk_fp8_f32 v12, v18, v13
	v_mul_f32_e32 v14, v14, v17
	v_mul_f32_e32 v15, v15, v17
	v_mul_f32_e32 v8, v8, v17
	v_mul_f32_e32 v9, v9, v17
	v_mov_b32_e32 v13, v253
	v_cvt_pk_fp8_f32 v12, v14, v15 op_sel:[0,0,1]
	v_mul_f32_e32 v4, v4, v17
	v_mul_f32_e32 v5, v5, v17
	v_mov_b32_e32 v14, v253
	v_mul_f32_e32 v0, v0, v17
	v_mul_f32_e32 v1, v1, v17
	v_mov_b32_e32 v15, v253
	v_cvt_pk_fp8_f32 v13, v8, v9
	v_cvt_pk_fp8_f32 v14, v4, v5
	v_cvt_pk_fp8_f32 v15, v0, v1
	v_mul_f32_e32 v8, v10, v17
	v_mul_f32_e32 v9, v11, v17
	v_mul_f32_e32 v4, v6, v17
	v_mul_f32_e32 v5, v7, v17
	v_mul_f32_e32 v0, v2, v17
	v_mul_f32_e32 v1, v3, v17
	v_cvt_pk_fp8_f32 v13, v8, v9 op_sel:[0,0,1]
	v_cvt_pk_fp8_f32 v14, v4, v5 op_sel:[0,0,1]
	v_cvt_pk_fp8_f32 v15, v0, v1 op_sel:[0,0,1]
	s_add_u32 s98, s92, 0x6100000
	s_addc_u32 s99, s93, 0
	v_subrev_u32_e32 v100, s98, v50
	v_lshrrev_b32_e32 v100, 10, v100
	v_mbcnt_lo_u32_b32 v101, -1, 0
	v_mbcnt_hi_u32_b32 v101, -1, v101
	v_and_b32_e32 v102, 7, v101
	v_lshrrev_b32_e32 v101, 3, v101
	v_lshlrev_b32_e32 v101, 21, v101
	v_lshl_or_b32 v101, v102, 4, v101
	v_lshl_add_u32 v100, v100, 7, v101
	global_store_dwordx4 v100, v[12:15], s[98:99] offset:128
	s_and_saveexec_b64 s[6:7], s[0:1]
	s_cbranch_execz .LBB0_66
	v_mul_f32_e32 v0, 0x3b124925, v16
	v_cndmask_b32_e32 v2, 1.0, v0, vcc
	v_add_co_u32_e32 v0, vcc, 0x4080000, v48
	s_nop 1
	v_addc_co_u32_e32 v1, vcc, 0, v49, vcc
	global_store_dword v[0:1], v2, off offset:12
	s_branch .LBB0_66

.LBB0_123:
	s_and_b64 vcc, exec, s[0:1]
	s_cbranch_vccz .LBB0_142
	v_readlane_b32 s0, v255, 63
	s_cmp_eq_u32 s0, 0
	s_cbranch_scc1 .Lgl1_entry
	s_cmp_eq_u32 s0, 1
	s_cbranch_scc1 .Lgu_entry
	s_cmp_eq_u32 s0, 2
	s_cbranch_scc1 .Lga_entry
	s_cmp_eq_u32 s0, 3
	s_cbranch_scc1 .Lgv_entry
	s_branch .Lgl2_entry
.Lgl1_entry:
	s_mov_b64 s[82:83], exec
	v_readlane_b32 s4, v254, 40
	v_readlane_b32 s5, v254, 41
	v_readlane_b32 s6, v255, 15
	v_readlane_b32 s7, v254, 21
	s_nop 4
	s_load_dword s8, s[4:5], 0x0
	v_mbcnt_lo_u32_b32 v0, -1, 0
	v_mbcnt_hi_u32_b32 v0, -1, v0
	v_readlane_b32 s9, v255, 48
	v_readlane_b32 s10, v255, 52
	v_readlane_b32 s11, v255, 53
	v_readlane_b32 s12, v255, 54
	v_readlane_b32 s13, v255, 55
	v_readlane_b32 s14, v255, 50
	v_readlane_b32 s15, v255, 51
	v_lshlrev_b32_e32 v1, 6, v0
	v_lshlrev_b32_e32 v2, 5, v0
	v_lshlrev_b32_e32 v3, 2, v0
	v_xor_b32_e32 v4, 0x4, v3
	v_xor_b32_e32 v5, 0x8, v3
	v_xor_b32_e32 v6, 0x10, v3
	v_xor_b32_e32 v7, 0x20, v3
	v_xor_b32_e32 v8, 0x40, v3
	v_xor_b32_e32 v9, 0x80, v3
	v_mov_b32_e32 v10, 0x3727c5ac
	s_and_b32 s9, s9, 0xff
	s_lshl_b32 s9, s9, 13
	s_add_u32 s10, s10, s9
	s_addc_u32 s11, s11, 0
	s_add_u32 s12, s12, s9
	s_addc_u32 s13, s13, 0
	global_load_dwordx4 v[16:19], v1, s[10:11]
	global_load_dwordx4 v[20:23], v1, s[10:11] offset:16
	global_load_dwordx4 v[24:27], v1, s[10:11] offset:32
	global_load_dwordx4 v[28:31], v1, s[10:11] offset:48
	global_load_dwordx4 v[32:35], v1, s[12:13]
	global_load_dwordx4 v[36:39], v1, s[12:13] offset:16
	global_load_dwordx4 v[40:43], v1, s[12:13] offset:32
	global_load_dwordx4 v[44:47], v1, s[12:13] offset:48
	v_add_u32_e32 v49, 0x1000, v1
	v_add_u32_e32 v53, 0x800, v2
	v_add_u32_e32 v50, 0x2000, v1
	v_add_u32_e32 v54, 0x1000, v2
	v_add_u32_e32 v51, 0x3000, v1
	v_add_u32_e32 v55, 0x1800, v2
	v_mov_b32_e32 v48, v1
	v_mov_b32_e32 v52, v2
	s_lshl_b32 s6, s6, 2
	s_lshr_b32 s7, s7, 6
	s_add_u32 s6, s6, s7
	s_lshl_b32 s22, s6, 2
	s_waitcnt lgkmcnt(0)
	s_lshl_b32 s26, s8, 4
	s_add_u32 s16, s92, 0xc100000
	s_addc_u32 s17, s93, 0
	s_add_u32 s18, s92, 0x8100000
	s_addc_u32 s19, s93, 0
	s_add_u32 s14, s92, 0x2a100000
	s_addc_u32 s15, s93, 0
	s_cmp_ge_u32 s22, 0x8000
	s_cbranch_scc1 .Lgl1_done
.Lgl1_loop:
	s_lshl_b32 s30, s22, 12
	s_add_u32 s40, s16, s30
	s_addc_u32 s41, s17, 0
	s_add_u32 s64, s14, s30
	s_addc_u32 s65, s15, 0
	s_lshl_b32 s30, s22, 11
	s_add_u32 s66, s18, s30
	s_addc_u32 s67, s19, 0
	global_load_dwordx4 v[64:67], v48, s[40:41]
	global_load_dwordx4 v[68:71], v48, s[40:41] offset:16
	global_load_dwordx4 v[72:75], v48, s[40:41] offset:32
	global_load_dwordx4 v[76:79], v48, s[40:41] offset:48
	global_load_dwordx4 v[80:83], v49, s[40:41]
	global_load_dwordx4 v[84:87], v49, s[40:41] offset:16
	global_load_dwordx4 v[88:91], v49, s[40:41] offset:32
	global_load_dwordx4 v[92:95], v49, s[40:41] offset:48
	global_load_dwordx4 v[96:99], v50, s[40:41]
	global_load_dwordx4 v[100:103], v50, s[40:41] offset:16
	global_load_dwordx4 v[104:107], v50, s[40:41] offset:32
	global_load_dwordx4 v[108:111], v50, s[40:41] offset:48
	global_load_dwordx4 v[112:115], v51, s[40:41]
	global_load_dwordx4 v[116:119], v51, s[40:41] offset:16
	global_load_dwordx4 v[120:123], v51, s[40:41] offset:32
	global_load_dwordx4 v[124:127], v51, s[40:41] offset:48
	s_waitcnt vmcnt(12)
	v_add_f32_e32 v56, v64, v65
	v_add_f32_e32 v56, v66, v56
	v_add_f32_e32 v56, v67, v56
	v_add_f32_e32 v56, v68, v56
	v_add_f32_e32 v56, v69, v56
	v_add_f32_e32 v56, v70, v56
	v_add_f32_e32 v56, v71, v56
	v_add_f32_e32 v56, v72, v56
	v_add_f32_e32 v56, v73, v56
	v_add_f32_e32 v56, v74, v56
	v_add_f32_e32 v56, v75, v56
	v_add_f32_e32 v56, v76, v56
	v_add_f32_e32 v56, v77, v56
	v_add_f32_e32 v56, v78, v56
	v_add_f32_e32 v56, v79, v56
	s_waitcnt vmcnt(8)
	v_add_f32_e32 v57, v80, v81
	v_add_f32_e32 v57, v82, v57
	v_add_f32_e32 v57, v83, v57
	v_add_f32_e32 v57, v84, v57
	v_add_f32_e32 v57, v85, v57
	v_add_f32_e32 v57, v86, v57
	v_add_f32_e32 v57, v87, v57
	v_add_f32_e32 v57, v88, v57
	v_add_f32_e32 v57, v89, v57
	v_add_f32_e32 v57, v90, v57
	v_add_f32_e32 v57, v91, v57
	v_add_f32_e32 v57, v92, v57
	v_add_f32_e32 v57, v93, v57
	v_add_f32_e32 v57, v94, v57
	v_add_f32_e32 v57, v95, v57
	s_waitcnt vmcnt(4)
	v_add_f32_e32 v58, v96, v97
	v_add_f32_e32 v58, v98, v58
	v_add_f32_e32 v58, v99, v58
	v_add_f32_e32 v58, v100, v58
	v_add_f32_e32 v58, v101, v58
	v_add_f32_e32 v58, v102, v58
	v_add_f32_e32 v58, v103, v58
	v_add_f32_e32 v58, v104, v58
	v_add_f32_e32 v58, v105, v58
	v_add_f32_e32 v58, v106, v58
	v_add_f32_e32 v58, v107, v58
	v_add_f32_e32 v58, v108, v58
	v_add_f32_e32 v58, v109, v58
	v_add_f32_e32 v58, v110, v58
	v_add_f32_e32 v58, v111, v58
	s_waitcnt vmcnt(0)
	v_add_f32_e32 v59, v112, v113
	v_add_f32_e32 v59, v114, v59
	v_add_f32_e32 v59, v115, v59
	v_add_f32_e32 v59, v116, v59
	v_add_f32_e32 v59, v117, v59
	v_add_f32_e32 v59, v118, v59
	v_add_f32_e32 v59, v119, v59
	v_add_f32_e32 v59, v120, v59
	v_add_f32_e32 v59, v121, v59
	v_add_f32_e32 v59, v122, v59
	v_add_f32_e32 v59, v123, v59
	v_add_f32_e32 v59, v124, v59
	v_add_f32_e32 v59, v125, v59
	v_add_f32_e32 v59, v126, v59
	v_add_f32_e32 v59, v127, v59
	ds_bpermute_b32 v60, v4, v56
	ds_bpermute_b32 v61, v4, v57
	ds_bpermute_b32 v62, v4, v58
	ds_bpermute_b32 v63, v4, v59
	s_waitcnt lgkmcnt(3)
	v_add_f32_e32 v56, v56, v60
	s_waitcnt lgkmcnt(2)
	v_add_f32_e32 v57, v57, v61
	s_waitcnt lgkmcnt(1)
	v_add_f32_e32 v58, v58, v62
	s_waitcnt lgkmcnt(0)
	v_add_f32_e32 v59, v59, v63
	ds_bpermute_b32 v60, v5, v56
	ds_bpermute_b32 v61, v5, v57
	ds_bpermute_b32 v62, v5, v58
	ds_bpermute_b32 v63, v5, v59
	s_waitcnt lgkmcnt(3)
	v_add_f32_e32 v56, v56, v60
	s_waitcnt lgkmcnt(2)
	v_add_f32_e32 v57, v57, v61
	s_waitcnt lgkmcnt(1)
	v_add_f32_e32 v58, v58, v62
	s_waitcnt lgkmcnt(0)
	v_add_f32_e32 v59, v59, v63
	ds_bpermute_b32 v60, v6, v56
	ds_bpermute_b32 v61, v6, v57
	ds_bpermute_b32 v62, v6, v58
	ds_bpermute_b32 v63, v6, v59
	s_waitcnt lgkmcnt(3)
	v_add_f32_e32 v56, v56, v60
	s_waitcnt lgkmcnt(2)
	v_add_f32_e32 v57, v57, v61
	s_waitcnt lgkmcnt(1)
	v_add_f32_e32 v58, v58, v62
	s_waitcnt lgkmcnt(0)
	v_add_f32_e32 v59, v59, v63
	ds_bpermute_b32 v60, v7, v56
	ds_bpermute_b32 v61, v7, v57
	ds_bpermute_b32 v62, v7, v58
	ds_bpermute_b32 v63, v7, v59
	s_waitcnt lgkmcnt(3)
	v_add_f32_e32 v56, v56, v60
	s_waitcnt lgkmcnt(2)
	v_add_f32_e32 v57, v57, v61
	s_waitcnt lgkmcnt(1)
	v_add_f32_e32 v58, v58, v62
	s_waitcnt lgkmcnt(0)
	v_add_f32_e32 v59, v59, v63
	ds_bpermute_b32 v60, v8, v56
	ds_bpermute_b32 v61, v8, v57
	ds_bpermute_b32 v62, v8, v58
	ds_bpermute_b32 v63, v8, v59
	s_waitcnt lgkmcnt(3)
	v_add_f32_e32 v56, v56, v60
	s_waitcnt lgkmcnt(2)
	v_add_f32_e32 v57, v57, v61
	s_waitcnt lgkmcnt(1)
	v_add_f32_e32 v58, v58, v62
	s_waitcnt lgkmcnt(0)
	v_add_f32_e32 v59, v59, v63
	ds_bpermute_b32 v60, v9, v56
	ds_bpermute_b32 v61, v9, v57
	ds_bpermute_b32 v62, v9, v58
	ds_bpermute_b32 v63, v9, v59
	s_waitcnt lgkmcnt(3)
	v_add_f32_e32 v56, v56, v60
	s_waitcnt lgkmcnt(2)
	v_add_f32_e32 v57, v57, v61
	s_waitcnt lgkmcnt(1)
	v_add_f32_e32 v58, v58, v62
	s_waitcnt lgkmcnt(0)
	v_add_f32_e32 v59, v59, v63
	v_mul_f32_e32 v60, 0x3a800000, v56
	v_sub_f32_e32 v64, v64, v60
	v_sub_f32_e32 v65, v65, v60
	v_sub_f32_e32 v66, v66, v60
	v_sub_f32_e32 v67, v67, v60
	v_sub_f32_e32 v68, v68, v60
	v_sub_f32_e32 v69, v69, v60
	v_sub_f32_e32 v70, v70, v60
	v_sub_f32_e32 v71, v71, v60
	v_sub_f32_e32 v72, v72, v60
	v_sub_f32_e32 v73, v73, v60
	v_sub_f32_e32 v74, v74, v60
	v_sub_f32_e32 v75, v75, v60
	v_sub_f32_e32 v76, v76, v60
	v_sub_f32_e32 v77, v77, v60
	v_sub_f32_e32 v78, v78, v60
	v_sub_f32_e32 v79, v79, v60
	v_mul_f32_e32 v56, v64, v64
	v_fmac_f32_e32 v56, v65, v65
	v_fmac_f32_e32 v56, v66, v66
	v_fmac_f32_e32 v56, v67, v67
	v_fmac_f32_e32 v56, v68, v68
	v_fmac_f32_e32 v56, v69, v69
	v_fmac_f32_e32 v56, v70, v70
	v_fmac_f32_e32 v56, v71, v71
	v_fmac_f32_e32 v56, v72, v72
	v_fmac_f32_e32 v56, v73, v73
	v_fmac_f32_e32 v56, v74, v74
	v_fmac_f32_e32 v56, v75, v75
	v_fmac_f32_e32 v56, v76, v76
	v_fmac_f32_e32 v56, v77, v77
	v_fmac_f32_e32 v56, v78, v78
	v_fmac_f32_e32 v56, v79, v79
	v_mul_f32_e32 v61, 0x3a800000, v57
	v_sub_f32_e32 v80, v80, v61
	v_sub_f32_e32 v81, v81, v61
	v_sub_f32_e32 v82, v82, v61
	v_sub_f32_e32 v83, v83, v61
	v_sub_f32_e32 v84, v84, v61
	v_sub_f32_e32 v85, v85, v61
	v_sub_f32_e32 v86, v86, v61
	v_sub_f32_e32 v87, v87, v61
	v_sub_f32_e32 v88, v88, v61
	v_sub_f32_e32 v89, v89, v61
	v_sub_f32_e32 v90, v90, v61
	v_sub_f32_e32 v91, v91, v61
	v_sub_f32_e32 v92, v92, v61
	v_sub_f32_e32 v93, v93, v61
	v_sub_f32_e32 v94, v94, v61
	v_sub_f32_e32 v95, v95, v61
	v_mul_f32_e32 v57, v80, v80
	v_fmac_f32_e32 v57, v81, v81
	v_fmac_f32_e32 v57, v82, v82
	v_fmac_f32_e32 v57, v83, v83
	v_fmac_f32_e32 v57, v84, v84
	v_fmac_f32_e32 v57, v85, v85
	v_fmac_f32_e32 v57, v86, v86
	v_fmac_f32_e32 v57, v87, v87
	v_fmac_f32_e32 v57, v88, v88
	v_fmac_f32_e32 v57, v89, v89
	v_fmac_f32_e32 v57, v90, v90
	v_fmac_f32_e32 v57, v91, v91
	v_fmac_f32_e32 v57, v92, v92
	v_fmac_f32_e32 v57, v93, v93
	v_fmac_f32_e32 v57, v94, v94
	v_fmac_f32_e32 v57, v95, v95
	v_mul_f32_e32 v62, 0x3a800000, v58
	v_sub_f32_e32 v96, v96, v62
	v_sub_f32_e32 v97, v97, v62
	v_sub_f32_e32 v98, v98, v62
	v_sub_f32_e32 v99, v99, v62
	v_sub_f32_e32 v100, v100, v62
	v_sub_f32_e32 v101, v101, v62
	v_sub_f32_e32 v102, v102, v62
	v_sub_f32_e32 v103, v103, v62
	v_sub_f32_e32 v104, v104, v62
	v_sub_f32_e32 v105, v105, v62
	v_sub_f32_e32 v106, v106, v62
	v_sub_f32_e32 v107, v107, v62
	v_sub_f32_e32 v108, v108, v62
	v_sub_f32_e32 v109, v109, v62
	v_sub_f32_e32 v110, v110, v62
	v_sub_f32_e32 v111, v111, v62
	v_mul_f32_e32 v58, v96, v96
	v_fmac_f32_e32 v58, v97, v97
	v_fmac_f32_e32 v58, v98, v98
	v_fmac_f32_e32 v58, v99, v99
	v_fmac_f32_e32 v58, v100, v100
	v_fmac_f32_e32 v58, v101, v101
	v_fmac_f32_e32 v58, v102, v102
	v_fmac_f32_e32 v58, v103, v103
	v_fmac_f32_e32 v58, v104, v104
	v_fmac_f32_e32 v58, v105, v105
	v_fmac_f32_e32 v58, v106, v106
	v_fmac_f32_e32 v58, v107, v107
	v_fmac_f32_e32 v58, v108, v108
	v_fmac_f32_e32 v58, v109, v109
	v_fmac_f32_e32 v58, v110, v110
	v_fmac_f32_e32 v58, v111, v111
	v_mul_f32_e32 v63, 0x3a800000, v59
	v_sub_f32_e32 v112, v112, v63
	v_sub_f32_e32 v113, v113, v63
	v_sub_f32_e32 v114, v114, v63
	v_sub_f32_e32 v115, v115, v63
	v_sub_f32_e32 v116, v116, v63
	v_sub_f32_e32 v117, v117, v63
	v_sub_f32_e32 v118, v118, v63
	v_sub_f32_e32 v119, v119, v63
	v_sub_f32_e32 v120, v120, v63
	v_sub_f32_e32 v121, v121, v63
	v_sub_f32_e32 v122, v122, v63
	v_sub_f32_e32 v123, v123, v63
	v_sub_f32_e32 v124, v124, v63
	v_sub_f32_e32 v125, v125, v63
	v_sub_f32_e32 v126, v126, v63
	v_sub_f32_e32 v127, v127, v63
	v_mul_f32_e32 v59, v112, v112
	v_fmac_f32_e32 v59, v113, v113
	v_fmac_f32_e32 v59, v114, v114
	v_fmac_f32_e32 v59, v115, v115
	v_fmac_f32_e32 v59, v116, v116
	v_fmac_f32_e32 v59, v117, v117
	v_fmac_f32_e32 v59, v118, v118
	v_fmac_f32_e32 v59, v119, v119
	v_fmac_f32_e32 v59, v120, v120
	v_fmac_f32_e32 v59, v121, v121
	v_fmac_f32_e32 v59, v122, v122
	v_fmac_f32_e32 v59, v123, v123
	v_fmac_f32_e32 v59, v124, v124
	v_fmac_f32_e32 v59, v125, v125
	v_fmac_f32_e32 v59, v126, v126
	v_fmac_f32_e32 v59, v127, v127
	ds_bpermute_b32 v60, v4, v56
	ds_bpermute_b32 v61, v4, v57
	ds_bpermute_b32 v62, v4, v58
	ds_bpermute_b32 v63, v4, v59
	s_waitcnt lgkmcnt(3)
	v_add_f32_e32 v56, v56, v60
	s_waitcnt lgkmcnt(2)
	v_add_f32_e32 v57, v57, v61
	s_waitcnt lgkmcnt(1)
	v_add_f32_e32 v58, v58, v62
	s_waitcnt lgkmcnt(0)
	v_add_f32_e32 v59, v59, v63
	ds_bpermute_b32 v60, v5, v56
	ds_bpermute_b32 v61, v5, v57
	ds_bpermute_b32 v62, v5, v58
	ds_bpermute_b32 v63, v5, v59
	s_waitcnt lgkmcnt(3)
	v_add_f32_e32 v56, v56, v60
	s_waitcnt lgkmcnt(2)
	v_add_f32_e32 v57, v57, v61
	s_waitcnt lgkmcnt(1)
	v_add_f32_e32 v58, v58, v62
	s_waitcnt lgkmcnt(0)
	v_add_f32_e32 v59, v59, v63
	ds_bpermute_b32 v60, v6, v56
	ds_bpermute_b32 v61, v6, v57
	ds_bpermute_b32 v62, v6, v58
	ds_bpermute_b32 v63, v6, v59
	s_waitcnt lgkmcnt(3)
	v_add_f32_e32 v56, v56, v60
	s_waitcnt lgkmcnt(2)
	v_add_f32_e32 v57, v57, v61
	s_waitcnt lgkmcnt(1)
	v_add_f32_e32 v58, v58, v62
	s_waitcnt lgkmcnt(0)
	v_add_f32_e32 v59, v59, v63
	ds_bpermute_b32 v60, v7, v56
	ds_bpermute_b32 v61, v7, v57
	ds_bpermute_b32 v62, v7, v58
	ds_bpermute_b32 v63, v7, v59
	s_waitcnt lgkmcnt(3)
	v_add_f32_e32 v56, v56, v60
	s_waitcnt lgkmcnt(2)
	v_add_f32_e32 v57, v57, v61
	s_waitcnt lgkmcnt(1)
	v_add_f32_e32 v58, v58, v62
	s_waitcnt lgkmcnt(0)
	v_add_f32_e32 v59, v59, v63
	ds_bpermute_b32 v60, v8, v56
	ds_bpermute_b32 v61, v8, v57
	ds_bpermute_b32 v62, v8, v58
	ds_bpermute_b32 v63, v8, v59
	s_waitcnt lgkmcnt(3)
	v_add_f32_e32 v56, v56, v60
	s_waitcnt lgkmcnt(2)
	v_add_f32_e32 v57, v57, v61
	s_waitcnt lgkmcnt(1)
	v_add_f32_e32 v58, v58, v62
	s_waitcnt lgkmcnt(0)
	v_add_f32_e32 v59, v59, v63
	ds_bpermute_b32 v60, v9, v56
	ds_bpermute_b32 v61, v9, v57
	ds_bpermute_b32 v62, v9, v58
	ds_bpermute_b32 v63, v9, v59
	s_waitcnt lgkmcnt(3)
	v_add_f32_e32 v56, v56, v60
	s_waitcnt lgkmcnt(2)
	v_add_f32_e32 v57, v57, v61
	s_waitcnt lgkmcnt(1)
	v_add_f32_e32 v58, v58, v62
	s_waitcnt lgkmcnt(0)
	v_add_f32_e32 v59, v59, v63
	v_fmamk_f32 v56, v56, 0x3a800000, v10
	v_fmamk_f32 v57, v57, 0x3a800000, v10
	v_fmamk_f32 v58, v58, 0x3a800000, v10
	v_fmamk_f32 v59, v59, 0x3a800000, v10
	v_rsq_f32_e32 v56, v56
	v_rsq_f32_e32 v57, v57
	v_rsq_f32_e32 v58, v58
	v_rsq_f32_e32 v59, v59
	s_nop 1
	s_waitcnt vmcnt(0)
	v_mul_f32_e32 v64, v64, v56
	v_mul_f32_e32 v65, v65, v56
	v_mul_f32_e32 v66, v66, v56
	v_mul_f32_e32 v67, v67, v56
	v_mul_f32_e32 v68, v68, v56
	v_mul_f32_e32 v69, v69, v56
	v_mul_f32_e32 v70, v70, v56
	v_mul_f32_e32 v71, v71, v56
	v_mul_f32_e32 v72, v72, v56
	v_mul_f32_e32 v73, v73, v56
	v_mul_f32_e32 v74, v74, v56
	v_mul_f32_e32 v75, v75, v56
	v_mul_f32_e32 v76, v76, v56
	v_mul_f32_e32 v77, v77, v56
	v_mul_f32_e32 v78, v78, v56
	v_mul_f32_e32 v79, v79, v56
	v_fma_f32 v64, v64, v16, v32
	v_fma_f32 v65, v65, v17, v33
	v_fma_f32 v66, v66, v18, v34
	v_fma_f32 v67, v67, v19, v35
	v_fma_f32 v68, v68, v20, v36
	v_fma_f32 v69, v69, v21, v37
	v_fma_f32 v70, v70, v22, v38
	v_fma_f32 v71, v71, v23, v39
	v_fma_f32 v72, v72, v24, v40
	v_fma_f32 v73, v73, v25, v41
	v_fma_f32 v74, v74, v26, v42
	v_fma_f32 v75, v75, v27, v43
	v_fma_f32 v76, v76, v28, v44
	v_fma_f32 v77, v77, v29, v45
	v_fma_f32 v78, v78, v30, v46
	v_fma_f32 v79, v79, v31, v47
	global_store_dwordx4 v48, v[64:67], s[64:65]
	global_store_dwordx4 v48, v[68:71], s[64:65] offset:16
	global_store_dwordx4 v48, v[72:75], s[64:65] offset:32
	global_store_dwordx4 v48, v[76:79], s[64:65] offset:48
	v_mul_f32_e32 v80, v80, v57
	v_mul_f32_e32 v81, v81, v57
	v_mul_f32_e32 v82, v82, v57
	v_mul_f32_e32 v83, v83, v57
	v_mul_f32_e32 v84, v84, v57
	v_mul_f32_e32 v85, v85, v57
	v_mul_f32_e32 v86, v86, v57
	v_mul_f32_e32 v87, v87, v57
	v_mul_f32_e32 v88, v88, v57
	v_mul_f32_e32 v89, v89, v57
	v_mul_f32_e32 v90, v90, v57
	v_mul_f32_e32 v91, v91, v57
	v_mul_f32_e32 v92, v92, v57
	v_mul_f32_e32 v93, v93, v57
	v_mul_f32_e32 v94, v94, v57
	v_mul_f32_e32 v95, v95, v57
	v_fma_f32 v80, v80, v16, v32
	v_fma_f32 v81, v81, v17, v33
	v_fma_f32 v82, v82, v18, v34
	v_fma_f32 v83, v83, v19, v35
	v_fma_f32 v84, v84, v20, v36
	v_fma_f32 v85, v85, v21, v37
	v_fma_f32 v86, v86, v22, v38
	v_fma_f32 v87, v87, v23, v39
	v_fma_f32 v88, v88, v24, v40
	v_fma_f32 v89, v89, v25, v41
	v_fma_f32 v90, v90, v26, v42
	v_fma_f32 v91, v91, v27, v43
	v_fma_f32 v92, v92, v28, v44
	v_fma_f32 v93, v93, v29, v45
	v_fma_f32 v94, v94, v30, v46
	v_fma_f32 v95, v95, v31, v47
	global_store_dwordx4 v49, v[80:83], s[64:65]
	global_store_dwordx4 v49, v[84:87], s[64:65] offset:16
	global_store_dwordx4 v49, v[88:91], s[64:65] offset:32
	global_store_dwordx4 v49, v[92:95], s[64:65] offset:48
	v_mul_f32_e32 v96, v96, v58
	v_mul_f32_e32 v97, v97, v58
	v_mul_f32_e32 v98, v98, v58
	v_mul_f32_e32 v99, v99, v58
	v_mul_f32_e32 v100, v100, v58
	v_mul_f32_e32 v101, v101, v58
	v_mul_f32_e32 v102, v102, v58
	v_mul_f32_e32 v103, v103, v58
	v_mul_f32_e32 v104, v104, v58
	v_mul_f32_e32 v105, v105, v58
	v_mul_f32_e32 v106, v106, v58
	v_mul_f32_e32 v107, v107, v58
	v_mul_f32_e32 v108, v108, v58
	v_mul_f32_e32 v109, v109, v58
	v_mul_f32_e32 v110, v110, v58
	v_mul_f32_e32 v111, v111, v58
	v_fma_f32 v96, v96, v16, v32
	v_fma_f32 v97, v97, v17, v33
	v_fma_f32 v98, v98, v18, v34
	v_fma_f32 v99, v99, v19, v35
	v_fma_f32 v100, v100, v20, v36
	v_fma_f32 v101, v101, v21, v37
	v_fma_f32 v102, v102, v22, v38
	v_fma_f32 v103, v103, v23, v39
	v_fma_f32 v104, v104, v24, v40
	v_fma_f32 v105, v105, v25, v41
	v_fma_f32 v106, v106, v26, v42
	v_fma_f32 v107, v107, v27, v43
	v_fma_f32 v108, v108, v28, v44
	v_fma_f32 v109, v109, v29, v45
	v_fma_f32 v110, v110, v30, v46
	v_fma_f32 v111, v111, v31, v47
	global_store_dwordx4 v50, v[96:99], s[64:65]
	global_store_dwordx4 v50, v[100:103], s[64:65] offset:16
	global_store_dwordx4 v50, v[104:107], s[64:65] offset:32
	global_store_dwordx4 v50, v[108:111], s[64:65] offset:48
	v_mul_f32_e32 v112, v112, v59
	v_mul_f32_e32 v113, v113, v59
	v_mul_f32_e32 v114, v114, v59
	v_mul_f32_e32 v115, v115, v59
	v_mul_f32_e32 v116, v116, v59
	v_mul_f32_e32 v117, v117, v59
	v_mul_f32_e32 v118, v118, v59
	v_mul_f32_e32 v119, v119, v59
	v_mul_f32_e32 v120, v120, v59
	v_mul_f32_e32 v121, v121, v59
	v_mul_f32_e32 v122, v122, v59
	v_mul_f32_e32 v123, v123, v59
	v_mul_f32_e32 v124, v124, v59
	v_mul_f32_e32 v125, v125, v59
	v_mul_f32_e32 v126, v126, v59
	v_mul_f32_e32 v127, v127, v59
	v_fma_f32 v112, v112, v16, v32
	v_fma_f32 v113, v113, v17, v33
	v_fma_f32 v114, v114, v18, v34
	v_fma_f32 v115, v115, v19, v35
	v_fma_f32 v116, v116, v20, v36
	v_fma_f32 v117, v117, v21, v37
	v_fma_f32 v118, v118, v22, v38
	v_fma_f32 v119, v119, v23, v39
	v_fma_f32 v120, v120, v24, v40
	v_fma_f32 v121, v121, v25, v41
	v_fma_f32 v122, v122, v26, v42
	v_fma_f32 v123, v123, v27, v43
	v_fma_f32 v124, v124, v28, v44
	v_fma_f32 v125, v125, v29, v45
	v_fma_f32 v126, v126, v30, v46
	v_fma_f32 v127, v127, v31, v47
	global_store_dwordx4 v51, v[112:115], s[64:65]
	global_store_dwordx4 v51, v[116:119], s[64:65] offset:16
	global_store_dwordx4 v51, v[120:123], s[64:65] offset:32
	global_store_dwordx4 v51, v[124:127], s[64:65] offset:48
	s_add_u32 s22, s22, s26
	s_cmp_lt_u32 s22, 0x8000
	s_cbranch_scc1 .Lgl1_loop
.Lgl1_done:
	s_waitcnt vmcnt(0) lgkmcnt(0)
	s_branch .LBB0_141
.Lgu_entry:
	s_mov_b64 s[82:83], exec
	v_readlane_b32 s4, v254, 40
	v_readlane_b32 s5, v254, 41
	v_readlane_b32 s6, v255, 15
	v_readlane_b32 s7, v254, 21
	s_nop 4
	s_load_dword s8, s[4:5], 0x0
	v_mbcnt_lo_u32_b32 v0, -1, 0
	v_mbcnt_hi_u32_b32 v0, -1, v0
	v_lshlrev_b32_e32 v1, 2, v0
	v_lshlrev_b32_e32 v2, 3, v0
	v_and_b32_e32 v3, 7, v0
	v_lshlrev_b32_e32 v3, 4, v3
	v_lshrrev_b32_e32 v4, 3, v0
	s_lshl_b32 s9, s7, 6
	v_add_u32_e32 v5, s9, v1
	v_lshlrev_b32_e32 v6, 5, v0
	v_add_u32_e32 v6, s9, v6
	v_lshlrev_b32_e32 v7, 2, v3
	v_lshlrev_b32_e32 v4, 2, v4
	s_and_b32 s10, s6, 7
	s_lshr_b32 s11, s6, 3
	s_lshr_b32 s12, s7, 6
	s_lshl_b32 s11, s11, 2
	s_add_u32 s11, s11, s12
	s_waitcnt lgkmcnt(0)
	s_lshr_b32 s12, s8, 3
	s_lshl_b32 s12, s12, 2
	s_lshl_b32 s13, s10, 21
	s_add_u32 s14, s92, 0x4100000
	s_addc_u32 s15, s93, 0
	s_add_u32 s14, s14, s13
	s_addc_u32 s15, s15, 0
	s_lshl_b32 s13, s10, 9
	s_add_u32 s16, s92, 0x2a100000
	s_addc_u32 s17, s93, 0
	s_add_u32 s16, s16, s13
	s_addc_u32 s17, s17, 0
	s_add_u32 s18, s92, 0x14100000
	s_addc_u32 s19, s93, 0
	s_add_u32 s20, s92, 0x32100000
	s_addc_u32 s21, s93, 0
	s_add_u32 s20, s20, s13
	s_addc_u32 s21, s21, 0
	s_cmp_ge_u32 s11, s12
	s_cbranch_scc1 .Lgu_done
	s_cmp_ge_u32 s11, 0x8000
	s_cbranch_scc1 .Lgu_done
	s_mov_b32 s22, s11
	s_lshl_b32 s30, s22, 9
	s_add_u32 s40, s18, s30
	s_addc_u32 s41, s19, 0
	global_load_dword v10, v1, s[40:41]
	global_load_dword v11, v1, s[40:41] offset:256
	s_mov_b32 s31, s12
	s_add_u32 s26, s22, s31
	s_min_u32 s26, s26, 0x7fff
	s_waitcnt vmcnt(0)
	v_mov_b32_e32 v8, v10
	v_mov_b32_e32 v9, v11
	s_lshl_b32 s30, s26, 9
	s_add_u32 s40, s18, s30
	s_addc_u32 s41, s19, 0
	global_load_dword v10, v1, s[40:41]
	global_load_dword v11, v1, s[40:41] offset:256
	ds_bpermute_b32 v192, v4, v8
	ds_bpermute_b32 v193, v4, v8 offset:32
	ds_bpermute_b32 v194, v4, v8 offset:64
	ds_bpermute_b32 v195, v4, v8 offset:96
	ds_bpermute_b32 v196, v4, v8 offset:128
	ds_bpermute_b32 v197, v4, v8 offset:160
	ds_bpermute_b32 v198, v4, v8 offset:192
	ds_bpermute_b32 v199, v4, v8 offset:224
	ds_bpermute_b32 v200, v4, v9
	ds_bpermute_b32 v201, v4, v9 offset:32
	ds_bpermute_b32 v202, v4, v9 offset:64
	ds_bpermute_b32 v203, v4, v9 offset:96
	ds_bpermute_b32 v204, v4, v9 offset:128
	ds_bpermute_b32 v205, v4, v9 offset:160
	ds_bpermute_b32 v206, v4, v9 offset:192
	ds_bpermute_b32 v207, v4, v9 offset:224
	s_lshl_b32 s30, s22, 12
	s_add_u32 s66, s16, s30
	s_addc_u32 s67, s17, 0
	global_load_dwordx4 v[208:211], v7, s[66:67]
	global_load_dwordx4 v[212:215], v7, s[66:67] offset:16
	global_load_dwordx4 v[216:219], v7, s[66:67] offset:32
	global_load_dwordx4 v[220:223], v7, s[66:67] offset:48
	s_waitcnt lgkmcnt(15)
	v_lshl_add_u32 v192, v192, 7, v3
	global_load_dwordx4 v[64:67], v192, s[14:15]
	s_waitcnt lgkmcnt(14)
	v_lshl_add_u32 v193, v193, 7, v3
	global_load_dwordx4 v[68:71], v193, s[14:15]
	s_waitcnt lgkmcnt(13)
	v_lshl_add_u32 v194, v194, 7, v3
	global_load_dwordx4 v[72:75], v194, s[14:15]
	s_waitcnt lgkmcnt(12)
	v_lshl_add_u32 v195, v195, 7, v3
	global_load_dwordx4 v[76:79], v195, s[14:15]
	s_waitcnt lgkmcnt(11)
	v_lshl_add_u32 v196, v196, 7, v3
	global_load_dwordx4 v[80:83], v196, s[14:15]
	s_waitcnt lgkmcnt(10)
	v_lshl_add_u32 v197, v197, 7, v3
	global_load_dwordx4 v[84:87], v197, s[14:15]
	s_waitcnt lgkmcnt(9)
	v_lshl_add_u32 v198, v198, 7, v3
	global_load_dwordx4 v[88:91], v198, s[14:15]
	s_waitcnt lgkmcnt(8)
	v_lshl_add_u32 v199, v199, 7, v3
	global_load_dwordx4 v[92:95], v199, s[14:15]
	s_waitcnt lgkmcnt(7)
	v_lshl_add_u32 v200, v200, 7, v3
	global_load_dwordx4 v[96:99], v200, s[14:15]
	s_waitcnt lgkmcnt(6)
	v_lshl_add_u32 v201, v201, 7, v3
	global_load_dwordx4 v[100:103], v201, s[14:15]
	s_waitcnt lgkmcnt(5)
	v_lshl_add_u32 v202, v202, 7, v3
	global_load_dwordx4 v[104:107], v202, s[14:15]
	s_waitcnt lgkmcnt(4)
	v_lshl_add_u32 v203, v203, 7, v3
	global_load_dwordx4 v[108:111], v203, s[14:15]
	s_waitcnt lgkmcnt(3)
	v_lshl_add_u32 v204, v204, 7, v3
	global_load_dwordx4 v[112:115], v204, s[14:15]
	s_waitcnt lgkmcnt(2)
	v_lshl_add_u32 v205, v205, 7, v3
	global_load_dwordx4 v[116:119], v205, s[14:15]
	s_waitcnt lgkmcnt(1)
	v_lshl_add_u32 v206, v206, 7, v3
	global_load_dwordx4 v[120:123], v206, s[14:15]
	s_waitcnt lgkmcnt(0)
	v_lshl_add_u32 v207, v207, 7, v3
	global_load_dwordx4 v[124:127], v207, s[14:15]
	s_mov_b32 s42, s26
.Lgu_loop:
	s_waitcnt vmcnt(20)
	v_mov_b32_e32 v8, v10
	v_mov_b32_e32 v9, v11
	s_mov_b32 s31, s12
	s_add_u32 s26, s22, s31
	s_min_u32 s26, s26, 0x7fff
	s_mov_b32 s42, s26
	s_mul_i32 s31, s12, 2
	s_add_u32 s26, s22, s31
	s_min_u32 s26, s26, 0x7fff
	s_lshl_b32 s30, s26, 9
	s_add_u32 s40, s18, s30
	s_addc_u32 s41, s19, 0
	global_load_dword v10, v1, s[40:41]
	global_load_dword v11, v1, s[40:41] offset:256
	ds_bpermute_b32 v192, v4, v8
	ds_bpermute_b32 v193, v4, v8 offset:32
	ds_bpermute_b32 v194, v4, v8 offset:64
	ds_bpermute_b32 v195, v4, v8 offset:96
	ds_bpermute_b32 v196, v4, v8 offset:128
	ds_bpermute_b32 v197, v4, v8 offset:160
	ds_bpermute_b32 v198, v4, v8 offset:192
	ds_bpermute_b32 v199, v4, v8 offset:224
	ds_bpermute_b32 v200, v4, v9
	ds_bpermute_b32 v201, v4, v9 offset:32
	ds_bpermute_b32 v202, v4, v9 offset:64
	ds_bpermute_b32 v203, v4, v9 offset:96
	ds_bpermute_b32 v204, v4, v9 offset:128
	ds_bpermute_b32 v205, v4, v9 offset:160
	ds_bpermute_b32 v206, v4, v9 offset:192
	ds_bpermute_b32 v207, v4, v9 offset:224
	s_lshl_b32 s30, s42, 12
	s_add_u32 s66, s16, s30
	s_addc_u32 s67, s17, 0
	global_load_dwordx4 v[224:227], v7, s[66:67]
	global_load_dwordx4 v[228:231], v7, s[66:67] offset:16
	global_load_dwordx4 v[232:235], v7, s[66:67] offset:32
	global_load_dwordx4 v[236:239], v7, s[66:67] offset:48
	s_waitcnt lgkmcnt(15)
	v_lshl_add_u32 v192, v192, 7, v3
	global_load_dwordx4 v[128:131], v192, s[14:15]
	s_waitcnt lgkmcnt(14)
	v_lshl_add_u32 v193, v193, 7, v3
	global_load_dwordx4 v[132:135], v193, s[14:15]
	s_waitcnt lgkmcnt(13)
	v_lshl_add_u32 v194, v194, 7, v3
	global_load_dwordx4 v[136:139], v194, s[14:15]
	s_waitcnt lgkmcnt(12)
	v_lshl_add_u32 v195, v195, 7, v3
	global_load_dwordx4 v[140:143], v195, s[14:15]
	s_waitcnt lgkmcnt(11)
	v_lshl_add_u32 v196, v196, 7, v3
	global_load_dwordx4 v[144:147], v196, s[14:15]
	s_waitcnt lgkmcnt(10)
	v_lshl_add_u32 v197, v197, 7, v3
	global_load_dwordx4 v[148:151], v197, s[14:15]
	s_waitcnt lgkmcnt(9)
	v_lshl_add_u32 v198, v198, 7, v3
	global_load_dwordx4 v[152:155], v198, s[14:15]
	s_waitcnt lgkmcnt(8)
	v_lshl_add_u32 v199, v199, 7, v3
	global_load_dwordx4 v[156:159], v199, s[14:15]
	s_waitcnt lgkmcnt(7)
	v_lshl_add_u32 v200, v200, 7, v3
	global_load_dwordx4 v[160:163], v200, s[14:15]
	s_waitcnt lgkmcnt(6)
	v_lshl_add_u32 v201, v201, 7, v3
	global_load_dwordx4 v[164:167], v201, s[14:15]
	s_waitcnt lgkmcnt(5)
	v_lshl_add_u32 v202, v202, 7, v3
	global_load_dwordx4 v[168:171], v202, s[14:15]
	s_waitcnt lgkmcnt(4)
	v_lshl_add_u32 v203, v203, 7, v3
	global_load_dwordx4 v[172:175], v203, s[14:15]
	s_waitcnt lgkmcnt(3)
	v_lshl_add_u32 v204, v204, 7, v3
	global_load_dwordx4 v[176:179], v204, s[14:15]
	s_waitcnt lgkmcnt(2)
	v_lshl_add_u32 v205, v205, 7, v3
	global_load_dwordx4 v[180:183], v205, s[14:15]
	s_waitcnt lgkmcnt(1)
	v_lshl_add_u32 v206, v206, 7, v3
	global_load_dwordx4 v[184:187], v206, s[14:15]
	s_waitcnt lgkmcnt(0)
	v_lshl_add_u32 v207, v207, 7, v3
	global_load_dwordx4 v[188:191], v207, s[14:15]
	s_waitcnt vmcnt(37)
	v_cvt_pk_f32_fp8_e32 v[40:41], v64
	v_cvt_pk_f32_fp8_sdwa v[42:43], v64 src0_sel:WORD_1
	v_cvt_pk_f32_fp8_e32 v[44:45], v65
	v_cvt_pk_f32_fp8_sdwa v[46:47], v65 src0_sel:WORD_1
	v_cvt_pk_f32_fp8_e32 v[48:49], v66
	v_cvt_pk_f32_fp8_sdwa v[50:51], v66 src0_sel:WORD_1
	v_cvt_pk_f32_fp8_e32 v[52:53], v67
	v_cvt_pk_f32_fp8_sdwa v[54:55], v67 src0_sel:WORD_1
	v_pk_mul_f32 v[24:25], v[40:41], v[208:209]
	v_pk_fma_f32 v[24:25], v[42:43], v[210:211], v[24:25]
	v_pk_fma_f32 v[24:25], v[44:45], v[212:213], v[24:25]
	v_pk_fma_f32 v[24:25], v[46:47], v[214:215], v[24:25]
	v_pk_fma_f32 v[24:25], v[48:49], v[216:217], v[24:25]
	v_pk_fma_f32 v[24:25], v[50:51], v[218:219], v[24:25]
	v_pk_fma_f32 v[24:25], v[52:53], v[220:221], v[24:25]
	v_pk_fma_f32 v[24:25], v[54:55], v[222:223], v[24:25]
	v_add_f32_e32 v56, v24, v25
	ds_write_b32 v5, v56
	s_waitcnt vmcnt(36)
	v_cvt_pk_f32_fp8_e32 v[40:41], v68
	v_cvt_pk_f32_fp8_sdwa v[42:43], v68 src0_sel:WORD_1
	v_cvt_pk_f32_fp8_e32 v[44:45], v69
	v_cvt_pk_f32_fp8_sdwa v[46:47], v69 src0_sel:WORD_1
	v_cvt_pk_f32_fp8_e32 v[48:49], v70
	v_cvt_pk_f32_fp8_sdwa v[50:51], v70 src0_sel:WORD_1
	v_cvt_pk_f32_fp8_e32 v[52:53], v71
	v_cvt_pk_f32_fp8_sdwa v[54:55], v71 src0_sel:WORD_1
	v_pk_mul_f32 v[24:25], v[40:41], v[208:209]
	v_pk_fma_f32 v[24:25], v[42:43], v[210:211], v[24:25]
	v_pk_fma_f32 v[24:25], v[44:45], v[212:213], v[24:25]
	v_pk_fma_f32 v[24:25], v[46:47], v[214:215], v[24:25]
	v_pk_fma_f32 v[24:25], v[48:49], v[216:217], v[24:25]
	v_pk_fma_f32 v[24:25], v[50:51], v[218:219], v[24:25]
	v_pk_fma_f32 v[24:25], v[52:53], v[220:221], v[24:25]
	v_pk_fma_f32 v[24:25], v[54:55], v[222:223], v[24:25]
	v_add_f32_e32 v56, v24, v25
	ds_write_b32 v5, v56 offset:256
	s_waitcnt vmcnt(35)
	v_cvt_pk_f32_fp8_e32 v[40:41], v72
	v_cvt_pk_f32_fp8_sdwa v[42:43], v72 src0_sel:WORD_1
	v_cvt_pk_f32_fp8_e32 v[44:45], v73
	v_cvt_pk_f32_fp8_sdwa v[46:47], v73 src0_sel:WORD_1
	v_cvt_pk_f32_fp8_e32 v[48:49], v74
	v_cvt_pk_f32_fp8_sdwa v[50:51], v74 src0_sel:WORD_1
	v_cvt_pk_f32_fp8_e32 v[52:53], v75
	v_cvt_pk_f32_fp8_sdwa v[54:55], v75 src0_sel:WORD_1
	v_pk_mul_f32 v[24:25], v[40:41], v[208:209]
	v_pk_fma_f32 v[24:25], v[42:43], v[210:211], v[24:25]
	v_pk_fma_f32 v[24:25], v[44:45], v[212:213], v[24:25]
	v_pk_fma_f32 v[24:25], v[46:47], v[214:215], v[24:25]
	v_pk_fma_f32 v[24:25], v[48:49], v[216:217], v[24:25]
	v_pk_fma_f32 v[24:25], v[50:51], v[218:219], v[24:25]
	v_pk_fma_f32 v[24:25], v[52:53], v[220:221], v[24:25]
	v_pk_fma_f32 v[24:25], v[54:55], v[222:223], v[24:25]
	v_add_f32_e32 v56, v24, v25
	ds_write_b32 v5, v56 offset:512
	s_waitcnt vmcnt(34)
	v_cvt_pk_f32_fp8_e32 v[40:41], v76
	v_cvt_pk_f32_fp8_sdwa v[42:43], v76 src0_sel:WORD_1
	v_cvt_pk_f32_fp8_e32 v[44:45], v77
	v_cvt_pk_f32_fp8_sdwa v[46:47], v77 src0_sel:WORD_1
	v_cvt_pk_f32_fp8_e32 v[48:49], v78
	v_cvt_pk_f32_fp8_sdwa v[50:51], v78 src0_sel:WORD_1
	v_cvt_pk_f32_fp8_e32 v[52:53], v79
	v_cvt_pk_f32_fp8_sdwa v[54:55], v79 src0_sel:WORD_1
	v_pk_mul_f32 v[24:25], v[40:41], v[208:209]
	v_pk_fma_f32 v[24:25], v[42:43], v[210:211], v[24:25]
	v_pk_fma_f32 v[24:25], v[44:45], v[212:213], v[24:25]
	v_pk_fma_f32 v[24:25], v[46:47], v[214:215], v[24:25]
	v_pk_fma_f32 v[24:25], v[48:49], v[216:217], v[24:25]
	v_pk_fma_f32 v[24:25], v[50:51], v[218:219], v[24:25]
	v_pk_fma_f32 v[24:25], v[52:53], v[220:221], v[24:25]
	v_pk_fma_f32 v[24:25], v[54:55], v[222:223], v[24:25]
	v_add_f32_e32 v56, v24, v25
	ds_write_b32 v5, v56 offset:768
	s_waitcnt vmcnt(33)
	v_cvt_pk_f32_fp8_e32 v[40:41], v80
	v_cvt_pk_f32_fp8_sdwa v[42:43], v80 src0_sel:WORD_1
	v_cvt_pk_f32_fp8_e32 v[44:45], v81
	v_cvt_pk_f32_fp8_sdwa v[46:47], v81 src0_sel:WORD_1
	v_cvt_pk_f32_fp8_e32 v[48:49], v82
	v_cvt_pk_f32_fp8_sdwa v[50:51], v82 src0_sel:WORD_1
	v_cvt_pk_f32_fp8_e32 v[52:53], v83
	v_cvt_pk_f32_fp8_sdwa v[54:55], v83 src0_sel:WORD_1
	v_pk_mul_f32 v[24:25], v[40:41], v[208:209]
	v_pk_fma_f32 v[24:25], v[42:43], v[210:211], v[24:25]
	v_pk_fma_f32 v[24:25], v[44:45], v[212:213], v[24:25]
	v_pk_fma_f32 v[24:25], v[46:47], v[214:215], v[24:25]
	v_pk_fma_f32 v[24:25], v[48:49], v[216:217], v[24:25]
	v_pk_fma_f32 v[24:25], v[50:51], v[218:219], v[24:25]
	v_pk_fma_f32 v[24:25], v[52:53], v[220:221], v[24:25]
	v_pk_fma_f32 v[24:25], v[54:55], v[222:223], v[24:25]
	v_add_f32_e32 v56, v24, v25
	ds_write_b32 v5, v56 offset:1024
	s_waitcnt vmcnt(32)
	v_cvt_pk_f32_fp8_e32 v[40:41], v84
	v_cvt_pk_f32_fp8_sdwa v[42:43], v84 src0_sel:WORD_1
	v_cvt_pk_f32_fp8_e32 v[44:45], v85
	v_cvt_pk_f32_fp8_sdwa v[46:47], v85 src0_sel:WORD_1
	v_cvt_pk_f32_fp8_e32 v[48:49], v86
	v_cvt_pk_f32_fp8_sdwa v[50:51], v86 src0_sel:WORD_1
	v_cvt_pk_f32_fp8_e32 v[52:53], v87
	v_cvt_pk_f32_fp8_sdwa v[54:55], v87 src0_sel:WORD_1
	v_pk_mul_f32 v[24:25], v[40:41], v[208:209]
	v_pk_fma_f32 v[24:25], v[42:43], v[210:211], v[24:25]
	v_pk_fma_f32 v[24:25], v[44:45], v[212:213], v[24:25]
	v_pk_fma_f32 v[24:25], v[46:47], v[214:215], v[24:25]
	v_pk_fma_f32 v[24:25], v[48:49], v[216:217], v[24:25]
	v_pk_fma_f32 v[24:25], v[50:51], v[218:219], v[24:25]
	v_pk_fma_f32 v[24:25], v[52:53], v[220:221], v[24:25]
	v_pk_fma_f32 v[24:25], v[54:55], v[222:223], v[24:25]
	v_add_f32_e32 v56, v24, v25
	ds_write_b32 v5, v56 offset:1280
	s_waitcnt vmcnt(31)
	v_cvt_pk_f32_fp8_e32 v[40:41], v88
	v_cvt_pk_f32_fp8_sdwa v[42:43], v88 src0_sel:WORD_1
	v_cvt_pk_f32_fp8_e32 v[44:45], v89
	v_cvt_pk_f32_fp8_sdwa v[46:47], v89 src0_sel:WORD_1
	v_cvt_pk_f32_fp8_e32 v[48:49], v90
	v_cvt_pk_f32_fp8_sdwa v[50:51], v90 src0_sel:WORD_1
	v_cvt_pk_f32_fp8_e32 v[52:53], v91
	v_cvt_pk_f32_fp8_sdwa v[54:55], v91 src0_sel:WORD_1
	v_pk_mul_f32 v[24:25], v[40:41], v[208:209]
	v_pk_fma_f32 v[24:25], v[42:43], v[210:211], v[24:25]
	v_pk_fma_f32 v[24:25], v[44:45], v[212:213], v[24:25]
	v_pk_fma_f32 v[24:25], v[46:47], v[214:215], v[24:25]
	v_pk_fma_f32 v[24:25], v[48:49], v[216:217], v[24:25]
	v_pk_fma_f32 v[24:25], v[50:51], v[218:219], v[24:25]
	v_pk_fma_f32 v[24:25], v[52:53], v[220:221], v[24:25]
	v_pk_fma_f32 v[24:25], v[54:55], v[222:223], v[24:25]
	v_add_f32_e32 v56, v24, v25
	ds_write_b32 v5, v56 offset:1536
	s_waitcnt vmcnt(30)
	v_cvt_pk_f32_fp8_e32 v[40:41], v92
	v_cvt_pk_f32_fp8_sdwa v[42:43], v92 src0_sel:WORD_1
	v_cvt_pk_f32_fp8_e32 v[44:45], v93
	v_cvt_pk_f32_fp8_sdwa v[46:47], v93 src0_sel:WORD_1
	v_cvt_pk_f32_fp8_e32 v[48:49], v94
	v_cvt_pk_f32_fp8_sdwa v[50:51], v94 src0_sel:WORD_1
	v_cvt_pk_f32_fp8_e32 v[52:53], v95
	v_cvt_pk_f32_fp8_sdwa v[54:55], v95 src0_sel:WORD_1
	v_pk_mul_f32 v[24:25], v[40:41], v[208:209]
	v_pk_fma_f32 v[24:25], v[42:43], v[210:211], v[24:25]
	v_pk_fma_f32 v[24:25], v[44:45], v[212:213], v[24:25]
	v_pk_fma_f32 v[24:25], v[46:47], v[214:215], v[24:25]
	v_pk_fma_f32 v[24:25], v[48:49], v[216:217], v[24:25]
	v_pk_fma_f32 v[24:25], v[50:51], v[218:219], v[24:25]
	v_pk_fma_f32 v[24:25], v[52:53], v[220:221], v[24:25]
	v_pk_fma_f32 v[24:25], v[54:55], v[222:223], v[24:25]
	v_add_f32_e32 v56, v24, v25
	ds_write_b32 v5, v56 offset:1792
	s_waitcnt vmcnt(29)
	v_cvt_pk_f32_fp8_e32 v[40:41], v96
	v_cvt_pk_f32_fp8_sdwa v[42:43], v96 src0_sel:WORD_1
	v_cvt_pk_f32_fp8_e32 v[44:45], v97
	v_cvt_pk_f32_fp8_sdwa v[46:47], v97 src0_sel:WORD_1
	v_cvt_pk_f32_fp8_e32 v[48:49], v98
	v_cvt_pk_f32_fp8_sdwa v[50:51], v98 src0_sel:WORD_1
	v_cvt_pk_f32_fp8_e32 v[52:53], v99
	v_cvt_pk_f32_fp8_sdwa v[54:55], v99 src0_sel:WORD_1
	v_pk_mul_f32 v[24:25], v[40:41], v[208:209]
	v_pk_fma_f32 v[24:25], v[42:43], v[210:211], v[24:25]
	v_pk_fma_f32 v[24:25], v[44:45], v[212:213], v[24:25]
	v_pk_fma_f32 v[24:25], v[46:47], v[214:215], v[24:25]
	v_pk_fma_f32 v[24:25], v[48:49], v[216:217], v[24:25]
	v_pk_fma_f32 v[24:25], v[50:51], v[218:219], v[24:25]
	v_pk_fma_f32 v[24:25], v[52:53], v[220:221], v[24:25]
	v_pk_fma_f32 v[24:25], v[54:55], v[222:223], v[24:25]
	v_add_f32_e32 v56, v24, v25
	ds_write_b32 v5, v56 offset:2048
	s_waitcnt vmcnt(28)
	v_cvt_pk_f32_fp8_e32 v[40:41], v100
	v_cvt_pk_f32_fp8_sdwa v[42:43], v100 src0_sel:WORD_1
	v_cvt_pk_f32_fp8_e32 v[44:45], v101
	v_cvt_pk_f32_fp8_sdwa v[46:47], v101 src0_sel:WORD_1
	v_cvt_pk_f32_fp8_e32 v[48:49], v102
	v_cvt_pk_f32_fp8_sdwa v[50:51], v102 src0_sel:WORD_1
	v_cvt_pk_f32_fp8_e32 v[52:53], v103
	v_cvt_pk_f32_fp8_sdwa v[54:55], v103 src0_sel:WORD_1
	v_pk_mul_f32 v[24:25], v[40:41], v[208:209]
	v_pk_fma_f32 v[24:25], v[42:43], v[210:211], v[24:25]
	v_pk_fma_f32 v[24:25], v[44:45], v[212:213], v[24:25]
	v_pk_fma_f32 v[24:25], v[46:47], v[214:215], v[24:25]
	v_pk_fma_f32 v[24:25], v[48:49], v[216:217], v[24:25]
	v_pk_fma_f32 v[24:25], v[50:51], v[218:219], v[24:25]
	v_pk_fma_f32 v[24:25], v[52:53], v[220:221], v[24:25]
	v_pk_fma_f32 v[24:25], v[54:55], v[222:223], v[24:25]
	v_add_f32_e32 v56, v24, v25
	ds_write_b32 v5, v56 offset:2304
	s_waitcnt vmcnt(27)
	v_cvt_pk_f32_fp8_e32 v[40:41], v104
	v_cvt_pk_f32_fp8_sdwa v[42:43], v104 src0_sel:WORD_1
	v_cvt_pk_f32_fp8_e32 v[44:45], v105
	v_cvt_pk_f32_fp8_sdwa v[46:47], v105 src0_sel:WORD_1
	v_cvt_pk_f32_fp8_e32 v[48:49], v106
	v_cvt_pk_f32_fp8_sdwa v[50:51], v106 src0_sel:WORD_1
	v_cvt_pk_f32_fp8_e32 v[52:53], v107
	v_cvt_pk_f32_fp8_sdwa v[54:55], v107 src0_sel:WORD_1
	v_pk_mul_f32 v[24:25], v[40:41], v[208:209]
	v_pk_fma_f32 v[24:25], v[42:43], v[210:211], v[24:25]
	v_pk_fma_f32 v[24:25], v[44:45], v[212:213], v[24:25]
	v_pk_fma_f32 v[24:25], v[46:47], v[214:215], v[24:25]
	v_pk_fma_f32 v[24:25], v[48:49], v[216:217], v[24:25]
	v_pk_fma_f32 v[24:25], v[50:51], v[218:219], v[24:25]
	v_pk_fma_f32 v[24:25], v[52:53], v[220:221], v[24:25]
	v_pk_fma_f32 v[24:25], v[54:55], v[222:223], v[24:25]
	v_add_f32_e32 v56, v24, v25
	ds_write_b32 v5, v56 offset:2560
	s_waitcnt vmcnt(26)
	v_cvt_pk_f32_fp8_e32 v[40:41], v108
	v_cvt_pk_f32_fp8_sdwa v[42:43], v108 src0_sel:WORD_1
	v_cvt_pk_f32_fp8_e32 v[44:45], v109
	v_cvt_pk_f32_fp8_sdwa v[46:47], v109 src0_sel:WORD_1
	v_cvt_pk_f32_fp8_e32 v[48:49], v110
	v_cvt_pk_f32_fp8_sdwa v[50:51], v110 src0_sel:WORD_1
	v_cvt_pk_f32_fp8_e32 v[52:53], v111
	v_cvt_pk_f32_fp8_sdwa v[54:55], v111 src0_sel:WORD_1
	v_pk_mul_f32 v[24:25], v[40:41], v[208:209]
	v_pk_fma_f32 v[24:25], v[42:43], v[210:211], v[24:25]
	v_pk_fma_f32 v[24:25], v[44:45], v[212:213], v[24:25]
	v_pk_fma_f32 v[24:25], v[46:47], v[214:215], v[24:25]
	v_pk_fma_f32 v[24:25], v[48:49], v[216:217], v[24:25]
	v_pk_fma_f32 v[24:25], v[50:51], v[218:219], v[24:25]
	v_pk_fma_f32 v[24:25], v[52:53], v[220:221], v[24:25]
	v_pk_fma_f32 v[24:25], v[54:55], v[222:223], v[24:25]
	v_add_f32_e32 v56, v24, v25
	ds_write_b32 v5, v56 offset:2816
	s_waitcnt vmcnt(25)
	v_cvt_pk_f32_fp8_e32 v[40:41], v112
	v_cvt_pk_f32_fp8_sdwa v[42:43], v112 src0_sel:WORD_1
	v_cvt_pk_f32_fp8_e32 v[44:45], v113
	v_cvt_pk_f32_fp8_sdwa v[46:47], v113 src0_sel:WORD_1
	v_cvt_pk_f32_fp8_e32 v[48:49], v114
	v_cvt_pk_f32_fp8_sdwa v[50:51], v114 src0_sel:WORD_1
	v_cvt_pk_f32_fp8_e32 v[52:53], v115
	v_cvt_pk_f32_fp8_sdwa v[54:55], v115 src0_sel:WORD_1
	v_pk_mul_f32 v[24:25], v[40:41], v[208:209]
	v_pk_fma_f32 v[24:25], v[42:43], v[210:211], v[24:25]
	v_pk_fma_f32 v[24:25], v[44:45], v[212:213], v[24:25]
	v_pk_fma_f32 v[24:25], v[46:47], v[214:215], v[24:25]
	v_pk_fma_f32 v[24:25], v[48:49], v[216:217], v[24:25]
	v_pk_fma_f32 v[24:25], v[50:51], v[218:219], v[24:25]
	v_pk_fma_f32 v[24:25], v[52:53], v[220:221], v[24:25]
	v_pk_fma_f32 v[24:25], v[54:55], v[222:223], v[24:25]
	v_add_f32_e32 v56, v24, v25
	ds_write_b32 v5, v56 offset:3072
	s_waitcnt vmcnt(24)
	v_cvt_pk_f32_fp8_e32 v[40:41], v116
	v_cvt_pk_f32_fp8_sdwa v[42:43], v116 src0_sel:WORD_1
	v_cvt_pk_f32_fp8_e32 v[44:45], v117
	v_cvt_pk_f32_fp8_sdwa v[46:47], v117 src0_sel:WORD_1
	v_cvt_pk_f32_fp8_e32 v[48:49], v118
	v_cvt_pk_f32_fp8_sdwa v[50:51], v118 src0_sel:WORD_1
	v_cvt_pk_f32_fp8_e32 v[52:53], v119
	v_cvt_pk_f32_fp8_sdwa v[54:55], v119 src0_sel:WORD_1
	v_pk_mul_f32 v[24:25], v[40:41], v[208:209]
	v_pk_fma_f32 v[24:25], v[42:43], v[210:211], v[24:25]
	v_pk_fma_f32 v[24:25], v[44:45], v[212:213], v[24:25]
	v_pk_fma_f32 v[24:25], v[46:47], v[214:215], v[24:25]
	v_pk_fma_f32 v[24:25], v[48:49], v[216:217], v[24:25]
	v_pk_fma_f32 v[24:25], v[50:51], v[218:219], v[24:25]
	v_pk_fma_f32 v[24:25], v[52:53], v[220:221], v[24:25]
	v_pk_fma_f32 v[24:25], v[54:55], v[222:223], v[24:25]
	v_add_f32_e32 v56, v24, v25
	ds_write_b32 v5, v56 offset:3328
	s_waitcnt vmcnt(23)
	v_cvt_pk_f32_fp8_e32 v[40:41], v120
	v_cvt_pk_f32_fp8_sdwa v[42:43], v120 src0_sel:WORD_1
	v_cvt_pk_f32_fp8_e32 v[44:45], v121
	v_cvt_pk_f32_fp8_sdwa v[46:47], v121 src0_sel:WORD_1
	v_cvt_pk_f32_fp8_e32 v[48:49], v122
	v_cvt_pk_f32_fp8_sdwa v[50:51], v122 src0_sel:WORD_1
	v_cvt_pk_f32_fp8_e32 v[52:53], v123
	v_cvt_pk_f32_fp8_sdwa v[54:55], v123 src0_sel:WORD_1
	v_pk_mul_f32 v[24:25], v[40:41], v[208:209]
	v_pk_fma_f32 v[24:25], v[42:43], v[210:211], v[24:25]
	v_pk_fma_f32 v[24:25], v[44:45], v[212:213], v[24:25]
	v_pk_fma_f32 v[24:25], v[46:47], v[214:215], v[24:25]
	v_pk_fma_f32 v[24:25], v[48:49], v[216:217], v[24:25]
	v_pk_fma_f32 v[24:25], v[50:51], v[218:219], v[24:25]
	v_pk_fma_f32 v[24:25], v[52:53], v[220:221], v[24:25]
	v_pk_fma_f32 v[24:25], v[54:55], v[222:223], v[24:25]
	v_add_f32_e32 v56, v24, v25
	ds_write_b32 v5, v56 offset:3584
	s_waitcnt vmcnt(22)
	v_cvt_pk_f32_fp8_e32 v[40:41], v124
	v_cvt_pk_f32_fp8_sdwa v[42:43], v124 src0_sel:WORD_1
	v_cvt_pk_f32_fp8_e32 v[44:45], v125
	v_cvt_pk_f32_fp8_sdwa v[46:47], v125 src0_sel:WORD_1
	v_cvt_pk_f32_fp8_e32 v[48:49], v126
	v_cvt_pk_f32_fp8_sdwa v[50:51], v126 src0_sel:WORD_1
	v_cvt_pk_f32_fp8_e32 v[52:53], v127
	v_cvt_pk_f32_fp8_sdwa v[54:55], v127 src0_sel:WORD_1
	v_pk_mul_f32 v[24:25], v[40:41], v[208:209]
	v_pk_fma_f32 v[24:25], v[42:43], v[210:211], v[24:25]
	v_pk_fma_f32 v[24:25], v[44:45], v[212:213], v[24:25]
	v_pk_fma_f32 v[24:25], v[46:47], v[214:215], v[24:25]
	v_pk_fma_f32 v[24:25], v[48:49], v[216:217], v[24:25]
	v_pk_fma_f32 v[24:25], v[50:51], v[218:219], v[24:25]
	v_pk_fma_f32 v[24:25], v[52:53], v[220:221], v[24:25]
	v_pk_fma_f32 v[24:25], v[54:55], v[222:223], v[24:25]
	v_add_f32_e32 v56, v24, v25
	ds_write_b32 v5, v56 offset:3840
	ds_read_b128 v[40:43], v6
	ds_read_b128 v[44:47], v6 offset:16
	ds_read_b128 v[48:51], v6 offset:2048
	ds_read_b128 v[52:55], v6 offset:2064
	s_waitcnt lgkmcnt(2)
	v_add_f32_e32 v40, v40, v41
	v_add_f32_e32 v40, v40, v42
	v_add_f32_e32 v40, v40, v43
	v_add_f32_e32 v40, v40, v44
	v_add_f32_e32 v40, v40, v45
	v_add_f32_e32 v40, v40, v46
	v_add_f32_e32 v40, v40, v47
	s_waitcnt lgkmcnt(0)
	v_add_f32_e32 v48, v48, v49
	v_add_f32_e32 v48, v48, v50
	v_add_f32_e32 v48, v48, v51
	v_add_f32_e32 v48, v48, v52
	v_add_f32_e32 v48, v48, v53
	v_add_f32_e32 v48, v48, v54
	v_add_f32_e32 v48, v48, v55
	s_lshl_b32 s30, s22, 12
	s_add_u32 s66, s20, s30
	s_addc_u32 s67, s21, 0
	global_store_dword v1, v40, s[66:67]
	global_store_dword v1, v48, s[66:67] offset:256
	s_add_u32 s22, s22, s12
	s_cmp_ge_u32 s22, 0x8000
	s_cbranch_scc1 .Lgu_done
	s_waitcnt vmcnt(20)
	v_mov_b32_e32 v8, v10
	v_mov_b32_e32 v9, v11
	s_mov_b32 s31, s12
	s_add_u32 s26, s22, s31
	s_min_u32 s26, s26, 0x7fff
	s_mov_b32 s42, s26
	s_mul_i32 s31, s12, 2
	s_add_u32 s26, s22, s31
	s_min_u32 s26, s26, 0x7fff
	s_lshl_b32 s30, s26, 9
	s_add_u32 s40, s18, s30
	s_addc_u32 s41, s19, 0
	global_load_dword v10, v1, s[40:41]
	global_load_dword v11, v1, s[40:41] offset:256
	ds_bpermute_b32 v192, v4, v8
	ds_bpermute_b32 v193, v4, v8 offset:32
	ds_bpermute_b32 v194, v4, v8 offset:64
	ds_bpermute_b32 v195, v4, v8 offset:96
	ds_bpermute_b32 v196, v4, v8 offset:128
	ds_bpermute_b32 v197, v4, v8 offset:160
	ds_bpermute_b32 v198, v4, v8 offset:192
	ds_bpermute_b32 v199, v4, v8 offset:224
	ds_bpermute_b32 v200, v4, v9
	ds_bpermute_b32 v201, v4, v9 offset:32
	ds_bpermute_b32 v202, v4, v9 offset:64
	ds_bpermute_b32 v203, v4, v9 offset:96
	ds_bpermute_b32 v204, v4, v9 offset:128
	ds_bpermute_b32 v205, v4, v9 offset:160
	ds_bpermute_b32 v206, v4, v9 offset:192
	ds_bpermute_b32 v207, v4, v9 offset:224
	s_lshl_b32 s30, s42, 12
	s_add_u32 s66, s16, s30
	s_addc_u32 s67, s17, 0
	global_load_dwordx4 v[208:211], v7, s[66:67]
	global_load_dwordx4 v[212:215], v7, s[66:67] offset:16
	global_load_dwordx4 v[216:219], v7, s[66:67] offset:32
	global_load_dwordx4 v[220:223], v7, s[66:67] offset:48
	s_waitcnt lgkmcnt(15)
	v_lshl_add_u32 v192, v192, 7, v3
	global_load_dwordx4 v[64:67], v192, s[14:15]
	s_waitcnt lgkmcnt(14)
	v_lshl_add_u32 v193, v193, 7, v3
	global_load_dwordx4 v[68:71], v193, s[14:15]
	s_waitcnt lgkmcnt(13)
	v_lshl_add_u32 v194, v194, 7, v3
	global_load_dwordx4 v[72:75], v194, s[14:15]
	s_waitcnt lgkmcnt(12)
	v_lshl_add_u32 v195, v195, 7, v3
	global_load_dwordx4 v[76:79], v195, s[14:15]
	s_waitcnt lgkmcnt(11)
	v_lshl_add_u32 v196, v196, 7, v3
	global_load_dwordx4 v[80:83], v196, s[14:15]
	s_waitcnt lgkmcnt(10)
	v_lshl_add_u32 v197, v197, 7, v3
	global_load_dwordx4 v[84:87], v197, s[14:15]
	s_waitcnt lgkmcnt(9)
	v_lshl_add_u32 v198, v198, 7, v3
	global_load_dwordx4 v[88:91], v198, s[14:15]
	s_waitcnt lgkmcnt(8)
	v_lshl_add_u32 v199, v199, 7, v3
	global_load_dwordx4 v[92:95], v199, s[14:15]
	s_waitcnt lgkmcnt(7)
	v_lshl_add_u32 v200, v200, 7, v3
	global_load_dwordx4 v[96:99], v200, s[14:15]
	s_waitcnt lgkmcnt(6)
	v_lshl_add_u32 v201, v201, 7, v3
	global_load_dwordx4 v[100:103], v201, s[14:15]
	s_waitcnt lgkmcnt(5)
	v_lshl_add_u32 v202, v202, 7, v3
	global_load_dwordx4 v[104:107], v202, s[14:15]
	s_waitcnt lgkmcnt(4)
	v_lshl_add_u32 v203, v203, 7, v3
	global_load_dwordx4 v[108:111], v203, s[14:15]
	s_waitcnt lgkmcnt(3)
	v_lshl_add_u32 v204, v204, 7, v3
	global_load_dwordx4 v[112:115], v204, s[14:15]
	s_waitcnt lgkmcnt(2)
	v_lshl_add_u32 v205, v205, 7, v3
	global_load_dwordx4 v[116:119], v205, s[14:15]
	s_waitcnt lgkmcnt(1)
	v_lshl_add_u32 v206, v206, 7, v3
	global_load_dwordx4 v[120:123], v206, s[14:15]
	s_waitcnt lgkmcnt(0)
	v_lshl_add_u32 v207, v207, 7, v3
	global_load_dwordx4 v[124:127], v207, s[14:15]
	s_waitcnt vmcnt(37)
	v_cvt_pk_f32_fp8_e32 v[40:41], v128
	v_cvt_pk_f32_fp8_sdwa v[42:43], v128 src0_sel:WORD_1
	v_cvt_pk_f32_fp8_e32 v[44:45], v129
	v_cvt_pk_f32_fp8_sdwa v[46:47], v129 src0_sel:WORD_1
	v_cvt_pk_f32_fp8_e32 v[48:49], v130
	v_cvt_pk_f32_fp8_sdwa v[50:51], v130 src0_sel:WORD_1
	v_cvt_pk_f32_fp8_e32 v[52:53], v131
	v_cvt_pk_f32_fp8_sdwa v[54:55], v131 src0_sel:WORD_1
	v_pk_mul_f32 v[24:25], v[40:41], v[224:225]
	v_pk_fma_f32 v[24:25], v[42:43], v[226:227], v[24:25]
	v_pk_fma_f32 v[24:25], v[44:45], v[228:229], v[24:25]
	v_pk_fma_f32 v[24:25], v[46:47], v[230:231], v[24:25]
	v_pk_fma_f32 v[24:25], v[48:49], v[232:233], v[24:25]
	v_pk_fma_f32 v[24:25], v[50:51], v[234:235], v[24:25]
	v_pk_fma_f32 v[24:25], v[52:53], v[236:237], v[24:25]
	v_pk_fma_f32 v[24:25], v[54:55], v[238:239], v[24:25]
	v_add_f32_e32 v56, v24, v25
	ds_write_b32 v5, v56
	s_waitcnt vmcnt(36)
	v_cvt_pk_f32_fp8_e32 v[40:41], v132
	v_cvt_pk_f32_fp8_sdwa v[42:43], v132 src0_sel:WORD_1
	v_cvt_pk_f32_fp8_e32 v[44:45], v133
	v_cvt_pk_f32_fp8_sdwa v[46:47], v133 src0_sel:WORD_1
	v_cvt_pk_f32_fp8_e32 v[48:49], v134
	v_cvt_pk_f32_fp8_sdwa v[50:51], v134 src0_sel:WORD_1
	v_cvt_pk_f32_fp8_e32 v[52:53], v135
	v_cvt_pk_f32_fp8_sdwa v[54:55], v135 src0_sel:WORD_1
	v_pk_mul_f32 v[24:25], v[40:41], v[224:225]
	v_pk_fma_f32 v[24:25], v[42:43], v[226:227], v[24:25]
	v_pk_fma_f32 v[24:25], v[44:45], v[228:229], v[24:25]
	v_pk_fma_f32 v[24:25], v[46:47], v[230:231], v[24:25]
	v_pk_fma_f32 v[24:25], v[48:49], v[232:233], v[24:25]
	v_pk_fma_f32 v[24:25], v[50:51], v[234:235], v[24:25]
	v_pk_fma_f32 v[24:25], v[52:53], v[236:237], v[24:25]
	v_pk_fma_f32 v[24:25], v[54:55], v[238:239], v[24:25]
	v_add_f32_e32 v56, v24, v25
	ds_write_b32 v5, v56 offset:256
	s_waitcnt vmcnt(35)
	v_cvt_pk_f32_fp8_e32 v[40:41], v136
	v_cvt_pk_f32_fp8_sdwa v[42:43], v136 src0_sel:WORD_1
	v_cvt_pk_f32_fp8_e32 v[44:45], v137
	v_cvt_pk_f32_fp8_sdwa v[46:47], v137 src0_sel:WORD_1
	v_cvt_pk_f32_fp8_e32 v[48:49], v138
	v_cvt_pk_f32_fp8_sdwa v[50:51], v138 src0_sel:WORD_1
	v_cvt_pk_f32_fp8_e32 v[52:53], v139
	v_cvt_pk_f32_fp8_sdwa v[54:55], v139 src0_sel:WORD_1
	v_pk_mul_f32 v[24:25], v[40:41], v[224:225]
	v_pk_fma_f32 v[24:25], v[42:43], v[226:227], v[24:25]
	v_pk_fma_f32 v[24:25], v[44:45], v[228:229], v[24:25]
	v_pk_fma_f32 v[24:25], v[46:47], v[230:231], v[24:25]
	v_pk_fma_f32 v[24:25], v[48:49], v[232:233], v[24:25]
	v_pk_fma_f32 v[24:25], v[50:51], v[234:235], v[24:25]
	v_pk_fma_f32 v[24:25], v[52:53], v[236:237], v[24:25]
	v_pk_fma_f32 v[24:25], v[54:55], v[238:239], v[24:25]
	v_add_f32_e32 v56, v24, v25
	ds_write_b32 v5, v56 offset:512
	s_waitcnt vmcnt(34)
	v_cvt_pk_f32_fp8_e32 v[40:41], v140
	v_cvt_pk_f32_fp8_sdwa v[42:43], v140 src0_sel:WORD_1
	v_cvt_pk_f32_fp8_e32 v[44:45], v141
	v_cvt_pk_f32_fp8_sdwa v[46:47], v141 src0_sel:WORD_1
	v_cvt_pk_f32_fp8_e32 v[48:49], v142
	v_cvt_pk_f32_fp8_sdwa v[50:51], v142 src0_sel:WORD_1
	v_cvt_pk_f32_fp8_e32 v[52:53], v143
	v_cvt_pk_f32_fp8_sdwa v[54:55], v143 src0_sel:WORD_1
	v_pk_mul_f32 v[24:25], v[40:41], v[224:225]
	v_pk_fma_f32 v[24:25], v[42:43], v[226:227], v[24:25]
	v_pk_fma_f32 v[24:25], v[44:45], v[228:229], v[24:25]
	v_pk_fma_f32 v[24:25], v[46:47], v[230:231], v[24:25]
	v_pk_fma_f32 v[24:25], v[48:49], v[232:233], v[24:25]
	v_pk_fma_f32 v[24:25], v[50:51], v[234:235], v[24:25]
	v_pk_fma_f32 v[24:25], v[52:53], v[236:237], v[24:25]
	v_pk_fma_f32 v[24:25], v[54:55], v[238:239], v[24:25]
	v_add_f32_e32 v56, v24, v25
	ds_write_b32 v5, v56 offset:768
	s_waitcnt vmcnt(33)
	v_cvt_pk_f32_fp8_e32 v[40:41], v144
	v_cvt_pk_f32_fp8_sdwa v[42:43], v144 src0_sel:WORD_1
	v_cvt_pk_f32_fp8_e32 v[44:45], v145
	v_cvt_pk_f32_fp8_sdwa v[46:47], v145 src0_sel:WORD_1
	v_cvt_pk_f32_fp8_e32 v[48:49], v146
	v_cvt_pk_f32_fp8_sdwa v[50:51], v146 src0_sel:WORD_1
	v_cvt_pk_f32_fp8_e32 v[52:53], v147
	v_cvt_pk_f32_fp8_sdwa v[54:55], v147 src0_sel:WORD_1
	v_pk_mul_f32 v[24:25], v[40:41], v[224:225]
	v_pk_fma_f32 v[24:25], v[42:43], v[226:227], v[24:25]
	v_pk_fma_f32 v[24:25], v[44:45], v[228:229], v[24:25]
	v_pk_fma_f32 v[24:25], v[46:47], v[230:231], v[24:25]
	v_pk_fma_f32 v[24:25], v[48:49], v[232:233], v[24:25]
	v_pk_fma_f32 v[24:25], v[50:51], v[234:235], v[24:25]
	v_pk_fma_f32 v[24:25], v[52:53], v[236:237], v[24:25]
	v_pk_fma_f32 v[24:25], v[54:55], v[238:239], v[24:25]
	v_add_f32_e32 v56, v24, v25
	ds_write_b32 v5, v56 offset:1024
	s_waitcnt vmcnt(32)
	v_cvt_pk_f32_fp8_e32 v[40:41], v148
	v_cvt_pk_f32_fp8_sdwa v[42:43], v148 src0_sel:WORD_1
	v_cvt_pk_f32_fp8_e32 v[44:45], v149
	v_cvt_pk_f32_fp8_sdwa v[46:47], v149 src0_sel:WORD_1
	v_cvt_pk_f32_fp8_e32 v[48:49], v150
	v_cvt_pk_f32_fp8_sdwa v[50:51], v150 src0_sel:WORD_1
	v_cvt_pk_f32_fp8_e32 v[52:53], v151
	v_cvt_pk_f32_fp8_sdwa v[54:55], v151 src0_sel:WORD_1
	v_pk_mul_f32 v[24:25], v[40:41], v[224:225]
	v_pk_fma_f32 v[24:25], v[42:43], v[226:227], v[24:25]
	v_pk_fma_f32 v[24:25], v[44:45], v[228:229], v[24:25]
	v_pk_fma_f32 v[24:25], v[46:47], v[230:231], v[24:25]
	v_pk_fma_f32 v[24:25], v[48:49], v[232:233], v[24:25]
	v_pk_fma_f32 v[24:25], v[50:51], v[234:235], v[24:25]
	v_pk_fma_f32 v[24:25], v[52:53], v[236:237], v[24:25]
	v_pk_fma_f32 v[24:25], v[54:55], v[238:239], v[24:25]
	v_add_f32_e32 v56, v24, v25
	ds_write_b32 v5, v56 offset:1280
	s_waitcnt vmcnt(31)
	v_cvt_pk_f32_fp8_e32 v[40:41], v152
	v_cvt_pk_f32_fp8_sdwa v[42:43], v152 src0_sel:WORD_1
	v_cvt_pk_f32_fp8_e32 v[44:45], v153
	v_cvt_pk_f32_fp8_sdwa v[46:47], v153 src0_sel:WORD_1
	v_cvt_pk_f32_fp8_e32 v[48:49], v154
	v_cvt_pk_f32_fp8_sdwa v[50:51], v154 src0_sel:WORD_1
	v_cvt_pk_f32_fp8_e32 v[52:53], v155
	v_cvt_pk_f32_fp8_sdwa v[54:55], v155 src0_sel:WORD_1
	v_pk_mul_f32 v[24:25], v[40:41], v[224:225]
	v_pk_fma_f32 v[24:25], v[42:43], v[226:227], v[24:25]
	v_pk_fma_f32 v[24:25], v[44:45], v[228:229], v[24:25]
	v_pk_fma_f32 v[24:25], v[46:47], v[230:231], v[24:25]
	v_pk_fma_f32 v[24:25], v[48:49], v[232:233], v[24:25]
	v_pk_fma_f32 v[24:25], v[50:51], v[234:235], v[24:25]
	v_pk_fma_f32 v[24:25], v[52:53], v[236:237], v[24:25]
	v_pk_fma_f32 v[24:25], v[54:55], v[238:239], v[24:25]
	v_add_f32_e32 v56, v24, v25
	ds_write_b32 v5, v56 offset:1536
	s_waitcnt vmcnt(30)
	v_cvt_pk_f32_fp8_e32 v[40:41], v156
	v_cvt_pk_f32_fp8_sdwa v[42:43], v156 src0_sel:WORD_1
	v_cvt_pk_f32_fp8_e32 v[44:45], v157
	v_cvt_pk_f32_fp8_sdwa v[46:47], v157 src0_sel:WORD_1
	v_cvt_pk_f32_fp8_e32 v[48:49], v158
	v_cvt_pk_f32_fp8_sdwa v[50:51], v158 src0_sel:WORD_1
	v_cvt_pk_f32_fp8_e32 v[52:53], v159
	v_cvt_pk_f32_fp8_sdwa v[54:55], v159 src0_sel:WORD_1
	v_pk_mul_f32 v[24:25], v[40:41], v[224:225]
	v_pk_fma_f32 v[24:25], v[42:43], v[226:227], v[24:25]
	v_pk_fma_f32 v[24:25], v[44:45], v[228:229], v[24:25]
	v_pk_fma_f32 v[24:25], v[46:47], v[230:231], v[24:25]
	v_pk_fma_f32 v[24:25], v[48:49], v[232:233], v[24:25]
	v_pk_fma_f32 v[24:25], v[50:51], v[234:235], v[24:25]
	v_pk_fma_f32 v[24:25], v[52:53], v[236:237], v[24:25]
	v_pk_fma_f32 v[24:25], v[54:55], v[238:239], v[24:25]
	v_add_f32_e32 v56, v24, v25
	ds_write_b32 v5, v56 offset:1792
	s_waitcnt vmcnt(29)
	v_cvt_pk_f32_fp8_e32 v[40:41], v160
	v_cvt_pk_f32_fp8_sdwa v[42:43], v160 src0_sel:WORD_1
	v_cvt_pk_f32_fp8_e32 v[44:45], v161
	v_cvt_pk_f32_fp8_sdwa v[46:47], v161 src0_sel:WORD_1
	v_cvt_pk_f32_fp8_e32 v[48:49], v162
	v_cvt_pk_f32_fp8_sdwa v[50:51], v162 src0_sel:WORD_1
	v_cvt_pk_f32_fp8_e32 v[52:53], v163
	v_cvt_pk_f32_fp8_sdwa v[54:55], v163 src0_sel:WORD_1
	v_pk_mul_f32 v[24:25], v[40:41], v[224:225]
	v_pk_fma_f32 v[24:25], v[42:43], v[226:227], v[24:25]
	v_pk_fma_f32 v[24:25], v[44:45], v[228:229], v[24:25]
	v_pk_fma_f32 v[24:25], v[46:47], v[230:231], v[24:25]
	v_pk_fma_f32 v[24:25], v[48:49], v[232:233], v[24:25]
	v_pk_fma_f32 v[24:25], v[50:51], v[234:235], v[24:25]
	v_pk_fma_f32 v[24:25], v[52:53], v[236:237], v[24:25]
	v_pk_fma_f32 v[24:25], v[54:55], v[238:239], v[24:25]
	v_add_f32_e32 v56, v24, v25
	ds_write_b32 v5, v56 offset:2048
	s_waitcnt vmcnt(28)
	v_cvt_pk_f32_fp8_e32 v[40:41], v164
	v_cvt_pk_f32_fp8_sdwa v[42:43], v164 src0_sel:WORD_1
	v_cvt_pk_f32_fp8_e32 v[44:45], v165
	v_cvt_pk_f32_fp8_sdwa v[46:47], v165 src0_sel:WORD_1
	v_cvt_pk_f32_fp8_e32 v[48:49], v166
	v_cvt_pk_f32_fp8_sdwa v[50:51], v166 src0_sel:WORD_1
	v_cvt_pk_f32_fp8_e32 v[52:53], v167
	v_cvt_pk_f32_fp8_sdwa v[54:55], v167 src0_sel:WORD_1
	v_pk_mul_f32 v[24:25], v[40:41], v[224:225]
	v_pk_fma_f32 v[24:25], v[42:43], v[226:227], v[24:25]
	v_pk_fma_f32 v[24:25], v[44:45], v[228:229], v[24:25]
	v_pk_fma_f32 v[24:25], v[46:47], v[230:231], v[24:25]
	v_pk_fma_f32 v[24:25], v[48:49], v[232:233], v[24:25]
	v_pk_fma_f32 v[24:25], v[50:51], v[234:235], v[24:25]
	v_pk_fma_f32 v[24:25], v[52:53], v[236:237], v[24:25]
	v_pk_fma_f32 v[24:25], v[54:55], v[238:239], v[24:25]
	v_add_f32_e32 v56, v24, v25
	ds_write_b32 v5, v56 offset:2304
	s_waitcnt vmcnt(27)
	v_cvt_pk_f32_fp8_e32 v[40:41], v168
	v_cvt_pk_f32_fp8_sdwa v[42:43], v168 src0_sel:WORD_1
	v_cvt_pk_f32_fp8_e32 v[44:45], v169
	v_cvt_pk_f32_fp8_sdwa v[46:47], v169 src0_sel:WORD_1
	v_cvt_pk_f32_fp8_e32 v[48:49], v170
	v_cvt_pk_f32_fp8_sdwa v[50:51], v170 src0_sel:WORD_1
	v_cvt_pk_f32_fp8_e32 v[52:53], v171
	v_cvt_pk_f32_fp8_sdwa v[54:55], v171 src0_sel:WORD_1
	v_pk_mul_f32 v[24:25], v[40:41], v[224:225]
	v_pk_fma_f32 v[24:25], v[42:43], v[226:227], v[24:25]
	v_pk_fma_f32 v[24:25], v[44:45], v[228:229], v[24:25]
	v_pk_fma_f32 v[24:25], v[46:47], v[230:231], v[24:25]
	v_pk_fma_f32 v[24:25], v[48:49], v[232:233], v[24:25]
	v_pk_fma_f32 v[24:25], v[50:51], v[234:235], v[24:25]
	v_pk_fma_f32 v[24:25], v[52:53], v[236:237], v[24:25]
	v_pk_fma_f32 v[24:25], v[54:55], v[238:239], v[24:25]
	v_add_f32_e32 v56, v24, v25
	ds_write_b32 v5, v56 offset:2560
	s_waitcnt vmcnt(26)
	v_cvt_pk_f32_fp8_e32 v[40:41], v172
	v_cvt_pk_f32_fp8_sdwa v[42:43], v172 src0_sel:WORD_1
	v_cvt_pk_f32_fp8_e32 v[44:45], v173
	v_cvt_pk_f32_fp8_sdwa v[46:47], v173 src0_sel:WORD_1
	v_cvt_pk_f32_fp8_e32 v[48:49], v174
	v_cvt_pk_f32_fp8_sdwa v[50:51], v174 src0_sel:WORD_1
	v_cvt_pk_f32_fp8_e32 v[52:53], v175
	v_cvt_pk_f32_fp8_sdwa v[54:55], v175 src0_sel:WORD_1
	v_pk_mul_f32 v[24:25], v[40:41], v[224:225]
	v_pk_fma_f32 v[24:25], v[42:43], v[226:227], v[24:25]
	v_pk_fma_f32 v[24:25], v[44:45], v[228:229], v[24:25]
	v_pk_fma_f32 v[24:25], v[46:47], v[230:231], v[24:25]
	v_pk_fma_f32 v[24:25], v[48:49], v[232:233], v[24:25]
	v_pk_fma_f32 v[24:25], v[50:51], v[234:235], v[24:25]
	v_pk_fma_f32 v[24:25], v[52:53], v[236:237], v[24:25]
	v_pk_fma_f32 v[24:25], v[54:55], v[238:239], v[24:25]
	v_add_f32_e32 v56, v24, v25
	ds_write_b32 v5, v56 offset:2816
	s_waitcnt vmcnt(25)
	v_cvt_pk_f32_fp8_e32 v[40:41], v176
	v_cvt_pk_f32_fp8_sdwa v[42:43], v176 src0_sel:WORD_1
	v_cvt_pk_f32_fp8_e32 v[44:45], v177
	v_cvt_pk_f32_fp8_sdwa v[46:47], v177 src0_sel:WORD_1
	v_cvt_pk_f32_fp8_e32 v[48:49], v178
	v_cvt_pk_f32_fp8_sdwa v[50:51], v178 src0_sel:WORD_1
	v_cvt_pk_f32_fp8_e32 v[52:53], v179
	v_cvt_pk_f32_fp8_sdwa v[54:55], v179 src0_sel:WORD_1
	v_pk_mul_f32 v[24:25], v[40:41], v[224:225]
	v_pk_fma_f32 v[24:25], v[42:43], v[226:227], v[24:25]
	v_pk_fma_f32 v[24:25], v[44:45], v[228:229], v[24:25]
	v_pk_fma_f32 v[24:25], v[46:47], v[230:231], v[24:25]
	v_pk_fma_f32 v[24:25], v[48:49], v[232:233], v[24:25]
	v_pk_fma_f32 v[24:25], v[50:51], v[234:235], v[24:25]
	v_pk_fma_f32 v[24:25], v[52:53], v[236:237], v[24:25]
	v_pk_fma_f32 v[24:25], v[54:55], v[238:239], v[24:25]
	v_add_f32_e32 v56, v24, v25
	ds_write_b32 v5, v56 offset:3072
	s_waitcnt vmcnt(24)
	v_cvt_pk_f32_fp8_e32 v[40:41], v180
	v_cvt_pk_f32_fp8_sdwa v[42:43], v180 src0_sel:WORD_1
	v_cvt_pk_f32_fp8_e32 v[44:45], v181
	v_cvt_pk_f32_fp8_sdwa v[46:47], v181 src0_sel:WORD_1
	v_cvt_pk_f32_fp8_e32 v[48:49], v182
	v_cvt_pk_f32_fp8_sdwa v[50:51], v182 src0_sel:WORD_1
	v_cvt_pk_f32_fp8_e32 v[52:53], v183
	v_cvt_pk_f32_fp8_sdwa v[54:55], v183 src0_sel:WORD_1
	v_pk_mul_f32 v[24:25], v[40:41], v[224:225]
	v_pk_fma_f32 v[24:25], v[42:43], v[226:227], v[24:25]
	v_pk_fma_f32 v[24:25], v[44:45], v[228:229], v[24:25]
	v_pk_fma_f32 v[24:25], v[46:47], v[230:231], v[24:25]
	v_pk_fma_f32 v[24:25], v[48:49], v[232:233], v[24:25]
	v_pk_fma_f32 v[24:25], v[50:51], v[234:235], v[24:25]
	v_pk_fma_f32 v[24:25], v[52:53], v[236:237], v[24:25]
	v_pk_fma_f32 v[24:25], v[54:55], v[238:239], v[24:25]
	v_add_f32_e32 v56, v24, v25
	ds_write_b32 v5, v56 offset:3328
	s_waitcnt vmcnt(23)
	v_cvt_pk_f32_fp8_e32 v[40:41], v184
	v_cvt_pk_f32_fp8_sdwa v[42:43], v184 src0_sel:WORD_1
	v_cvt_pk_f32_fp8_e32 v[44:45], v185
	v_cvt_pk_f32_fp8_sdwa v[46:47], v185 src0_sel:WORD_1
	v_cvt_pk_f32_fp8_e32 v[48:49], v186
	v_cvt_pk_f32_fp8_sdwa v[50:51], v186 src0_sel:WORD_1
	v_cvt_pk_f32_fp8_e32 v[52:53], v187
	v_cvt_pk_f32_fp8_sdwa v[54:55], v187 src0_sel:WORD_1
	v_pk_mul_f32 v[24:25], v[40:41], v[224:225]
	v_pk_fma_f32 v[24:25], v[42:43], v[226:227], v[24:25]
	v_pk_fma_f32 v[24:25], v[44:45], v[228:229], v[24:25]
	v_pk_fma_f32 v[24:25], v[46:47], v[230:231], v[24:25]
	v_pk_fma_f32 v[24:25], v[48:49], v[232:233], v[24:25]
	v_pk_fma_f32 v[24:25], v[50:51], v[234:235], v[24:25]
	v_pk_fma_f32 v[24:25], v[52:53], v[236:237], v[24:25]
	v_pk_fma_f32 v[24:25], v[54:55], v[238:239], v[24:25]
	v_add_f32_e32 v56, v24, v25
	ds_write_b32 v5, v56 offset:3584
	s_waitcnt vmcnt(22)
	v_cvt_pk_f32_fp8_e32 v[40:41], v188
	v_cvt_pk_f32_fp8_sdwa v[42:43], v188 src0_sel:WORD_1
	v_cvt_pk_f32_fp8_e32 v[44:45], v189
	v_cvt_pk_f32_fp8_sdwa v[46:47], v189 src0_sel:WORD_1
	v_cvt_pk_f32_fp8_e32 v[48:49], v190
	v_cvt_pk_f32_fp8_sdwa v[50:51], v190 src0_sel:WORD_1
	v_cvt_pk_f32_fp8_e32 v[52:53], v191
	v_cvt_pk_f32_fp8_sdwa v[54:55], v191 src0_sel:WORD_1
	v_pk_mul_f32 v[24:25], v[40:41], v[224:225]
	v_pk_fma_f32 v[24:25], v[42:43], v[226:227], v[24:25]
	v_pk_fma_f32 v[24:25], v[44:45], v[228:229], v[24:25]
	v_pk_fma_f32 v[24:25], v[46:47], v[230:231], v[24:25]
	v_pk_fma_f32 v[24:25], v[48:49], v[232:233], v[24:25]
	v_pk_fma_f32 v[24:25], v[50:51], v[234:235], v[24:25]
	v_pk_fma_f32 v[24:25], v[52:53], v[236:237], v[24:25]
	v_pk_fma_f32 v[24:25], v[54:55], v[238:239], v[24:25]
	v_add_f32_e32 v56, v24, v25
	ds_write_b32 v5, v56 offset:3840
	ds_read_b128 v[40:43], v6
	ds_read_b128 v[44:47], v6 offset:16
	ds_read_b128 v[48:51], v6 offset:2048
	ds_read_b128 v[52:55], v6 offset:2064
	s_waitcnt lgkmcnt(2)
	v_add_f32_e32 v40, v40, v41
	v_add_f32_e32 v40, v40, v42
	v_add_f32_e32 v40, v40, v43
	v_add_f32_e32 v40, v40, v44
	v_add_f32_e32 v40, v40, v45
	v_add_f32_e32 v40, v40, v46
	v_add_f32_e32 v40, v40, v47
	s_waitcnt lgkmcnt(0)
	v_add_f32_e32 v48, v48, v49
	v_add_f32_e32 v48, v48, v50
	v_add_f32_e32 v48, v48, v51
	v_add_f32_e32 v48, v48, v52
	v_add_f32_e32 v48, v48, v53
	v_add_f32_e32 v48, v48, v54
	v_add_f32_e32 v48, v48, v55
	s_lshl_b32 s30, s22, 12
	s_add_u32 s66, s20, s30
	s_addc_u32 s67, s21, 0
	global_store_dword v1, v40, s[66:67]
	global_store_dword v1, v48, s[66:67] offset:256
	s_add_u32 s22, s22, s12
	s_cmp_ge_u32 s22, 0x8000
	s_cbranch_scc0 .Lgu_loop

.Lga_entry:
	s_mov_b64 s[82:83], exec
	v_readlane_b32 s4, v254, 40
	v_readlane_b32 s5, v254, 41
	v_readlane_b32 s6, v255, 15
	v_readlane_b32 s7, v254, 21
	s_nop 4
	s_load_dword s8, s[4:5], 0x0
	v_mbcnt_lo_u32_b32 v0, -1, 0
	v_mbcnt_hi_u32_b32 v0, -1, v0
	v_lshlrev_b32_e32 v1, 2, v0
	s_lshl_b32 s6, s6, 2
	s_lshr_b32 s7, s7, 6
	s_add_u32 s6, s6, s7
	s_lshl_b32 s22, s6, 2
	s_waitcnt lgkmcnt(0)
	s_lshl_b32 s26, s8, 4
	s_add_u32 s10, s92, 0x32100000
	s_addc_u32 s11, s93, 0
	s_add_u32 s12, s92, 0x14100000
	s_addc_u32 s13, s93, 0
	s_add_u32 s14, s92, 0x15100000
	s_addc_u32 s15, s93, 0
	s_add_u32 s16, s92, 0x4040000
	s_addc_u32 s17, s93, 0
	s_add_u32 s18, s92, 0x4080000
	s_addc_u32 s19, s93, 0
	s_add_u32 s20, s92, 0x16100000
	s_addc_u32 s21, s93, 0
	s_cmp_ge_u32 s22, 0x8000
	s_cbranch_scc1 .Lga_done
.Lga_loop:
	s_add_u32 s30, s22, 0
	s_lshl_b32 s31, s30, 12
	s_add_u32 s40, s10, s31
	s_addc_u32 s41, s11, 0
	global_load_dword v64, v1, s[40:41]
	global_load_dword v65, v1, s[40:41] offset:512
	global_load_dword v66, v1, s[40:41] offset:1024
	global_load_dword v67, v1, s[40:41] offset:1536
	global_load_dword v68, v1, s[40:41] offset:2048
	global_load_dword v69, v1, s[40:41] offset:2560
	global_load_dword v70, v1, s[40:41] offset:3072
	global_load_dword v71, v1, s[40:41] offset:3584
	global_load_dword v72, v1, s[40:41] offset:256
	global_load_dword v73, v1, s[40:41] offset:768
	global_load_dword v74, v1, s[40:41] offset:1280
	global_load_dword v75, v1, s[40:41] offset:1792
	global_load_dword v76, v1, s[40:41] offset:2304
	global_load_dword v77, v1, s[40:41] offset:2816
	global_load_dword v78, v1, s[40:41] offset:3328
	global_load_dword v79, v1, s[40:41] offset:3840
	s_lshl_b32 s31, s30, 9
	s_add_u32 s64, s12, s31
	s_addc_u32 s65, s13, 0
	global_load_dword v8, v1, s[64:65]
	global_load_dword v9, v1, s[64:65] offset:256
	s_add_u32 s66, s14, s31
	s_addc_u32 s67, s15, 0
	global_load_dword v16, v1, s[66:67]
	global_load_dword v17, v1, s[66:67] offset:256
	s_add_u32 s30, s22, 1
	s_lshl_b32 s31, s30, 12
	s_add_u32 s40, s10, s31
	s_addc_u32 s41, s11, 0
	global_load_dword v80, v1, s[40:41]
	global_load_dword v81, v1, s[40:41] offset:512
	global_load_dword v82, v1, s[40:41] offset:1024
	global_load_dword v83, v1, s[40:41] offset:1536
	global_load_dword v84, v1, s[40:41] offset:2048
	global_load_dword v85, v1, s[40:41] offset:2560
	global_load_dword v86, v1, s[40:41] offset:3072
	global_load_dword v87, v1, s[40:41] offset:3584
	global_load_dword v88, v1, s[40:41] offset:256
	global_load_dword v89, v1, s[40:41] offset:768
	global_load_dword v90, v1, s[40:41] offset:1280
	global_load_dword v91, v1, s[40:41] offset:1792
	global_load_dword v92, v1, s[40:41] offset:2304
	global_load_dword v93, v1, s[40:41] offset:2816
	global_load_dword v94, v1, s[40:41] offset:3328
	global_load_dword v95, v1, s[40:41] offset:3840
	s_lshl_b32 s31, s30, 9
	s_add_u32 s64, s12, s31
	s_addc_u32 s65, s13, 0
	global_load_dword v10, v1, s[64:65]
	global_load_dword v11, v1, s[64:65] offset:256
	s_add_u32 s66, s14, s31
	s_addc_u32 s67, s15, 0
	global_load_dword v18, v1, s[66:67]
	global_load_dword v19, v1, s[66:67] offset:256
	s_add_u32 s30, s22, 2
	s_lshl_b32 s31, s30, 12
	s_add_u32 s40, s10, s31
	s_addc_u32 s41, s11, 0
	global_load_dword v96, v1, s[40:41]
	global_load_dword v97, v1, s[40:41] offset:512
	global_load_dword v98, v1, s[40:41] offset:1024
	global_load_dword v99, v1, s[40:41] offset:1536
	global_load_dword v100, v1, s[40:41] offset:2048
	global_load_dword v101, v1, s[40:41] offset:2560
	global_load_dword v102, v1, s[40:41] offset:3072
	global_load_dword v103, v1, s[40:41] offset:3584
	global_load_dword v104, v1, s[40:41] offset:256
	global_load_dword v105, v1, s[40:41] offset:768
	global_load_dword v106, v1, s[40:41] offset:1280
	global_load_dword v107, v1, s[40:41] offset:1792
	global_load_dword v108, v1, s[40:41] offset:2304
	global_load_dword v109, v1, s[40:41] offset:2816
	global_load_dword v110, v1, s[40:41] offset:3328
	global_load_dword v111, v1, s[40:41] offset:3840
	s_lshl_b32 s31, s30, 9
	s_add_u32 s64, s12, s31
	s_addc_u32 s65, s13, 0
	global_load_dword v12, v1, s[64:65]
	global_load_dword v13, v1, s[64:65] offset:256
	s_add_u32 s66, s14, s31
	s_addc_u32 s67, s15, 0
	global_load_dword v20, v1, s[66:67]
	global_load_dword v21, v1, s[66:67] offset:256
	s_add_u32 s30, s22, 3
	s_lshl_b32 s31, s30, 12
	s_add_u32 s40, s10, s31
	s_addc_u32 s41, s11, 0
	global_load_dword v112, v1, s[40:41]
	global_load_dword v113, v1, s[40:41] offset:512
	global_load_dword v114, v1, s[40:41] offset:1024
	global_load_dword v115, v1, s[40:41] offset:1536
	global_load_dword v116, v1, s[40:41] offset:2048
	global_load_dword v117, v1, s[40:41] offset:2560
	global_load_dword v118, v1, s[40:41] offset:3072
	global_load_dword v119, v1, s[40:41] offset:3584
	global_load_dword v120, v1, s[40:41] offset:256
	global_load_dword v121, v1, s[40:41] offset:768
	global_load_dword v122, v1, s[40:41] offset:1280
	global_load_dword v123, v1, s[40:41] offset:1792
	global_load_dword v124, v1, s[40:41] offset:2304
	global_load_dword v125, v1, s[40:41] offset:2816
	global_load_dword v126, v1, s[40:41] offset:3328
	global_load_dword v127, v1, s[40:41] offset:3840
	s_lshl_b32 s31, s30, 9
	s_add_u32 s64, s12, s31
	s_addc_u32 s65, s13, 0
	global_load_dword v14, v1, s[64:65]
	global_load_dword v15, v1, s[64:65] offset:256
	s_add_u32 s66, s14, s31
	s_addc_u32 s67, s15, 0
	global_load_dword v22, v1, s[66:67]
	global_load_dword v23, v1, s[66:67] offset:256
	s_waitcnt vmcnt(62)
	v_lshlrev_b32_e32 v8, 2, v8
	v_lshlrev_b32_e32 v9, 2, v9
	global_load_dword v24, v8, s[16:17]
	global_load_dword v32, v8, s[18:19]
	global_load_dword v25, v9, s[16:17]
	global_load_dword v33, v9, s[18:19]
	s_waitcnt vmcnt(46)
	v_lshlrev_b32_e32 v10, 2, v10
	v_lshlrev_b32_e32 v11, 2, v11
	global_load_dword v26, v10, s[16:17]
	global_load_dword v34, v10, s[18:19]
	global_load_dword v27, v11, s[16:17]
	global_load_dword v35, v11, s[18:19]
	s_waitcnt vmcnt(30)
	v_lshlrev_b32_e32 v12, 2, v12
	v_lshlrev_b32_e32 v13, 2, v13
	global_load_dword v28, v12, s[16:17]
	global_load_dword v36, v12, s[18:19]
	global_load_dword v29, v13, s[16:17]
	global_load_dword v37, v13, s[18:19]
	s_waitcnt vmcnt(14)
	v_lshlrev_b32_e32 v14, 2, v14
	v_lshlrev_b32_e32 v15, 2, v15
	global_load_dword v30, v14, s[16:17]
	global_load_dword v38, v14, s[18:19]
	global_load_dword v31, v15, s[16:17]
	global_load_dword v39, v15, s[18:19]
	s_waitcnt vmcnt(0)
	v_add_f32_e32 v64, v64, v65
	v_add_f32_e32 v64, v64, v66
	v_add_f32_e32 v64, v64, v67
	v_add_f32_e32 v64, v64, v68
	v_add_f32_e32 v64, v64, v69
	v_add_f32_e32 v64, v64, v70
	v_add_f32_e32 v64, v64, v71
	v_mul_f32_e32 v64, v24, v64
	v_mul_f32_e32 v40, 0x3d372713, v64
	v_mul_f32_e32 v40, v64, v40
	v_fma_f32 v40, v64, v40, v64
	v_mul_f32_e32 v40, 0x3f4c422a, v40
	v_add_f32_e32 v40, v40, v40
	v_mul_f32_e32 v40, 0x3fb8aa3b, v40
	v_exp_f32_e32 v40, v40
	v_mul_f32_e32 v42, 0.5, v64
	v_add_f32_e32 v40, 1.0, v40
	v_rcp_f32_e32 v40, v40
	s_nop 0
	v_fma_f32 v40, v40, -2.0, 1.0
	v_add_f32_e32 v40, 1.0, v40
	v_mul_f32_e32 v42, v42, v40
	v_mul_f32_e32 v42, v16, v42
	v_mul_f32_e32 v42, v32, v42
	v_add_f32_e32 v72, v72, v73
	v_add_f32_e32 v72, v72, v74
	v_add_f32_e32 v72, v72, v75
	v_add_f32_e32 v72, v72, v76
	v_add_f32_e32 v72, v72, v77
	v_add_f32_e32 v72, v72, v78
	v_add_f32_e32 v72, v72, v79
	v_mul_f32_e32 v72, v25, v72
	v_mul_f32_e32 v41, 0x3d372713, v72
	v_mul_f32_e32 v41, v72, v41
	v_fma_f32 v41, v72, v41, v72
	v_mul_f32_e32 v41, 0x3f4c422a, v41
	v_add_f32_e32 v41, v41, v41
	v_mul_f32_e32 v41, 0x3fb8aa3b, v41
	v_exp_f32_e32 v41, v41
	v_mul_f32_e32 v43, 0.5, v72
	v_add_f32_e32 v41, 1.0, v41
	v_rcp_f32_e32 v41, v41
	s_nop 0
	v_fma_f32 v41, v41, -2.0, 1.0
	v_add_f32_e32 v41, 1.0, v41
	v_mul_f32_e32 v43, v43, v41
	v_mul_f32_e32 v43, v17, v43
	v_mul_f32_e32 v43, v33, v43
	s_add_u32 s30, s22, 0
	s_lshl_b32 s31, s30, 9
	s_add_u32 s40, s20, s31
	s_addc_u32 s41, s21, 0
	global_store_dword v1, v42, s[40:41]
	global_store_dword v1, v43, s[40:41] offset:256
	v_add_f32_e32 v80, v80, v81
	v_add_f32_e32 v80, v80, v82
	v_add_f32_e32 v80, v80, v83
	v_add_f32_e32 v80, v80, v84
	v_add_f32_e32 v80, v80, v85
	v_add_f32_e32 v80, v80, v86
	v_add_f32_e32 v80, v80, v87
	v_mul_f32_e32 v80, v26, v80
	v_mul_f32_e32 v40, 0x3d372713, v80
	v_mul_f32_e32 v40, v80, v40
	v_fma_f32 v40, v80, v40, v80
	v_mul_f32_e32 v40, 0x3f4c422a, v40
	v_add_f32_e32 v40, v40, v40
	v_mul_f32_e32 v40, 0x3fb8aa3b, v40
	v_exp_f32_e32 v40, v40
	v_mul_f32_e32 v42, 0.5, v80
	v_add_f32_e32 v40, 1.0, v40
	v_rcp_f32_e32 v40, v40
	s_nop 0
	v_fma_f32 v40, v40, -2.0, 1.0
	v_add_f32_e32 v40, 1.0, v40
	v_mul_f32_e32 v42, v42, v40
	v_mul_f32_e32 v42, v18, v42
	v_mul_f32_e32 v42, v34, v42
	v_add_f32_e32 v88, v88, v89
	v_add_f32_e32 v88, v88, v90
	v_add_f32_e32 v88, v88, v91
	v_add_f32_e32 v88, v88, v92
	v_add_f32_e32 v88, v88, v93
	v_add_f32_e32 v88, v88, v94
	v_add_f32_e32 v88, v88, v95
	v_mul_f32_e32 v88, v27, v88
	v_mul_f32_e32 v41, 0x3d372713, v88
	v_mul_f32_e32 v41, v88, v41
	v_fma_f32 v41, v88, v41, v88
	v_mul_f32_e32 v41, 0x3f4c422a, v41
	v_add_f32_e32 v41, v41, v41
	v_mul_f32_e32 v41, 0x3fb8aa3b, v41
	v_exp_f32_e32 v41, v41
	v_mul_f32_e32 v43, 0.5, v88
	v_add_f32_e32 v41, 1.0, v41
	v_rcp_f32_e32 v41, v41
	s_nop 0
	v_fma_f32 v41, v41, -2.0, 1.0
	v_add_f32_e32 v41, 1.0, v41
	v_mul_f32_e32 v43, v43, v41
	v_mul_f32_e32 v43, v19, v43
	v_mul_f32_e32 v43, v35, v43
	s_add_u32 s30, s22, 1
	s_lshl_b32 s31, s30, 9
	s_add_u32 s40, s20, s31
	s_addc_u32 s41, s21, 0
	global_store_dword v1, v42, s[40:41]
	global_store_dword v1, v43, s[40:41] offset:256
	v_add_f32_e32 v96, v96, v97
	v_add_f32_e32 v96, v96, v98
	v_add_f32_e32 v96, v96, v99
	v_add_f32_e32 v96, v96, v100
	v_add_f32_e32 v96, v96, v101
	v_add_f32_e32 v96, v96, v102
	v_add_f32_e32 v96, v96, v103
	v_mul_f32_e32 v96, v28, v96
	v_mul_f32_e32 v40, 0x3d372713, v96
	v_mul_f32_e32 v40, v96, v40
	v_fma_f32 v40, v96, v40, v96
	v_mul_f32_e32 v40, 0x3f4c422a, v40
	v_add_f32_e32 v40, v40, v40
	v_mul_f32_e32 v40, 0x3fb8aa3b, v40
	v_exp_f32_e32 v40, v40
	v_mul_f32_e32 v42, 0.5, v96
	v_add_f32_e32 v40, 1.0, v40
	v_rcp_f32_e32 v40, v40
	s_nop 0
	v_fma_f32 v40, v40, -2.0, 1.0
	v_add_f32_e32 v40, 1.0, v40
	v_mul_f32_e32 v42, v42, v40
	v_mul_f32_e32 v42, v20, v42
	v_mul_f32_e32 v42, v36, v42
	v_add_f32_e32 v104, v104, v105
	v_add_f32_e32 v104, v104, v106
	v_add_f32_e32 v104, v104, v107
	v_add_f32_e32 v104, v104, v108
	v_add_f32_e32 v104, v104, v109
	v_add_f32_e32 v104, v104, v110
	v_add_f32_e32 v104, v104, v111
	v_mul_f32_e32 v104, v29, v104
	v_mul_f32_e32 v41, 0x3d372713, v104
	v_mul_f32_e32 v41, v104, v41
	v_fma_f32 v41, v104, v41, v104
	v_mul_f32_e32 v41, 0x3f4c422a, v41
	v_add_f32_e32 v41, v41, v41
	v_mul_f32_e32 v41, 0x3fb8aa3b, v41
	v_exp_f32_e32 v41, v41
	v_mul_f32_e32 v43, 0.5, v104
	v_add_f32_e32 v41, 1.0, v41
	v_rcp_f32_e32 v41, v41
	s_nop 0
	v_fma_f32 v41, v41, -2.0, 1.0
	v_add_f32_e32 v41, 1.0, v41
	v_mul_f32_e32 v43, v43, v41
	v_mul_f32_e32 v43, v21, v43
	v_mul_f32_e32 v43, v37, v43
	s_add_u32 s30, s22, 2
	s_lshl_b32 s31, s30, 9
	s_add_u32 s40, s20, s31
	s_addc_u32 s41, s21, 0
	global_store_dword v1, v42, s[40:41]
	global_store_dword v1, v43, s[40:41] offset:256
	v_add_f32_e32 v112, v112, v113
	v_add_f32_e32 v112, v112, v114
	v_add_f32_e32 v112, v112, v115
	v_add_f32_e32 v112, v112, v116
	v_add_f32_e32 v112, v112, v117
	v_add_f32_e32 v112, v112, v118
	v_add_f32_e32 v112, v112, v119
	v_mul_f32_e32 v112, v30, v112
	v_mul_f32_e32 v40, 0x3d372713, v112
	v_mul_f32_e32 v40, v112, v40
	v_fma_f32 v40, v112, v40, v112
	v_mul_f32_e32 v40, 0x3f4c422a, v40
	v_add_f32_e32 v40, v40, v40
	v_mul_f32_e32 v40, 0x3fb8aa3b, v40
	v_exp_f32_e32 v40, v40
	v_mul_f32_e32 v42, 0.5, v112
	v_add_f32_e32 v40, 1.0, v40
	v_rcp_f32_e32 v40, v40
	s_nop 0
	v_fma_f32 v40, v40, -2.0, 1.0
	v_add_f32_e32 v40, 1.0, v40
	v_mul_f32_e32 v42, v42, v40
	v_mul_f32_e32 v42, v22, v42
	v_mul_f32_e32 v42, v38, v42
	v_add_f32_e32 v120, v120, v121
	v_add_f32_e32 v120, v120, v122
	v_add_f32_e32 v120, v120, v123
	v_add_f32_e32 v120, v120, v124
	v_add_f32_e32 v120, v120, v125
	v_add_f32_e32 v120, v120, v126
	v_add_f32_e32 v120, v120, v127
	v_mul_f32_e32 v120, v31, v120
	v_mul_f32_e32 v41, 0x3d372713, v120
	v_mul_f32_e32 v41, v120, v41
	v_fma_f32 v41, v120, v41, v120
	v_mul_f32_e32 v41, 0x3f4c422a, v41
	v_add_f32_e32 v41, v41, v41
	v_mul_f32_e32 v41, 0x3fb8aa3b, v41
	v_exp_f32_e32 v41, v41
	v_mul_f32_e32 v43, 0.5, v120
	v_add_f32_e32 v41, 1.0, v41
	v_rcp_f32_e32 v41, v41
	s_nop 0
	v_fma_f32 v41, v41, -2.0, 1.0
	v_add_f32_e32 v41, 1.0, v41
	v_mul_f32_e32 v43, v43, v41
	v_mul_f32_e32 v43, v23, v43
	v_mul_f32_e32 v43, v39, v43
	s_add_u32 s30, s22, 3
	s_lshl_b32 s31, s30, 9
	s_add_u32 s40, s20, s31
	s_addc_u32 s41, s21, 0
	global_store_dword v1, v42, s[40:41]
	global_store_dword v1, v43, s[40:41] offset:256
	s_add_u32 s22, s22, s26
	s_cmp_lt_u32 s22, 0x8000
	s_cbranch_scc1 .Lga_loop

.Lgv_entry:
	s_mov_b64 s[82:83], exec
	v_readlane_b32 s4, v254, 40
	v_readlane_b32 s5, v254, 41
	v_readlane_b32 s6, v255, 15
	v_readlane_b32 s7, v254, 21
	s_nop 4
	s_load_dword s8, s[4:5], 0x0
	v_mbcnt_lo_u32_b32 v0, -1, 0
	v_mbcnt_hi_u32_b32 v0, -1, v0
	v_lshlrev_b32_e32 v1, 2, v0
	v_lshlrev_b32_e32 v2, 3, v0
	v_and_b32_e32 v3, 7, v0
	v_lshlrev_b32_e32 v3, 4, v3
	v_lshrrev_b32_e32 v4, 3, v0
	s_lshl_b32 s9, s7, 6
	v_lshlrev_b32_e32 v5, 9, v4
	v_lshl_add_u32 v5, v3, 2, v5
	v_add_u32_e32 v5, s9, v5
	v_add_u32_e32 v6, s9, v2
	v_lshlrev_b32_e32 v4, 2, v4
	s_and_b32 s10, s6, 7
	s_lshr_b32 s11, s6, 3
	s_lshr_b32 s12, s7, 6
	s_lshl_b32 s11, s11, 2
	s_add_u32 s11, s11, s12
	s_waitcnt lgkmcnt(0)
	s_lshr_b32 s12, s8, 3
	s_lshl_b32 s12, s12, 2
	s_lshl_b32 s13, s10, 21
	s_add_u32 s14, s92, 0x6100000
	s_addc_u32 s15, s93, 0
	s_add_u32 s14, s14, s13
	s_addc_u32 s15, s15, 0
	s_lshl_b32 s13, s10, 9
	s_add_u32 s16, s92, 0x2a100000
	s_addc_u32 s17, s93, 0
	s_add_u32 s16, s16, s13
	s_addc_u32 s17, s17, 0
	s_add_u32 s18, s92, 0x14100000
	s_addc_u32 s19, s93, 0
	s_add_u32 s20, s92, 0x16100000
	s_addc_u32 s21, s93, 0
	s_cmp_ge_u32 s11, s12
	s_cbranch_scc1 .Lgv_done
	s_cmp_ge_u32 s11, 0x8000
	s_cbranch_scc1 .Lgv_done
	s_mov_b32 s22, s11
	s_lshl_b32 s30, s22, 9
	s_add_u32 s40, s18, s30
	s_addc_u32 s41, s19, 0
	global_load_dword v10, v1, s[40:41]
	global_load_dword v11, v1, s[40:41] offset:256
	s_add_u32 s64, s20, s30
	s_addc_u32 s65, s21, 0
	global_load_dword v16, v1, s[64:65]
	global_load_dword v17, v1, s[64:65] offset:256
	s_lshl_b32 s30, s22, 12
	s_add_u32 s66, s16, s30
	s_addc_u32 s67, s17, 0
	global_load_dwordx2 v[22:23], v2, s[66:67]
	s_mov_b32 s31, s12
	s_add_u32 s26, s22, s31
	s_min_u32 s26, s26, 0x7fff
	s_waitcnt vmcnt(0)
	v_mov_b32_e32 v8, v10
	v_mov_b32_e32 v9, v11
	v_mov_b32_e32 v14, v16
	v_mov_b32_e32 v15, v17
	v_mov_b32_e32 v20, v22
	v_mov_b32_e32 v21, v23
	v_mov_b32_e32 v12, v14
	v_mov_b32_e32 v13, v15
	v_mov_b32_e32 v18, v20
	v_mov_b32_e32 v19, v21
	s_lshl_b32 s30, s26, 9
	s_add_u32 s40, s18, s30
	s_addc_u32 s41, s19, 0
	global_load_dword v10, v1, s[40:41]
	global_load_dword v11, v1, s[40:41] offset:256
	s_add_u32 s64, s20, s30
	s_addc_u32 s65, s21, 0
	global_load_dword v16, v1, s[64:65]
	global_load_dword v17, v1, s[64:65] offset:256
	s_lshl_b32 s30, s26, 12
	s_add_u32 s66, s16, s30
	s_addc_u32 s67, s17, 0
	global_load_dwordx2 v[22:23], v2, s[66:67]
	ds_bpermute_b32 v192, v4, v8
	ds_bpermute_b32 v193, v4, v8 offset:32
	ds_bpermute_b32 v194, v4, v8 offset:64
	ds_bpermute_b32 v195, v4, v8 offset:96
	ds_bpermute_b32 v196, v4, v8 offset:128
	ds_bpermute_b32 v197, v4, v8 offset:160
	ds_bpermute_b32 v198, v4, v8 offset:192
	ds_bpermute_b32 v199, v4, v8 offset:224
	ds_bpermute_b32 v200, v4, v9
	ds_bpermute_b32 v201, v4, v9 offset:32
	ds_bpermute_b32 v202, v4, v9 offset:64
	ds_bpermute_b32 v203, v4, v9 offset:96
	ds_bpermute_b32 v204, v4, v9 offset:128
	ds_bpermute_b32 v205, v4, v9 offset:160
	ds_bpermute_b32 v206, v4, v9 offset:192
	ds_bpermute_b32 v207, v4, v9 offset:224
	s_waitcnt lgkmcnt(15)
	v_lshl_add_u32 v192, v192, 7, v3
	global_load_dwordx4 v[64:67], v192, s[14:15]
	s_waitcnt lgkmcnt(14)
	v_lshl_add_u32 v193, v193, 7, v3
	global_load_dwordx4 v[68:71], v193, s[14:15]
	s_waitcnt lgkmcnt(13)
	v_lshl_add_u32 v194, v194, 7, v3
	global_load_dwordx4 v[72:75], v194, s[14:15]
	s_waitcnt lgkmcnt(12)
	v_lshl_add_u32 v195, v195, 7, v3
	global_load_dwordx4 v[76:79], v195, s[14:15]
	s_waitcnt lgkmcnt(11)
	v_lshl_add_u32 v196, v196, 7, v3
	global_load_dwordx4 v[80:83], v196, s[14:15]
	s_waitcnt lgkmcnt(10)
	v_lshl_add_u32 v197, v197, 7, v3
	global_load_dwordx4 v[84:87], v197, s[14:15]
	s_waitcnt lgkmcnt(9)
	v_lshl_add_u32 v198, v198, 7, v3
	global_load_dwordx4 v[88:91], v198, s[14:15]
	s_waitcnt lgkmcnt(8)
	v_lshl_add_u32 v199, v199, 7, v3
	global_load_dwordx4 v[92:95], v199, s[14:15]
	s_waitcnt lgkmcnt(7)
	v_lshl_add_u32 v200, v200, 7, v3
	global_load_dwordx4 v[96:99], v200, s[14:15]
	s_waitcnt lgkmcnt(6)
	v_lshl_add_u32 v201, v201, 7, v3
	global_load_dwordx4 v[100:103], v201, s[14:15]
	s_waitcnt lgkmcnt(5)
	v_lshl_add_u32 v202, v202, 7, v3
	global_load_dwordx4 v[104:107], v202, s[14:15]
	s_waitcnt lgkmcnt(4)
	v_lshl_add_u32 v203, v203, 7, v3
	global_load_dwordx4 v[108:111], v203, s[14:15]
	s_waitcnt lgkmcnt(3)
	v_lshl_add_u32 v204, v204, 7, v3
	global_load_dwordx4 v[112:115], v204, s[14:15]
	s_waitcnt lgkmcnt(2)
	v_lshl_add_u32 v205, v205, 7, v3
	global_load_dwordx4 v[116:119], v205, s[14:15]
	s_waitcnt lgkmcnt(1)
	v_lshl_add_u32 v206, v206, 7, v3
	global_load_dwordx4 v[120:123], v206, s[14:15]
	s_waitcnt lgkmcnt(0)
	v_lshl_add_u32 v207, v207, 7, v3
	global_load_dwordx4 v[124:127], v207, s[14:15]
	s_mov_b32 s42, s26
.Lgv_loop:
	s_waitcnt vmcnt(16)
	v_mov_b32_e32 v8, v10
	v_mov_b32_e32 v9, v11
	v_mov_b32_e32 v14, v16
	v_mov_b32_e32 v15, v17
	v_mov_b32_e32 v20, v22
	v_mov_b32_e32 v21, v23
	s_mov_b32 s31, s12
	s_add_u32 s26, s22, s31
	s_min_u32 s26, s26, 0x7fff
	s_mov_b32 s42, s26
	s_mul_i32 s31, s12, 2
	s_add_u32 s26, s22, s31
	s_min_u32 s26, s26, 0x7fff
	s_lshl_b32 s30, s26, 9
	s_add_u32 s40, s18, s30
	s_addc_u32 s41, s19, 0
	global_load_dword v10, v1, s[40:41]
	global_load_dword v11, v1, s[40:41] offset:256
	s_add_u32 s64, s20, s30
	s_addc_u32 s65, s21, 0
	global_load_dword v16, v1, s[64:65]
	global_load_dword v17, v1, s[64:65] offset:256
	s_lshl_b32 s30, s26, 12
	s_add_u32 s66, s16, s30
	s_addc_u32 s67, s17, 0
	global_load_dwordx2 v[22:23], v2, s[66:67]
	ds_bpermute_b32 v192, v4, v8
	ds_bpermute_b32 v193, v4, v8 offset:32
	ds_bpermute_b32 v194, v4, v8 offset:64
	ds_bpermute_b32 v195, v4, v8 offset:96
	ds_bpermute_b32 v196, v4, v8 offset:128
	ds_bpermute_b32 v197, v4, v8 offset:160
	ds_bpermute_b32 v198, v4, v8 offset:192
	ds_bpermute_b32 v199, v4, v8 offset:224
	ds_bpermute_b32 v200, v4, v9
	ds_bpermute_b32 v201, v4, v9 offset:32
	ds_bpermute_b32 v202, v4, v9 offset:64
	ds_bpermute_b32 v203, v4, v9 offset:96
	ds_bpermute_b32 v204, v4, v9 offset:128
	ds_bpermute_b32 v205, v4, v9 offset:160
	ds_bpermute_b32 v206, v4, v9 offset:192
	ds_bpermute_b32 v207, v4, v9 offset:224
	s_waitcnt lgkmcnt(15)
	v_lshl_add_u32 v192, v192, 7, v3
	global_load_dwordx4 v[128:131], v192, s[14:15]
	s_waitcnt lgkmcnt(14)
	v_lshl_add_u32 v193, v193, 7, v3
	global_load_dwordx4 v[132:135], v193, s[14:15]
	s_waitcnt lgkmcnt(13)
	v_lshl_add_u32 v194, v194, 7, v3
	global_load_dwordx4 v[136:139], v194, s[14:15]
	s_waitcnt lgkmcnt(12)
	v_lshl_add_u32 v195, v195, 7, v3
	global_load_dwordx4 v[140:143], v195, s[14:15]
	s_waitcnt lgkmcnt(11)
	v_lshl_add_u32 v196, v196, 7, v3
	global_load_dwordx4 v[144:147], v196, s[14:15]
	s_waitcnt lgkmcnt(10)
	v_lshl_add_u32 v197, v197, 7, v3
	global_load_dwordx4 v[148:151], v197, s[14:15]
	s_waitcnt lgkmcnt(9)
	v_lshl_add_u32 v198, v198, 7, v3
	global_load_dwordx4 v[152:155], v198, s[14:15]
	s_waitcnt lgkmcnt(8)
	v_lshl_add_u32 v199, v199, 7, v3
	global_load_dwordx4 v[156:159], v199, s[14:15]
	s_waitcnt lgkmcnt(7)
	v_lshl_add_u32 v200, v200, 7, v3
	global_load_dwordx4 v[160:163], v200, s[14:15]
	s_waitcnt lgkmcnt(6)
	v_lshl_add_u32 v201, v201, 7, v3
	global_load_dwordx4 v[164:167], v201, s[14:15]
	s_waitcnt lgkmcnt(5)
	v_lshl_add_u32 v202, v202, 7, v3
	global_load_dwordx4 v[168:171], v202, s[14:15]
	s_waitcnt lgkmcnt(4)
	v_lshl_add_u32 v203, v203, 7, v3
	global_load_dwordx4 v[172:175], v203, s[14:15]
	s_waitcnt lgkmcnt(3)
	v_lshl_add_u32 v204, v204, 7, v3
	global_load_dwordx4 v[176:179], v204, s[14:15]
	s_waitcnt lgkmcnt(2)
	v_lshl_add_u32 v205, v205, 7, v3
	global_load_dwordx4 v[180:183], v205, s[14:15]
	s_waitcnt lgkmcnt(1)
	v_lshl_add_u32 v206, v206, 7, v3
	global_load_dwordx4 v[184:187], v206, s[14:15]
	s_waitcnt lgkmcnt(0)
	v_lshl_add_u32 v207, v207, 7, v3
	global_load_dwordx4 v[188:191], v207, s[14:15]
	ds_bpermute_b32 v208, v4, v12
	ds_bpermute_b32 v210, v4, v12 offset:32
	ds_bpermute_b32 v212, v4, v12 offset:64
	ds_bpermute_b32 v214, v4, v12 offset:96
	ds_bpermute_b32 v216, v4, v12 offset:128
	ds_bpermute_b32 v218, v4, v12 offset:160
	ds_bpermute_b32 v220, v4, v12 offset:192
	ds_bpermute_b32 v222, v4, v12 offset:224
	ds_bpermute_b32 v224, v4, v13
	ds_bpermute_b32 v226, v4, v13 offset:32
	ds_bpermute_b32 v228, v4, v13 offset:64
	ds_bpermute_b32 v230, v4, v13 offset:96
	ds_bpermute_b32 v232, v4, v13 offset:128
	ds_bpermute_b32 v234, v4, v13 offset:160
	ds_bpermute_b32 v236, v4, v13 offset:192
	ds_bpermute_b32 v238, v4, v13 offset:224
	s_waitcnt vmcnt(36) lgkmcnt(15)
	v_cvt_pk_f32_fp8_e32 v[40:41], v64
	v_cvt_pk_f32_fp8_sdwa v[42:43], v64 src0_sel:WORD_1
	v_cvt_pk_f32_fp8_e32 v[44:45], v65
	v_cvt_pk_f32_fp8_sdwa v[46:47], v65 src0_sel:WORD_1
	v_cvt_pk_f32_fp8_e32 v[48:49], v66
	v_cvt_pk_f32_fp8_sdwa v[50:51], v66 src0_sel:WORD_1
	v_cvt_pk_f32_fp8_e32 v[52:53], v67
	v_cvt_pk_f32_fp8_sdwa v[54:55], v67 src0_sel:WORD_1
	v_pk_mul_f32 v[24:25], v[40:41], v[208:209] op_sel_hi:[1,0]
	v_pk_mul_f32 v[26:27], v[42:43], v[208:209] op_sel_hi:[1,0]
	v_pk_mul_f32 v[28:29], v[44:45], v[208:209] op_sel_hi:[1,0]
	v_pk_mul_f32 v[30:31], v[46:47], v[208:209] op_sel_hi:[1,0]
	v_pk_mul_f32 v[32:33], v[48:49], v[208:209] op_sel_hi:[1,0]
	v_pk_mul_f32 v[34:35], v[50:51], v[208:209] op_sel_hi:[1,0]
	v_pk_mul_f32 v[36:37], v[52:53], v[208:209] op_sel_hi:[1,0]
	v_pk_mul_f32 v[38:39], v[54:55], v[208:209] op_sel_hi:[1,0]
	s_waitcnt vmcnt(35) lgkmcnt(14)
	v_cvt_pk_f32_fp8_e32 v[40:41], v68
	v_cvt_pk_f32_fp8_sdwa v[42:43], v68 src0_sel:WORD_1
	v_cvt_pk_f32_fp8_e32 v[44:45], v69
	v_cvt_pk_f32_fp8_sdwa v[46:47], v69 src0_sel:WORD_1
	v_cvt_pk_f32_fp8_e32 v[48:49], v70
	v_cvt_pk_f32_fp8_sdwa v[50:51], v70 src0_sel:WORD_1
	v_cvt_pk_f32_fp8_e32 v[52:53], v71
	v_cvt_pk_f32_fp8_sdwa v[54:55], v71 src0_sel:WORD_1
	v_pk_fma_f32 v[24:25], v[40:41], v[210:211], v[24:25] op_sel_hi:[1,0,1]
	v_pk_fma_f32 v[26:27], v[42:43], v[210:211], v[26:27] op_sel_hi:[1,0,1]
	v_pk_fma_f32 v[28:29], v[44:45], v[210:211], v[28:29] op_sel_hi:[1,0,1]
	v_pk_fma_f32 v[30:31], v[46:47], v[210:211], v[30:31] op_sel_hi:[1,0,1]
	v_pk_fma_f32 v[32:33], v[48:49], v[210:211], v[32:33] op_sel_hi:[1,0,1]
	v_pk_fma_f32 v[34:35], v[50:51], v[210:211], v[34:35] op_sel_hi:[1,0,1]
	v_pk_fma_f32 v[36:37], v[52:53], v[210:211], v[36:37] op_sel_hi:[1,0,1]
	v_pk_fma_f32 v[38:39], v[54:55], v[210:211], v[38:39] op_sel_hi:[1,0,1]
	s_waitcnt vmcnt(34) lgkmcnt(13)
	v_cvt_pk_f32_fp8_e32 v[40:41], v72
	v_cvt_pk_f32_fp8_sdwa v[42:43], v72 src0_sel:WORD_1
	v_cvt_pk_f32_fp8_e32 v[44:45], v73
	v_cvt_pk_f32_fp8_sdwa v[46:47], v73 src0_sel:WORD_1
	v_cvt_pk_f32_fp8_e32 v[48:49], v74
	v_cvt_pk_f32_fp8_sdwa v[50:51], v74 src0_sel:WORD_1
	v_cvt_pk_f32_fp8_e32 v[52:53], v75
	v_cvt_pk_f32_fp8_sdwa v[54:55], v75 src0_sel:WORD_1
	v_pk_fma_f32 v[24:25], v[40:41], v[212:213], v[24:25] op_sel_hi:[1,0,1]
	v_pk_fma_f32 v[26:27], v[42:43], v[212:213], v[26:27] op_sel_hi:[1,0,1]
	v_pk_fma_f32 v[28:29], v[44:45], v[212:213], v[28:29] op_sel_hi:[1,0,1]
	v_pk_fma_f32 v[30:31], v[46:47], v[212:213], v[30:31] op_sel_hi:[1,0,1]
	v_pk_fma_f32 v[32:33], v[48:49], v[212:213], v[32:33] op_sel_hi:[1,0,1]
	v_pk_fma_f32 v[34:35], v[50:51], v[212:213], v[34:35] op_sel_hi:[1,0,1]
	v_pk_fma_f32 v[36:37], v[52:53], v[212:213], v[36:37] op_sel_hi:[1,0,1]
	v_pk_fma_f32 v[38:39], v[54:55], v[212:213], v[38:39] op_sel_hi:[1,0,1]
	s_waitcnt vmcnt(33) lgkmcnt(12)
	v_cvt_pk_f32_fp8_e32 v[40:41], v76
	v_cvt_pk_f32_fp8_sdwa v[42:43], v76 src0_sel:WORD_1
	v_cvt_pk_f32_fp8_e32 v[44:45], v77
	v_cvt_pk_f32_fp8_sdwa v[46:47], v77 src0_sel:WORD_1
	v_cvt_pk_f32_fp8_e32 v[48:49], v78
	v_cvt_pk_f32_fp8_sdwa v[50:51], v78 src0_sel:WORD_1
	v_cvt_pk_f32_fp8_e32 v[52:53], v79
	v_cvt_pk_f32_fp8_sdwa v[54:55], v79 src0_sel:WORD_1
	v_pk_fma_f32 v[24:25], v[40:41], v[214:215], v[24:25] op_sel_hi:[1,0,1]
	v_pk_fma_f32 v[26:27], v[42:43], v[214:215], v[26:27] op_sel_hi:[1,0,1]
	v_pk_fma_f32 v[28:29], v[44:45], v[214:215], v[28:29] op_sel_hi:[1,0,1]
	v_pk_fma_f32 v[30:31], v[46:47], v[214:215], v[30:31] op_sel_hi:[1,0,1]
	v_pk_fma_f32 v[32:33], v[48:49], v[214:215], v[32:33] op_sel_hi:[1,0,1]
	v_pk_fma_f32 v[34:35], v[50:51], v[214:215], v[34:35] op_sel_hi:[1,0,1]
	v_pk_fma_f32 v[36:37], v[52:53], v[214:215], v[36:37] op_sel_hi:[1,0,1]
	v_pk_fma_f32 v[38:39], v[54:55], v[214:215], v[38:39] op_sel_hi:[1,0,1]
	s_waitcnt vmcnt(32) lgkmcnt(11)
	v_cvt_pk_f32_fp8_e32 v[40:41], v80
	v_cvt_pk_f32_fp8_sdwa v[42:43], v80 src0_sel:WORD_1
	v_cvt_pk_f32_fp8_e32 v[44:45], v81
	v_cvt_pk_f32_fp8_sdwa v[46:47], v81 src0_sel:WORD_1
	v_cvt_pk_f32_fp8_e32 v[48:49], v82
	v_cvt_pk_f32_fp8_sdwa v[50:51], v82 src0_sel:WORD_1
	v_cvt_pk_f32_fp8_e32 v[52:53], v83
	v_cvt_pk_f32_fp8_sdwa v[54:55], v83 src0_sel:WORD_1
	v_pk_fma_f32 v[24:25], v[40:41], v[216:217], v[24:25] op_sel_hi:[1,0,1]
	v_pk_fma_f32 v[26:27], v[42:43], v[216:217], v[26:27] op_sel_hi:[1,0,1]
	v_pk_fma_f32 v[28:29], v[44:45], v[216:217], v[28:29] op_sel_hi:[1,0,1]
	v_pk_fma_f32 v[30:31], v[46:47], v[216:217], v[30:31] op_sel_hi:[1,0,1]
	v_pk_fma_f32 v[32:33], v[48:49], v[216:217], v[32:33] op_sel_hi:[1,0,1]
	v_pk_fma_f32 v[34:35], v[50:51], v[216:217], v[34:35] op_sel_hi:[1,0,1]
	v_pk_fma_f32 v[36:37], v[52:53], v[216:217], v[36:37] op_sel_hi:[1,0,1]
	v_pk_fma_f32 v[38:39], v[54:55], v[216:217], v[38:39] op_sel_hi:[1,0,1]
	s_waitcnt vmcnt(31) lgkmcnt(10)
	v_cvt_pk_f32_fp8_e32 v[40:41], v84
	v_cvt_pk_f32_fp8_sdwa v[42:43], v84 src0_sel:WORD_1
	v_cvt_pk_f32_fp8_e32 v[44:45], v85
	v_cvt_pk_f32_fp8_sdwa v[46:47], v85 src0_sel:WORD_1
	v_cvt_pk_f32_fp8_e32 v[48:49], v86
	v_cvt_pk_f32_fp8_sdwa v[50:51], v86 src0_sel:WORD_1
	v_cvt_pk_f32_fp8_e32 v[52:53], v87
	v_cvt_pk_f32_fp8_sdwa v[54:55], v87 src0_sel:WORD_1
	v_pk_fma_f32 v[24:25], v[40:41], v[218:219], v[24:25] op_sel_hi:[1,0,1]
	v_pk_fma_f32 v[26:27], v[42:43], v[218:219], v[26:27] op_sel_hi:[1,0,1]
	v_pk_fma_f32 v[28:29], v[44:45], v[218:219], v[28:29] op_sel_hi:[1,0,1]
	v_pk_fma_f32 v[30:31], v[46:47], v[218:219], v[30:31] op_sel_hi:[1,0,1]
	v_pk_fma_f32 v[32:33], v[48:49], v[218:219], v[32:33] op_sel_hi:[1,0,1]
	v_pk_fma_f32 v[34:35], v[50:51], v[218:219], v[34:35] op_sel_hi:[1,0,1]
	v_pk_fma_f32 v[36:37], v[52:53], v[218:219], v[36:37] op_sel_hi:[1,0,1]
	v_pk_fma_f32 v[38:39], v[54:55], v[218:219], v[38:39] op_sel_hi:[1,0,1]
	s_waitcnt vmcnt(30) lgkmcnt(9)
	v_cvt_pk_f32_fp8_e32 v[40:41], v88
	v_cvt_pk_f32_fp8_sdwa v[42:43], v88 src0_sel:WORD_1
	v_cvt_pk_f32_fp8_e32 v[44:45], v89
	v_cvt_pk_f32_fp8_sdwa v[46:47], v89 src0_sel:WORD_1
	v_cvt_pk_f32_fp8_e32 v[48:49], v90
	v_cvt_pk_f32_fp8_sdwa v[50:51], v90 src0_sel:WORD_1
	v_cvt_pk_f32_fp8_e32 v[52:53], v91
	v_cvt_pk_f32_fp8_sdwa v[54:55], v91 src0_sel:WORD_1
	v_pk_fma_f32 v[24:25], v[40:41], v[220:221], v[24:25] op_sel_hi:[1,0,1]
	v_pk_fma_f32 v[26:27], v[42:43], v[220:221], v[26:27] op_sel_hi:[1,0,1]
	v_pk_fma_f32 v[28:29], v[44:45], v[220:221], v[28:29] op_sel_hi:[1,0,1]
	v_pk_fma_f32 v[30:31], v[46:47], v[220:221], v[30:31] op_sel_hi:[1,0,1]
	v_pk_fma_f32 v[32:33], v[48:49], v[220:221], v[32:33] op_sel_hi:[1,0,1]
	v_pk_fma_f32 v[34:35], v[50:51], v[220:221], v[34:35] op_sel_hi:[1,0,1]
	v_pk_fma_f32 v[36:37], v[52:53], v[220:221], v[36:37] op_sel_hi:[1,0,1]
	v_pk_fma_f32 v[38:39], v[54:55], v[220:221], v[38:39] op_sel_hi:[1,0,1]
	s_waitcnt vmcnt(29) lgkmcnt(8)
	v_cvt_pk_f32_fp8_e32 v[40:41], v92
	v_cvt_pk_f32_fp8_sdwa v[42:43], v92 src0_sel:WORD_1
	v_cvt_pk_f32_fp8_e32 v[44:45], v93
	v_cvt_pk_f32_fp8_sdwa v[46:47], v93 src0_sel:WORD_1
	v_cvt_pk_f32_fp8_e32 v[48:49], v94
	v_cvt_pk_f32_fp8_sdwa v[50:51], v94 src0_sel:WORD_1
	v_cvt_pk_f32_fp8_e32 v[52:53], v95
	v_cvt_pk_f32_fp8_sdwa v[54:55], v95 src0_sel:WORD_1
	v_pk_fma_f32 v[24:25], v[40:41], v[222:223], v[24:25] op_sel_hi:[1,0,1]
	v_pk_fma_f32 v[26:27], v[42:43], v[222:223], v[26:27] op_sel_hi:[1,0,1]
	v_pk_fma_f32 v[28:29], v[44:45], v[222:223], v[28:29] op_sel_hi:[1,0,1]
	v_pk_fma_f32 v[30:31], v[46:47], v[222:223], v[30:31] op_sel_hi:[1,0,1]
	v_pk_fma_f32 v[32:33], v[48:49], v[222:223], v[32:33] op_sel_hi:[1,0,1]
	v_pk_fma_f32 v[34:35], v[50:51], v[222:223], v[34:35] op_sel_hi:[1,0,1]
	v_pk_fma_f32 v[36:37], v[52:53], v[222:223], v[36:37] op_sel_hi:[1,0,1]
	v_pk_fma_f32 v[38:39], v[54:55], v[222:223], v[38:39] op_sel_hi:[1,0,1]
	s_waitcnt vmcnt(28) lgkmcnt(7)
	v_cvt_pk_f32_fp8_e32 v[40:41], v96
	v_cvt_pk_f32_fp8_sdwa v[42:43], v96 src0_sel:WORD_1
	v_cvt_pk_f32_fp8_e32 v[44:45], v97
	v_cvt_pk_f32_fp8_sdwa v[46:47], v97 src0_sel:WORD_1
	v_cvt_pk_f32_fp8_e32 v[48:49], v98
	v_cvt_pk_f32_fp8_sdwa v[50:51], v98 src0_sel:WORD_1
	v_cvt_pk_f32_fp8_e32 v[52:53], v99
	v_cvt_pk_f32_fp8_sdwa v[54:55], v99 src0_sel:WORD_1
	v_pk_fma_f32 v[24:25], v[40:41], v[224:225], v[24:25] op_sel_hi:[1,0,1]
	v_pk_fma_f32 v[26:27], v[42:43], v[224:225], v[26:27] op_sel_hi:[1,0,1]
	v_pk_fma_f32 v[28:29], v[44:45], v[224:225], v[28:29] op_sel_hi:[1,0,1]
	v_pk_fma_f32 v[30:31], v[46:47], v[224:225], v[30:31] op_sel_hi:[1,0,1]
	v_pk_fma_f32 v[32:33], v[48:49], v[224:225], v[32:33] op_sel_hi:[1,0,1]
	v_pk_fma_f32 v[34:35], v[50:51], v[224:225], v[34:35] op_sel_hi:[1,0,1]
	v_pk_fma_f32 v[36:37], v[52:53], v[224:225], v[36:37] op_sel_hi:[1,0,1]
	v_pk_fma_f32 v[38:39], v[54:55], v[224:225], v[38:39] op_sel_hi:[1,0,1]
	s_waitcnt vmcnt(27) lgkmcnt(6)
	v_cvt_pk_f32_fp8_e32 v[40:41], v100
	v_cvt_pk_f32_fp8_sdwa v[42:43], v100 src0_sel:WORD_1
	v_cvt_pk_f32_fp8_e32 v[44:45], v101
	v_cvt_pk_f32_fp8_sdwa v[46:47], v101 src0_sel:WORD_1
	v_cvt_pk_f32_fp8_e32 v[48:49], v102
	v_cvt_pk_f32_fp8_sdwa v[50:51], v102 src0_sel:WORD_1
	v_cvt_pk_f32_fp8_e32 v[52:53], v103
	v_cvt_pk_f32_fp8_sdwa v[54:55], v103 src0_sel:WORD_1
	v_pk_fma_f32 v[24:25], v[40:41], v[226:227], v[24:25] op_sel_hi:[1,0,1]
	v_pk_fma_f32 v[26:27], v[42:43], v[226:227], v[26:27] op_sel_hi:[1,0,1]
	v_pk_fma_f32 v[28:29], v[44:45], v[226:227], v[28:29] op_sel_hi:[1,0,1]
	v_pk_fma_f32 v[30:31], v[46:47], v[226:227], v[30:31] op_sel_hi:[1,0,1]
	v_pk_fma_f32 v[32:33], v[48:49], v[226:227], v[32:33] op_sel_hi:[1,0,1]
	v_pk_fma_f32 v[34:35], v[50:51], v[226:227], v[34:35] op_sel_hi:[1,0,1]
	v_pk_fma_f32 v[36:37], v[52:53], v[226:227], v[36:37] op_sel_hi:[1,0,1]
	v_pk_fma_f32 v[38:39], v[54:55], v[226:227], v[38:39] op_sel_hi:[1,0,1]
	s_waitcnt vmcnt(26) lgkmcnt(5)
	v_cvt_pk_f32_fp8_e32 v[40:41], v104
	v_cvt_pk_f32_fp8_sdwa v[42:43], v104 src0_sel:WORD_1
	v_cvt_pk_f32_fp8_e32 v[44:45], v105
	v_cvt_pk_f32_fp8_sdwa v[46:47], v105 src0_sel:WORD_1
	v_cvt_pk_f32_fp8_e32 v[48:49], v106
	v_cvt_pk_f32_fp8_sdwa v[50:51], v106 src0_sel:WORD_1
	v_cvt_pk_f32_fp8_e32 v[52:53], v107
	v_cvt_pk_f32_fp8_sdwa v[54:55], v107 src0_sel:WORD_1
	v_pk_fma_f32 v[24:25], v[40:41], v[228:229], v[24:25] op_sel_hi:[1,0,1]
	v_pk_fma_f32 v[26:27], v[42:43], v[228:229], v[26:27] op_sel_hi:[1,0,1]
	v_pk_fma_f32 v[28:29], v[44:45], v[228:229], v[28:29] op_sel_hi:[1,0,1]
	v_pk_fma_f32 v[30:31], v[46:47], v[228:229], v[30:31] op_sel_hi:[1,0,1]
	v_pk_fma_f32 v[32:33], v[48:49], v[228:229], v[32:33] op_sel_hi:[1,0,1]
	v_pk_fma_f32 v[34:35], v[50:51], v[228:229], v[34:35] op_sel_hi:[1,0,1]
	v_pk_fma_f32 v[36:37], v[52:53], v[228:229], v[36:37] op_sel_hi:[1,0,1]
	v_pk_fma_f32 v[38:39], v[54:55], v[228:229], v[38:39] op_sel_hi:[1,0,1]
	s_waitcnt vmcnt(25) lgkmcnt(4)
	v_cvt_pk_f32_fp8_e32 v[40:41], v108
	v_cvt_pk_f32_fp8_sdwa v[42:43], v108 src0_sel:WORD_1
	v_cvt_pk_f32_fp8_e32 v[44:45], v109
	v_cvt_pk_f32_fp8_sdwa v[46:47], v109 src0_sel:WORD_1
	v_cvt_pk_f32_fp8_e32 v[48:49], v110
	v_cvt_pk_f32_fp8_sdwa v[50:51], v110 src0_sel:WORD_1
	v_cvt_pk_f32_fp8_e32 v[52:53], v111
	v_cvt_pk_f32_fp8_sdwa v[54:55], v111 src0_sel:WORD_1
	v_pk_fma_f32 v[24:25], v[40:41], v[230:231], v[24:25] op_sel_hi:[1,0,1]
	v_pk_fma_f32 v[26:27], v[42:43], v[230:231], v[26:27] op_sel_hi:[1,0,1]
	v_pk_fma_f32 v[28:29], v[44:45], v[230:231], v[28:29] op_sel_hi:[1,0,1]
	v_pk_fma_f32 v[30:31], v[46:47], v[230:231], v[30:31] op_sel_hi:[1,0,1]
	v_pk_fma_f32 v[32:33], v[48:49], v[230:231], v[32:33] op_sel_hi:[1,0,1]
	v_pk_fma_f32 v[34:35], v[50:51], v[230:231], v[34:35] op_sel_hi:[1,0,1]
	v_pk_fma_f32 v[36:37], v[52:53], v[230:231], v[36:37] op_sel_hi:[1,0,1]
	v_pk_fma_f32 v[38:39], v[54:55], v[230:231], v[38:39] op_sel_hi:[1,0,1]
	s_waitcnt vmcnt(24) lgkmcnt(3)
	v_cvt_pk_f32_fp8_e32 v[40:41], v112
	v_cvt_pk_f32_fp8_sdwa v[42:43], v112 src0_sel:WORD_1
	v_cvt_pk_f32_fp8_e32 v[44:45], v113
	v_cvt_pk_f32_fp8_sdwa v[46:47], v113 src0_sel:WORD_1
	v_cvt_pk_f32_fp8_e32 v[48:49], v114
	v_cvt_pk_f32_fp8_sdwa v[50:51], v114 src0_sel:WORD_1
	v_cvt_pk_f32_fp8_e32 v[52:53], v115
	v_cvt_pk_f32_fp8_sdwa v[54:55], v115 src0_sel:WORD_1
	v_pk_fma_f32 v[24:25], v[40:41], v[232:233], v[24:25] op_sel_hi:[1,0,1]
	v_pk_fma_f32 v[26:27], v[42:43], v[232:233], v[26:27] op_sel_hi:[1,0,1]
	v_pk_fma_f32 v[28:29], v[44:45], v[232:233], v[28:29] op_sel_hi:[1,0,1]
	v_pk_fma_f32 v[30:31], v[46:47], v[232:233], v[30:31] op_sel_hi:[1,0,1]
	v_pk_fma_f32 v[32:33], v[48:49], v[232:233], v[32:33] op_sel_hi:[1,0,1]
	v_pk_fma_f32 v[34:35], v[50:51], v[232:233], v[34:35] op_sel_hi:[1,0,1]
	v_pk_fma_f32 v[36:37], v[52:53], v[232:233], v[36:37] op_sel_hi:[1,0,1]
	v_pk_fma_f32 v[38:39], v[54:55], v[232:233], v[38:39] op_sel_hi:[1,0,1]
	s_waitcnt vmcnt(23) lgkmcnt(2)
	v_cvt_pk_f32_fp8_e32 v[40:41], v116
	v_cvt_pk_f32_fp8_sdwa v[42:43], v116 src0_sel:WORD_1
	v_cvt_pk_f32_fp8_e32 v[44:45], v117
	v_cvt_pk_f32_fp8_sdwa v[46:47], v117 src0_sel:WORD_1
	v_cvt_pk_f32_fp8_e32 v[48:49], v118
	v_cvt_pk_f32_fp8_sdwa v[50:51], v118 src0_sel:WORD_1
	v_cvt_pk_f32_fp8_e32 v[52:53], v119
	v_cvt_pk_f32_fp8_sdwa v[54:55], v119 src0_sel:WORD_1
	v_pk_fma_f32 v[24:25], v[40:41], v[234:235], v[24:25] op_sel_hi:[1,0,1]
	v_pk_fma_f32 v[26:27], v[42:43], v[234:235], v[26:27] op_sel_hi:[1,0,1]
	v_pk_fma_f32 v[28:29], v[44:45], v[234:235], v[28:29] op_sel_hi:[1,0,1]
	v_pk_fma_f32 v[30:31], v[46:47], v[234:235], v[30:31] op_sel_hi:[1,0,1]
	v_pk_fma_f32 v[32:33], v[48:49], v[234:235], v[32:33] op_sel_hi:[1,0,1]
	v_pk_fma_f32 v[34:35], v[50:51], v[234:235], v[34:35] op_sel_hi:[1,0,1]
	v_pk_fma_f32 v[36:37], v[52:53], v[234:235], v[36:37] op_sel_hi:[1,0,1]
	v_pk_fma_f32 v[38:39], v[54:55], v[234:235], v[38:39] op_sel_hi:[1,0,1]
	s_waitcnt vmcnt(22) lgkmcnt(1)
	v_cvt_pk_f32_fp8_e32 v[40:41], v120
	v_cvt_pk_f32_fp8_sdwa v[42:43], v120 src0_sel:WORD_1
	v_cvt_pk_f32_fp8_e32 v[44:45], v121
	v_cvt_pk_f32_fp8_sdwa v[46:47], v121 src0_sel:WORD_1
	v_cvt_pk_f32_fp8_e32 v[48:49], v122
	v_cvt_pk_f32_fp8_sdwa v[50:51], v122 src0_sel:WORD_1
	v_cvt_pk_f32_fp8_e32 v[52:53], v123
	v_cvt_pk_f32_fp8_sdwa v[54:55], v123 src0_sel:WORD_1
	v_pk_fma_f32 v[24:25], v[40:41], v[236:237], v[24:25] op_sel_hi:[1,0,1]
	v_pk_fma_f32 v[26:27], v[42:43], v[236:237], v[26:27] op_sel_hi:[1,0,1]
	v_pk_fma_f32 v[28:29], v[44:45], v[236:237], v[28:29] op_sel_hi:[1,0,1]
	v_pk_fma_f32 v[30:31], v[46:47], v[236:237], v[30:31] op_sel_hi:[1,0,1]
	v_pk_fma_f32 v[32:33], v[48:49], v[236:237], v[32:33] op_sel_hi:[1,0,1]
	v_pk_fma_f32 v[34:35], v[50:51], v[236:237], v[34:35] op_sel_hi:[1,0,1]
	v_pk_fma_f32 v[36:37], v[52:53], v[236:237], v[36:37] op_sel_hi:[1,0,1]
	v_pk_fma_f32 v[38:39], v[54:55], v[236:237], v[38:39] op_sel_hi:[1,0,1]
	s_waitcnt vmcnt(21) lgkmcnt(0)
	v_cvt_pk_f32_fp8_e32 v[40:41], v124
	v_cvt_pk_f32_fp8_sdwa v[42:43], v124 src0_sel:WORD_1
	v_cvt_pk_f32_fp8_e32 v[44:45], v125
	v_cvt_pk_f32_fp8_sdwa v[46:47], v125 src0_sel:WORD_1
	v_cvt_pk_f32_fp8_e32 v[48:49], v126
	v_cvt_pk_f32_fp8_sdwa v[50:51], v126 src0_sel:WORD_1
	v_cvt_pk_f32_fp8_e32 v[52:53], v127
	v_cvt_pk_f32_fp8_sdwa v[54:55], v127 src0_sel:WORD_1
	v_pk_fma_f32 v[24:25], v[40:41], v[238:239], v[24:25] op_sel_hi:[1,0,1]
	v_pk_fma_f32 v[26:27], v[42:43], v[238:239], v[26:27] op_sel_hi:[1,0,1]
	v_pk_fma_f32 v[28:29], v[44:45], v[238:239], v[28:29] op_sel_hi:[1,0,1]
	v_pk_fma_f32 v[30:31], v[46:47], v[238:239], v[30:31] op_sel_hi:[1,0,1]
	v_pk_fma_f32 v[32:33], v[48:49], v[238:239], v[32:33] op_sel_hi:[1,0,1]
	v_pk_fma_f32 v[34:35], v[50:51], v[238:239], v[34:35] op_sel_hi:[1,0,1]
	v_pk_fma_f32 v[36:37], v[52:53], v[238:239], v[36:37] op_sel_hi:[1,0,1]
	v_pk_fma_f32 v[38:39], v[54:55], v[238:239], v[38:39] op_sel_hi:[1,0,1]
	ds_write_b128 v5, v[24:27]
	ds_write_b128 v5, v[28:31] offset:16
	ds_write_b128 v5, v[32:35] offset:32
	ds_write_b128 v5, v[36:39] offset:48
	ds_read_b64 v[40:41], v6
	ds_read_b64 v[42:43], v6 offset:512
	ds_read_b64 v[44:45], v6 offset:1024
	ds_read_b64 v[46:47], v6 offset:1536
	ds_read_b64 v[48:49], v6 offset:2048
	ds_read_b64 v[50:51], v6 offset:2560
	ds_read_b64 v[52:53], v6 offset:3072
	ds_read_b64 v[54:55], v6 offset:3584
	s_waitcnt lgkmcnt(6)
	v_pk_add_f32 v[40:41], v[40:41], v[42:43]
	s_waitcnt lgkmcnt(5)
	v_pk_add_f32 v[40:41], v[40:41], v[44:45]
	s_waitcnt lgkmcnt(4)
	v_pk_add_f32 v[40:41], v[40:41], v[46:47]
	s_waitcnt lgkmcnt(3)
	v_pk_add_f32 v[40:41], v[40:41], v[48:49]
	s_waitcnt lgkmcnt(2)
	v_pk_add_f32 v[40:41], v[40:41], v[50:51]
	s_waitcnt lgkmcnt(1)
	v_pk_add_f32 v[40:41], v[40:41], v[52:53]
	s_waitcnt lgkmcnt(0)
	v_pk_add_f32 v[40:41], v[40:41], v[54:55]
	v_pk_fma_f32 v[40:41], v[18:19], s[24:25], v[40:41] op_sel_hi:[1,0,1]
	s_lshl_b32 s30, s22, 12
	s_add_u32 s66, s16, s30
	s_addc_u32 s67, s17, 0
	global_store_dwordx2 v2, v[40:41], s[66:67]
	v_mov_b32_e32 v12, v14
	v_mov_b32_e32 v13, v15
	v_mov_b32_e32 v18, v20
	v_mov_b32_e32 v19, v21
	s_add_u32 s22, s22, s12
	s_cmp_ge_u32 s22, 0x8000
	s_cbranch_scc1 .Lgv_done
	s_waitcnt vmcnt(16)
	v_mov_b32_e32 v8, v10
	v_mov_b32_e32 v9, v11
	v_mov_b32_e32 v14, v16
	v_mov_b32_e32 v15, v17
	v_mov_b32_e32 v20, v22
	v_mov_b32_e32 v21, v23
	s_mov_b32 s31, s12
	s_add_u32 s26, s22, s31
	s_min_u32 s26, s26, 0x7fff
	s_mov_b32 s42, s26
	s_mul_i32 s31, s12, 2
	s_add_u32 s26, s22, s31
	s_min_u32 s26, s26, 0x7fff
	s_lshl_b32 s30, s26, 9
	s_add_u32 s40, s18, s30
	s_addc_u32 s41, s19, 0
	global_load_dword v10, v1, s[40:41]
	global_load_dword v11, v1, s[40:41] offset:256
	s_add_u32 s64, s20, s30
	s_addc_u32 s65, s21, 0
	global_load_dword v16, v1, s[64:65]
	global_load_dword v17, v1, s[64:65] offset:256
	s_lshl_b32 s30, s26, 12
	s_add_u32 s66, s16, s30
	s_addc_u32 s67, s17, 0
	global_load_dwordx2 v[22:23], v2, s[66:67]
	ds_bpermute_b32 v192, v4, v8
	ds_bpermute_b32 v193, v4, v8 offset:32
	ds_bpermute_b32 v194, v4, v8 offset:64
	ds_bpermute_b32 v195, v4, v8 offset:96
	ds_bpermute_b32 v196, v4, v8 offset:128
	ds_bpermute_b32 v197, v4, v8 offset:160
	ds_bpermute_b32 v198, v4, v8 offset:192
	ds_bpermute_b32 v199, v4, v8 offset:224
	ds_bpermute_b32 v200, v4, v9
	ds_bpermute_b32 v201, v4, v9 offset:32
	ds_bpermute_b32 v202, v4, v9 offset:64
	ds_bpermute_b32 v203, v4, v9 offset:96
	ds_bpermute_b32 v204, v4, v9 offset:128
	ds_bpermute_b32 v205, v4, v9 offset:160
	ds_bpermute_b32 v206, v4, v9 offset:192
	ds_bpermute_b32 v207, v4, v9 offset:224
	s_waitcnt lgkmcnt(15)
	v_lshl_add_u32 v192, v192, 7, v3
	global_load_dwordx4 v[64:67], v192, s[14:15]
	s_waitcnt lgkmcnt(14)
	v_lshl_add_u32 v193, v193, 7, v3
	global_load_dwordx4 v[68:71], v193, s[14:15]
	s_waitcnt lgkmcnt(13)
	v_lshl_add_u32 v194, v194, 7, v3
	global_load_dwordx4 v[72:75], v194, s[14:15]
	s_waitcnt lgkmcnt(12)
	v_lshl_add_u32 v195, v195, 7, v3
	global_load_dwordx4 v[76:79], v195, s[14:15]
	s_waitcnt lgkmcnt(11)
	v_lshl_add_u32 v196, v196, 7, v3
	global_load_dwordx4 v[80:83], v196, s[14:15]
	s_waitcnt lgkmcnt(10)
	v_lshl_add_u32 v197, v197, 7, v3
	global_load_dwordx4 v[84:87], v197, s[14:15]
	s_waitcnt lgkmcnt(9)
	v_lshl_add_u32 v198, v198, 7, v3
	global_load_dwordx4 v[88:91], v198, s[14:15]
	s_waitcnt lgkmcnt(8)
	v_lshl_add_u32 v199, v199, 7, v3
	global_load_dwordx4 v[92:95], v199, s[14:15]
	s_waitcnt lgkmcnt(7)
	v_lshl_add_u32 v200, v200, 7, v3
	global_load_dwordx4 v[96:99], v200, s[14:15]
	s_waitcnt lgkmcnt(6)
	v_lshl_add_u32 v201, v201, 7, v3
	global_load_dwordx4 v[100:103], v201, s[14:15]
	s_waitcnt lgkmcnt(5)
	v_lshl_add_u32 v202, v202, 7, v3
	global_load_dwordx4 v[104:107], v202, s[14:15]
	s_waitcnt lgkmcnt(4)
	v_lshl_add_u32 v203, v203, 7, v3
	global_load_dwordx4 v[108:111], v203, s[14:15]
	s_waitcnt lgkmcnt(3)
	v_lshl_add_u32 v204, v204, 7, v3
	global_load_dwordx4 v[112:115], v204, s[14:15]
	s_waitcnt lgkmcnt(2)
	v_lshl_add_u32 v205, v205, 7, v3
	global_load_dwordx4 v[116:119], v205, s[14:15]
	s_waitcnt lgkmcnt(1)
	v_lshl_add_u32 v206, v206, 7, v3
	global_load_dwordx4 v[120:123], v206, s[14:15]
	s_waitcnt lgkmcnt(0)
	v_lshl_add_u32 v207, v207, 7, v3
	global_load_dwordx4 v[124:127], v207, s[14:15]
	ds_bpermute_b32 v208, v4, v12
	ds_bpermute_b32 v210, v4, v12 offset:32
	ds_bpermute_b32 v212, v4, v12 offset:64
	ds_bpermute_b32 v214, v4, v12 offset:96
	ds_bpermute_b32 v216, v4, v12 offset:128
	ds_bpermute_b32 v218, v4, v12 offset:160
	ds_bpermute_b32 v220, v4, v12 offset:192
	ds_bpermute_b32 v222, v4, v12 offset:224
	ds_bpermute_b32 v224, v4, v13
	ds_bpermute_b32 v226, v4, v13 offset:32
	ds_bpermute_b32 v228, v4, v13 offset:64
	ds_bpermute_b32 v230, v4, v13 offset:96
	ds_bpermute_b32 v232, v4, v13 offset:128
	ds_bpermute_b32 v234, v4, v13 offset:160
	ds_bpermute_b32 v236, v4, v13 offset:192
	ds_bpermute_b32 v238, v4, v13 offset:224
	s_waitcnt vmcnt(36) lgkmcnt(15)
	v_cvt_pk_f32_fp8_e32 v[40:41], v128
	v_cvt_pk_f32_fp8_sdwa v[42:43], v128 src0_sel:WORD_1
	v_cvt_pk_f32_fp8_e32 v[44:45], v129
	v_cvt_pk_f32_fp8_sdwa v[46:47], v129 src0_sel:WORD_1
	v_cvt_pk_f32_fp8_e32 v[48:49], v130
	v_cvt_pk_f32_fp8_sdwa v[50:51], v130 src0_sel:WORD_1
	v_cvt_pk_f32_fp8_e32 v[52:53], v131
	v_cvt_pk_f32_fp8_sdwa v[54:55], v131 src0_sel:WORD_1
	v_pk_mul_f32 v[24:25], v[40:41], v[208:209] op_sel_hi:[1,0]
	v_pk_mul_f32 v[26:27], v[42:43], v[208:209] op_sel_hi:[1,0]
	v_pk_mul_f32 v[28:29], v[44:45], v[208:209] op_sel_hi:[1,0]
	v_pk_mul_f32 v[30:31], v[46:47], v[208:209] op_sel_hi:[1,0]
	v_pk_mul_f32 v[32:33], v[48:49], v[208:209] op_sel_hi:[1,0]
	v_pk_mul_f32 v[34:35], v[50:51], v[208:209] op_sel_hi:[1,0]
	v_pk_mul_f32 v[36:37], v[52:53], v[208:209] op_sel_hi:[1,0]
	v_pk_mul_f32 v[38:39], v[54:55], v[208:209] op_sel_hi:[1,0]
	s_waitcnt vmcnt(35) lgkmcnt(14)
	v_cvt_pk_f32_fp8_e32 v[40:41], v132
	v_cvt_pk_f32_fp8_sdwa v[42:43], v132 src0_sel:WORD_1
	v_cvt_pk_f32_fp8_e32 v[44:45], v133
	v_cvt_pk_f32_fp8_sdwa v[46:47], v133 src0_sel:WORD_1
	v_cvt_pk_f32_fp8_e32 v[48:49], v134
	v_cvt_pk_f32_fp8_sdwa v[50:51], v134 src0_sel:WORD_1
	v_cvt_pk_f32_fp8_e32 v[52:53], v135
	v_cvt_pk_f32_fp8_sdwa v[54:55], v135 src0_sel:WORD_1
	v_pk_fma_f32 v[24:25], v[40:41], v[210:211], v[24:25] op_sel_hi:[1,0,1]
	v_pk_fma_f32 v[26:27], v[42:43], v[210:211], v[26:27] op_sel_hi:[1,0,1]
	v_pk_fma_f32 v[28:29], v[44:45], v[210:211], v[28:29] op_sel_hi:[1,0,1]
	v_pk_fma_f32 v[30:31], v[46:47], v[210:211], v[30:31] op_sel_hi:[1,0,1]
	v_pk_fma_f32 v[32:33], v[48:49], v[210:211], v[32:33] op_sel_hi:[1,0,1]
	v_pk_fma_f32 v[34:35], v[50:51], v[210:211], v[34:35] op_sel_hi:[1,0,1]
	v_pk_fma_f32 v[36:37], v[52:53], v[210:211], v[36:37] op_sel_hi:[1,0,1]
	v_pk_fma_f32 v[38:39], v[54:55], v[210:211], v[38:39] op_sel_hi:[1,0,1]
	s_waitcnt vmcnt(34) lgkmcnt(13)
	v_cvt_pk_f32_fp8_e32 v[40:41], v136
	v_cvt_pk_f32_fp8_sdwa v[42:43], v136 src0_sel:WORD_1
	v_cvt_pk_f32_fp8_e32 v[44:45], v137
	v_cvt_pk_f32_fp8_sdwa v[46:47], v137 src0_sel:WORD_1
	v_cvt_pk_f32_fp8_e32 v[48:49], v138
	v_cvt_pk_f32_fp8_sdwa v[50:51], v138 src0_sel:WORD_1
	v_cvt_pk_f32_fp8_e32 v[52:53], v139
	v_cvt_pk_f32_fp8_sdwa v[54:55], v139 src0_sel:WORD_1
	v_pk_fma_f32 v[24:25], v[40:41], v[212:213], v[24:25] op_sel_hi:[1,0,1]
	v_pk_fma_f32 v[26:27], v[42:43], v[212:213], v[26:27] op_sel_hi:[1,0,1]
	v_pk_fma_f32 v[28:29], v[44:45], v[212:213], v[28:29] op_sel_hi:[1,0,1]
	v_pk_fma_f32 v[30:31], v[46:47], v[212:213], v[30:31] op_sel_hi:[1,0,1]
	v_pk_fma_f32 v[32:33], v[48:49], v[212:213], v[32:33] op_sel_hi:[1,0,1]
	v_pk_fma_f32 v[34:35], v[50:51], v[212:213], v[34:35] op_sel_hi:[1,0,1]
	v_pk_fma_f32 v[36:37], v[52:53], v[212:213], v[36:37] op_sel_hi:[1,0,1]
	v_pk_fma_f32 v[38:39], v[54:55], v[212:213], v[38:39] op_sel_hi:[1,0,1]
	s_waitcnt vmcnt(33) lgkmcnt(12)
	v_cvt_pk_f32_fp8_e32 v[40:41], v140
	v_cvt_pk_f32_fp8_sdwa v[42:43], v140 src0_sel:WORD_1
	v_cvt_pk_f32_fp8_e32 v[44:45], v141
	v_cvt_pk_f32_fp8_sdwa v[46:47], v141 src0_sel:WORD_1
	v_cvt_pk_f32_fp8_e32 v[48:49], v142
	v_cvt_pk_f32_fp8_sdwa v[50:51], v142 src0_sel:WORD_1
	v_cvt_pk_f32_fp8_e32 v[52:53], v143
	v_cvt_pk_f32_fp8_sdwa v[54:55], v143 src0_sel:WORD_1
	v_pk_fma_f32 v[24:25], v[40:41], v[214:215], v[24:25] op_sel_hi:[1,0,1]
	v_pk_fma_f32 v[26:27], v[42:43], v[214:215], v[26:27] op_sel_hi:[1,0,1]
	v_pk_fma_f32 v[28:29], v[44:45], v[214:215], v[28:29] op_sel_hi:[1,0,1]
	v_pk_fma_f32 v[30:31], v[46:47], v[214:215], v[30:31] op_sel_hi:[1,0,1]
	v_pk_fma_f32 v[32:33], v[48:49], v[214:215], v[32:33] op_sel_hi:[1,0,1]
	v_pk_fma_f32 v[34:35], v[50:51], v[214:215], v[34:35] op_sel_hi:[1,0,1]
	v_pk_fma_f32 v[36:37], v[52:53], v[214:215], v[36:37] op_sel_hi:[1,0,1]
	v_pk_fma_f32 v[38:39], v[54:55], v[214:215], v[38:39] op_sel_hi:[1,0,1]
	s_waitcnt vmcnt(32) lgkmcnt(11)
	v_cvt_pk_f32_fp8_e32 v[40:41], v144
	v_cvt_pk_f32_fp8_sdwa v[42:43], v144 src0_sel:WORD_1
	v_cvt_pk_f32_fp8_e32 v[44:45], v145
	v_cvt_pk_f32_fp8_sdwa v[46:47], v145 src0_sel:WORD_1
	v_cvt_pk_f32_fp8_e32 v[48:49], v146
	v_cvt_pk_f32_fp8_sdwa v[50:51], v146 src0_sel:WORD_1
	v_cvt_pk_f32_fp8_e32 v[52:53], v147
	v_cvt_pk_f32_fp8_sdwa v[54:55], v147 src0_sel:WORD_1
	v_pk_fma_f32 v[24:25], v[40:41], v[216:217], v[24:25] op_sel_hi:[1,0,1]
	v_pk_fma_f32 v[26:27], v[42:43], v[216:217], v[26:27] op_sel_hi:[1,0,1]
	v_pk_fma_f32 v[28:29], v[44:45], v[216:217], v[28:29] op_sel_hi:[1,0,1]
	v_pk_fma_f32 v[30:31], v[46:47], v[216:217], v[30:31] op_sel_hi:[1,0,1]
	v_pk_fma_f32 v[32:33], v[48:49], v[216:217], v[32:33] op_sel_hi:[1,0,1]
	v_pk_fma_f32 v[34:35], v[50:51], v[216:217], v[34:35] op_sel_hi:[1,0,1]
	v_pk_fma_f32 v[36:37], v[52:53], v[216:217], v[36:37] op_sel_hi:[1,0,1]
	v_pk_fma_f32 v[38:39], v[54:55], v[216:217], v[38:39] op_sel_hi:[1,0,1]
	s_waitcnt vmcnt(31) lgkmcnt(10)
	v_cvt_pk_f32_fp8_e32 v[40:41], v148
	v_cvt_pk_f32_fp8_sdwa v[42:43], v148 src0_sel:WORD_1
	v_cvt_pk_f32_fp8_e32 v[44:45], v149
	v_cvt_pk_f32_fp8_sdwa v[46:47], v149 src0_sel:WORD_1
	v_cvt_pk_f32_fp8_e32 v[48:49], v150
	v_cvt_pk_f32_fp8_sdwa v[50:51], v150 src0_sel:WORD_1
	v_cvt_pk_f32_fp8_e32 v[52:53], v151
	v_cvt_pk_f32_fp8_sdwa v[54:55], v151 src0_sel:WORD_1
	v_pk_fma_f32 v[24:25], v[40:41], v[218:219], v[24:25] op_sel_hi:[1,0,1]
	v_pk_fma_f32 v[26:27], v[42:43], v[218:219], v[26:27] op_sel_hi:[1,0,1]
	v_pk_fma_f32 v[28:29], v[44:45], v[218:219], v[28:29] op_sel_hi:[1,0,1]
	v_pk_fma_f32 v[30:31], v[46:47], v[218:219], v[30:31] op_sel_hi:[1,0,1]
	v_pk_fma_f32 v[32:33], v[48:49], v[218:219], v[32:33] op_sel_hi:[1,0,1]
	v_pk_fma_f32 v[34:35], v[50:51], v[218:219], v[34:35] op_sel_hi:[1,0,1]
	v_pk_fma_f32 v[36:37], v[52:53], v[218:219], v[36:37] op_sel_hi:[1,0,1]
	v_pk_fma_f32 v[38:39], v[54:55], v[218:219], v[38:39] op_sel_hi:[1,0,1]
	s_waitcnt vmcnt(30) lgkmcnt(9)
	v_cvt_pk_f32_fp8_e32 v[40:41], v152
	v_cvt_pk_f32_fp8_sdwa v[42:43], v152 src0_sel:WORD_1
	v_cvt_pk_f32_fp8_e32 v[44:45], v153
	v_cvt_pk_f32_fp8_sdwa v[46:47], v153 src0_sel:WORD_1
	v_cvt_pk_f32_fp8_e32 v[48:49], v154
	v_cvt_pk_f32_fp8_sdwa v[50:51], v154 src0_sel:WORD_1
	v_cvt_pk_f32_fp8_e32 v[52:53], v155
	v_cvt_pk_f32_fp8_sdwa v[54:55], v155 src0_sel:WORD_1
	v_pk_fma_f32 v[24:25], v[40:41], v[220:221], v[24:25] op_sel_hi:[1,0,1]
	v_pk_fma_f32 v[26:27], v[42:43], v[220:221], v[26:27] op_sel_hi:[1,0,1]
	v_pk_fma_f32 v[28:29], v[44:45], v[220:221], v[28:29] op_sel_hi:[1,0,1]
	v_pk_fma_f32 v[30:31], v[46:47], v[220:221], v[30:31] op_sel_hi:[1,0,1]
	v_pk_fma_f32 v[32:33], v[48:49], v[220:221], v[32:33] op_sel_hi:[1,0,1]
	v_pk_fma_f32 v[34:35], v[50:51], v[220:221], v[34:35] op_sel_hi:[1,0,1]
	v_pk_fma_f32 v[36:37], v[52:53], v[220:221], v[36:37] op_sel_hi:[1,0,1]
	v_pk_fma_f32 v[38:39], v[54:55], v[220:221], v[38:39] op_sel_hi:[1,0,1]
	s_waitcnt vmcnt(29) lgkmcnt(8)
	v_cvt_pk_f32_fp8_e32 v[40:41], v156
	v_cvt_pk_f32_fp8_sdwa v[42:43], v156 src0_sel:WORD_1
	v_cvt_pk_f32_fp8_e32 v[44:45], v157
	v_cvt_pk_f32_fp8_sdwa v[46:47], v157 src0_sel:WORD_1
	v_cvt_pk_f32_fp8_e32 v[48:49], v158
	v_cvt_pk_f32_fp8_sdwa v[50:51], v158 src0_sel:WORD_1
	v_cvt_pk_f32_fp8_e32 v[52:53], v159
	v_cvt_pk_f32_fp8_sdwa v[54:55], v159 src0_sel:WORD_1
	v_pk_fma_f32 v[24:25], v[40:41], v[222:223], v[24:25] op_sel_hi:[1,0,1]
	v_pk_fma_f32 v[26:27], v[42:43], v[222:223], v[26:27] op_sel_hi:[1,0,1]
	v_pk_fma_f32 v[28:29], v[44:45], v[222:223], v[28:29] op_sel_hi:[1,0,1]
	v_pk_fma_f32 v[30:31], v[46:47], v[222:223], v[30:31] op_sel_hi:[1,0,1]
	v_pk_fma_f32 v[32:33], v[48:49], v[222:223], v[32:33] op_sel_hi:[1,0,1]
	v_pk_fma_f32 v[34:35], v[50:51], v[222:223], v[34:35] op_sel_hi:[1,0,1]
	v_pk_fma_f32 v[36:37], v[52:53], v[222:223], v[36:37] op_sel_hi:[1,0,1]
	v_pk_fma_f32 v[38:39], v[54:55], v[222:223], v[38:39] op_sel_hi:[1,0,1]
	s_waitcnt vmcnt(28) lgkmcnt(7)
	v_cvt_pk_f32_fp8_e32 v[40:41], v160
	v_cvt_pk_f32_fp8_sdwa v[42:43], v160 src0_sel:WORD_1
	v_cvt_pk_f32_fp8_e32 v[44:45], v161
	v_cvt_pk_f32_fp8_sdwa v[46:47], v161 src0_sel:WORD_1
	v_cvt_pk_f32_fp8_e32 v[48:49], v162
	v_cvt_pk_f32_fp8_sdwa v[50:51], v162 src0_sel:WORD_1
	v_cvt_pk_f32_fp8_e32 v[52:53], v163
	v_cvt_pk_f32_fp8_sdwa v[54:55], v163 src0_sel:WORD_1
	v_pk_fma_f32 v[24:25], v[40:41], v[224:225], v[24:25] op_sel_hi:[1,0,1]
	v_pk_fma_f32 v[26:27], v[42:43], v[224:225], v[26:27] op_sel_hi:[1,0,1]
	v_pk_fma_f32 v[28:29], v[44:45], v[224:225], v[28:29] op_sel_hi:[1,0,1]
	v_pk_fma_f32 v[30:31], v[46:47], v[224:225], v[30:31] op_sel_hi:[1,0,1]
	v_pk_fma_f32 v[32:33], v[48:49], v[224:225], v[32:33] op_sel_hi:[1,0,1]
	v_pk_fma_f32 v[34:35], v[50:51], v[224:225], v[34:35] op_sel_hi:[1,0,1]
	v_pk_fma_f32 v[36:37], v[52:53], v[224:225], v[36:37] op_sel_hi:[1,0,1]
	v_pk_fma_f32 v[38:39], v[54:55], v[224:225], v[38:39] op_sel_hi:[1,0,1]
	s_waitcnt vmcnt(27) lgkmcnt(6)
	v_cvt_pk_f32_fp8_e32 v[40:41], v164
	v_cvt_pk_f32_fp8_sdwa v[42:43], v164 src0_sel:WORD_1
	v_cvt_pk_f32_fp8_e32 v[44:45], v165
	v_cvt_pk_f32_fp8_sdwa v[46:47], v165 src0_sel:WORD_1
	v_cvt_pk_f32_fp8_e32 v[48:49], v166
	v_cvt_pk_f32_fp8_sdwa v[50:51], v166 src0_sel:WORD_1
	v_cvt_pk_f32_fp8_e32 v[52:53], v167
	v_cvt_pk_f32_fp8_sdwa v[54:55], v167 src0_sel:WORD_1
	v_pk_fma_f32 v[24:25], v[40:41], v[226:227], v[24:25] op_sel_hi:[1,0,1]
	v_pk_fma_f32 v[26:27], v[42:43], v[226:227], v[26:27] op_sel_hi:[1,0,1]
	v_pk_fma_f32 v[28:29], v[44:45], v[226:227], v[28:29] op_sel_hi:[1,0,1]
	v_pk_fma_f32 v[30:31], v[46:47], v[226:227], v[30:31] op_sel_hi:[1,0,1]
	v_pk_fma_f32 v[32:33], v[48:49], v[226:227], v[32:33] op_sel_hi:[1,0,1]
	v_pk_fma_f32 v[34:35], v[50:51], v[226:227], v[34:35] op_sel_hi:[1,0,1]
	v_pk_fma_f32 v[36:37], v[52:53], v[226:227], v[36:37] op_sel_hi:[1,0,1]
	v_pk_fma_f32 v[38:39], v[54:55], v[226:227], v[38:39] op_sel_hi:[1,0,1]
	s_waitcnt vmcnt(26) lgkmcnt(5)
	v_cvt_pk_f32_fp8_e32 v[40:41], v168
	v_cvt_pk_f32_fp8_sdwa v[42:43], v168 src0_sel:WORD_1
	v_cvt_pk_f32_fp8_e32 v[44:45], v169
	v_cvt_pk_f32_fp8_sdwa v[46:47], v169 src0_sel:WORD_1
	v_cvt_pk_f32_fp8_e32 v[48:49], v170
	v_cvt_pk_f32_fp8_sdwa v[50:51], v170 src0_sel:WORD_1
	v_cvt_pk_f32_fp8_e32 v[52:53], v171
	v_cvt_pk_f32_fp8_sdwa v[54:55], v171 src0_sel:WORD_1
	v_pk_fma_f32 v[24:25], v[40:41], v[228:229], v[24:25] op_sel_hi:[1,0,1]
	v_pk_fma_f32 v[26:27], v[42:43], v[228:229], v[26:27] op_sel_hi:[1,0,1]
	v_pk_fma_f32 v[28:29], v[44:45], v[228:229], v[28:29] op_sel_hi:[1,0,1]
	v_pk_fma_f32 v[30:31], v[46:47], v[228:229], v[30:31] op_sel_hi:[1,0,1]
	v_pk_fma_f32 v[32:33], v[48:49], v[228:229], v[32:33] op_sel_hi:[1,0,1]
	v_pk_fma_f32 v[34:35], v[50:51], v[228:229], v[34:35] op_sel_hi:[1,0,1]
	v_pk_fma_f32 v[36:37], v[52:53], v[228:229], v[36:37] op_sel_hi:[1,0,1]
	v_pk_fma_f32 v[38:39], v[54:55], v[228:229], v[38:39] op_sel_hi:[1,0,1]
	s_waitcnt vmcnt(25) lgkmcnt(4)
	v_cvt_pk_f32_fp8_e32 v[40:41], v172
	v_cvt_pk_f32_fp8_sdwa v[42:43], v172 src0_sel:WORD_1
	v_cvt_pk_f32_fp8_e32 v[44:45], v173
	v_cvt_pk_f32_fp8_sdwa v[46:47], v173 src0_sel:WORD_1
	v_cvt_pk_f32_fp8_e32 v[48:49], v174
	v_cvt_pk_f32_fp8_sdwa v[50:51], v174 src0_sel:WORD_1
	v_cvt_pk_f32_fp8_e32 v[52:53], v175
	v_cvt_pk_f32_fp8_sdwa v[54:55], v175 src0_sel:WORD_1
	v_pk_fma_f32 v[24:25], v[40:41], v[230:231], v[24:25] op_sel_hi:[1,0,1]
	v_pk_fma_f32 v[26:27], v[42:43], v[230:231], v[26:27] op_sel_hi:[1,0,1]
	v_pk_fma_f32 v[28:29], v[44:45], v[230:231], v[28:29] op_sel_hi:[1,0,1]
	v_pk_fma_f32 v[30:31], v[46:47], v[230:231], v[30:31] op_sel_hi:[1,0,1]
	v_pk_fma_f32 v[32:33], v[48:49], v[230:231], v[32:33] op_sel_hi:[1,0,1]
	v_pk_fma_f32 v[34:35], v[50:51], v[230:231], v[34:35] op_sel_hi:[1,0,1]
	v_pk_fma_f32 v[36:37], v[52:53], v[230:231], v[36:37] op_sel_hi:[1,0,1]
	v_pk_fma_f32 v[38:39], v[54:55], v[230:231], v[38:39] op_sel_hi:[1,0,1]
	s_waitcnt vmcnt(24) lgkmcnt(3)
	v_cvt_pk_f32_fp8_e32 v[40:41], v176
	v_cvt_pk_f32_fp8_sdwa v[42:43], v176 src0_sel:WORD_1
	v_cvt_pk_f32_fp8_e32 v[44:45], v177
	v_cvt_pk_f32_fp8_sdwa v[46:47], v177 src0_sel:WORD_1
	v_cvt_pk_f32_fp8_e32 v[48:49], v178
	v_cvt_pk_f32_fp8_sdwa v[50:51], v178 src0_sel:WORD_1
	v_cvt_pk_f32_fp8_e32 v[52:53], v179
	v_cvt_pk_f32_fp8_sdwa v[54:55], v179 src0_sel:WORD_1
	v_pk_fma_f32 v[24:25], v[40:41], v[232:233], v[24:25] op_sel_hi:[1,0,1]
	v_pk_fma_f32 v[26:27], v[42:43], v[232:233], v[26:27] op_sel_hi:[1,0,1]
	v_pk_fma_f32 v[28:29], v[44:45], v[232:233], v[28:29] op_sel_hi:[1,0,1]
	v_pk_fma_f32 v[30:31], v[46:47], v[232:233], v[30:31] op_sel_hi:[1,0,1]
	v_pk_fma_f32 v[32:33], v[48:49], v[232:233], v[32:33] op_sel_hi:[1,0,1]
	v_pk_fma_f32 v[34:35], v[50:51], v[232:233], v[34:35] op_sel_hi:[1,0,1]
	v_pk_fma_f32 v[36:37], v[52:53], v[232:233], v[36:37] op_sel_hi:[1,0,1]
	v_pk_fma_f32 v[38:39], v[54:55], v[232:233], v[38:39] op_sel_hi:[1,0,1]
	s_waitcnt vmcnt(23) lgkmcnt(2)
	v_cvt_pk_f32_fp8_e32 v[40:41], v180
	v_cvt_pk_f32_fp8_sdwa v[42:43], v180 src0_sel:WORD_1
	v_cvt_pk_f32_fp8_e32 v[44:45], v181
	v_cvt_pk_f32_fp8_sdwa v[46:47], v181 src0_sel:WORD_1
	v_cvt_pk_f32_fp8_e32 v[48:49], v182
	v_cvt_pk_f32_fp8_sdwa v[50:51], v182 src0_sel:WORD_1
	v_cvt_pk_f32_fp8_e32 v[52:53], v183
	v_cvt_pk_f32_fp8_sdwa v[54:55], v183 src0_sel:WORD_1
	v_pk_fma_f32 v[24:25], v[40:41], v[234:235], v[24:25] op_sel_hi:[1,0,1]
	v_pk_fma_f32 v[26:27], v[42:43], v[234:235], v[26:27] op_sel_hi:[1,0,1]
	v_pk_fma_f32 v[28:29], v[44:45], v[234:235], v[28:29] op_sel_hi:[1,0,1]
	v_pk_fma_f32 v[30:31], v[46:47], v[234:235], v[30:31] op_sel_hi:[1,0,1]
	v_pk_fma_f32 v[32:33], v[48:49], v[234:235], v[32:33] op_sel_hi:[1,0,1]
	v_pk_fma_f32 v[34:35], v[50:51], v[234:235], v[34:35] op_sel_hi:[1,0,1]
	v_pk_fma_f32 v[36:37], v[52:53], v[234:235], v[36:37] op_sel_hi:[1,0,1]
	v_pk_fma_f32 v[38:39], v[54:55], v[234:235], v[38:39] op_sel_hi:[1,0,1]
	s_waitcnt vmcnt(22) lgkmcnt(1)
	v_cvt_pk_f32_fp8_e32 v[40:41], v184
	v_cvt_pk_f32_fp8_sdwa v[42:43], v184 src0_sel:WORD_1
	v_cvt_pk_f32_fp8_e32 v[44:45], v185
	v_cvt_pk_f32_fp8_sdwa v[46:47], v185 src0_sel:WORD_1
	v_cvt_pk_f32_fp8_e32 v[48:49], v186
	v_cvt_pk_f32_fp8_sdwa v[50:51], v186 src0_sel:WORD_1
	v_cvt_pk_f32_fp8_e32 v[52:53], v187
	v_cvt_pk_f32_fp8_sdwa v[54:55], v187 src0_sel:WORD_1
	v_pk_fma_f32 v[24:25], v[40:41], v[236:237], v[24:25] op_sel_hi:[1,0,1]
	v_pk_fma_f32 v[26:27], v[42:43], v[236:237], v[26:27] op_sel_hi:[1,0,1]
	v_pk_fma_f32 v[28:29], v[44:45], v[236:237], v[28:29] op_sel_hi:[1,0,1]
	v_pk_fma_f32 v[30:31], v[46:47], v[236:237], v[30:31] op_sel_hi:[1,0,1]
	v_pk_fma_f32 v[32:33], v[48:49], v[236:237], v[32:33] op_sel_hi:[1,0,1]
	v_pk_fma_f32 v[34:35], v[50:51], v[236:237], v[34:35] op_sel_hi:[1,0,1]
	v_pk_fma_f32 v[36:37], v[52:53], v[236:237], v[36:37] op_sel_hi:[1,0,1]
	v_pk_fma_f32 v[38:39], v[54:55], v[236:237], v[38:39] op_sel_hi:[1,0,1]
	s_waitcnt vmcnt(21) lgkmcnt(0)
	v_cvt_pk_f32_fp8_e32 v[40:41], v188
	v_cvt_pk_f32_fp8_sdwa v[42:43], v188 src0_sel:WORD_1
	v_cvt_pk_f32_fp8_e32 v[44:45], v189
	v_cvt_pk_f32_fp8_sdwa v[46:47], v189 src0_sel:WORD_1
	v_cvt_pk_f32_fp8_e32 v[48:49], v190
	v_cvt_pk_f32_fp8_sdwa v[50:51], v190 src0_sel:WORD_1
	v_cvt_pk_f32_fp8_e32 v[52:53], v191
	v_cvt_pk_f32_fp8_sdwa v[54:55], v191 src0_sel:WORD_1
	v_pk_fma_f32 v[24:25], v[40:41], v[238:239], v[24:25] op_sel_hi:[1,0,1]
	v_pk_fma_f32 v[26:27], v[42:43], v[238:239], v[26:27] op_sel_hi:[1,0,1]
	v_pk_fma_f32 v[28:29], v[44:45], v[238:239], v[28:29] op_sel_hi:[1,0,1]
	v_pk_fma_f32 v[30:31], v[46:47], v[238:239], v[30:31] op_sel_hi:[1,0,1]
	v_pk_fma_f32 v[32:33], v[48:49], v[238:239], v[32:33] op_sel_hi:[1,0,1]
	v_pk_fma_f32 v[34:35], v[50:51], v[238:239], v[34:35] op_sel_hi:[1,0,1]
	v_pk_fma_f32 v[36:37], v[52:53], v[238:239], v[36:37] op_sel_hi:[1,0,1]
	v_pk_fma_f32 v[38:39], v[54:55], v[238:239], v[38:39] op_sel_hi:[1,0,1]
	ds_write_b128 v5, v[24:27]
	ds_write_b128 v5, v[28:31] offset:16
	ds_write_b128 v5, v[32:35] offset:32
	ds_write_b128 v5, v[36:39] offset:48
	ds_read_b64 v[40:41], v6
	ds_read_b64 v[42:43], v6 offset:512
	ds_read_b64 v[44:45], v6 offset:1024
	ds_read_b64 v[46:47], v6 offset:1536
	ds_read_b64 v[48:49], v6 offset:2048
	ds_read_b64 v[50:51], v6 offset:2560
	ds_read_b64 v[52:53], v6 offset:3072
	ds_read_b64 v[54:55], v6 offset:3584
	s_waitcnt lgkmcnt(6)
	v_pk_add_f32 v[40:41], v[40:41], v[42:43]
	s_waitcnt lgkmcnt(5)
	v_pk_add_f32 v[40:41], v[40:41], v[44:45]
	s_waitcnt lgkmcnt(4)
	v_pk_add_f32 v[40:41], v[40:41], v[46:47]
	s_waitcnt lgkmcnt(3)
	v_pk_add_f32 v[40:41], v[40:41], v[48:49]
	s_waitcnt lgkmcnt(2)
	v_pk_add_f32 v[40:41], v[40:41], v[50:51]
	s_waitcnt lgkmcnt(1)
	v_pk_add_f32 v[40:41], v[40:41], v[52:53]
	s_waitcnt lgkmcnt(0)
	v_pk_add_f32 v[40:41], v[40:41], v[54:55]
	v_pk_fma_f32 v[40:41], v[18:19], s[24:25], v[40:41] op_sel_hi:[1,0,1]
	s_lshl_b32 s30, s22, 12
	s_add_u32 s66, s16, s30
	s_addc_u32 s67, s17, 0
	global_store_dwordx2 v2, v[40:41], s[66:67]
	v_mov_b32_e32 v12, v14
	v_mov_b32_e32 v13, v15
	v_mov_b32_e32 v18, v20
	v_mov_b32_e32 v19, v21
	s_add_u32 s22, s22, s12
	s_cmp_ge_u32 s22, 0x8000
	s_cbranch_scc0 .Lgv_loop

.Lgl2_entry:
	s_mov_b64 s[82:83], exec
	v_readlane_b32 s4, v254, 40
	v_readlane_b32 s5, v254, 41
	v_readlane_b32 s6, v255, 15
	v_readlane_b32 s7, v254, 21
	s_nop 4
	s_load_dword s8, s[4:5], 0x0
	v_mbcnt_lo_u32_b32 v0, -1, 0
	v_mbcnt_hi_u32_b32 v0, -1, v0
	v_readlane_b32 s9, v255, 48
	v_readlane_b32 s10, v255, 52
	v_readlane_b32 s11, v255, 53
	v_readlane_b32 s12, v255, 54
	v_readlane_b32 s13, v255, 55
	v_readlane_b32 s14, v255, 50
	v_readlane_b32 s15, v255, 51
	v_lshlrev_b32_e32 v1, 6, v0
	v_lshlrev_b32_e32 v2, 5, v0
	v_lshlrev_b32_e32 v3, 2, v0
	v_xor_b32_e32 v4, 0x4, v3
	v_xor_b32_e32 v5, 0x8, v3
	v_xor_b32_e32 v6, 0x10, v3
	v_xor_b32_e32 v7, 0x20, v3
	v_xor_b32_e32 v8, 0x40, v3
	v_xor_b32_e32 v9, 0x80, v3
	v_mov_b32_e32 v10, 0x3727c5ac
	s_and_b32 s9, s9, 0xff
	s_lshl_b32 s9, s9, 13
	s_add_u32 s9, s9, 0x1000
	s_add_u32 s10, s10, s9
	s_addc_u32 s11, s11, 0
	s_add_u32 s12, s12, s9
	s_addc_u32 s13, s13, 0
	global_load_dwordx4 v[16:19], v1, s[10:11]
	global_load_dwordx4 v[20:23], v1, s[10:11] offset:16
	global_load_dwordx4 v[24:27], v1, s[10:11] offset:32
	global_load_dwordx4 v[28:31], v1, s[10:11] offset:48
	global_load_dwordx4 v[32:35], v1, s[12:13]
	global_load_dwordx4 v[36:39], v1, s[12:13] offset:16
	global_load_dwordx4 v[40:43], v1, s[12:13] offset:32
	global_load_dwordx4 v[44:47], v1, s[12:13] offset:48
	v_add_u32_e32 v49, 0x1000, v1
	v_add_u32_e32 v53, 0x800, v2
	v_add_u32_e32 v50, 0x2000, v1
	v_add_u32_e32 v54, 0x1000, v2
	v_add_u32_e32 v51, 0x3000, v1
	v_add_u32_e32 v55, 0x1800, v2
	v_mov_b32_e32 v48, v1
	v_mov_b32_e32 v52, v2
	s_lshl_b32 s6, s6, 2
	s_lshr_b32 s7, s7, 6
	s_add_u32 s6, s6, s7
	s_lshl_b32 s22, s6, 2
	s_waitcnt lgkmcnt(0)
	s_lshl_b32 s26, s8, 4
	s_add_u32 s16, s92, 0x2a100000
	s_addc_u32 s17, s93, 0
	s_add_u32 s18, s92, 0x8100000
	s_addc_u32 s19, s93, 0
	s_cmp_ge_u32 s22, 0x8000
	s_cbranch_scc1 .Lgl2_done
.Lgl2_loop:
	s_lshl_b32 s30, s22, 12
	s_add_u32 s40, s16, s30
	s_addc_u32 s41, s17, 0
	s_add_u32 s64, s14, s30
	s_addc_u32 s65, s15, 0
	s_lshl_b32 s30, s22, 11
	s_add_u32 s66, s18, s30
	s_addc_u32 s67, s19, 0
	global_load_dwordx4 v[64:67], v48, s[40:41]
	global_load_dwordx4 v[68:71], v48, s[40:41] offset:16
	global_load_dwordx4 v[72:75], v48, s[40:41] offset:32
	global_load_dwordx4 v[76:79], v48, s[40:41] offset:48
	global_load_dwordx4 v[80:83], v49, s[40:41]
	global_load_dwordx4 v[84:87], v49, s[40:41] offset:16
	global_load_dwordx4 v[88:91], v49, s[40:41] offset:32
	global_load_dwordx4 v[92:95], v49, s[40:41] offset:48
	global_load_dwordx4 v[96:99], v50, s[40:41]
	global_load_dwordx4 v[100:103], v50, s[40:41] offset:16
	global_load_dwordx4 v[104:107], v50, s[40:41] offset:32
	global_load_dwordx4 v[108:111], v50, s[40:41] offset:48
	global_load_dwordx4 v[112:115], v51, s[40:41]
	global_load_dwordx4 v[116:119], v51, s[40:41] offset:16
	global_load_dwordx4 v[120:123], v51, s[40:41] offset:32
	global_load_dwordx4 v[124:127], v51, s[40:41] offset:48
	s_waitcnt vmcnt(12)
	v_add_f32_e32 v56, v64, v65
	v_add_f32_e32 v56, v66, v56
	v_add_f32_e32 v56, v67, v56
	v_add_f32_e32 v56, v68, v56
	v_add_f32_e32 v56, v69, v56
	v_add_f32_e32 v56, v70, v56
	v_add_f32_e32 v56, v71, v56
	v_add_f32_e32 v56, v72, v56
	v_add_f32_e32 v56, v73, v56
	v_add_f32_e32 v56, v74, v56
	v_add_f32_e32 v56, v75, v56
	v_add_f32_e32 v56, v76, v56
	v_add_f32_e32 v56, v77, v56
	v_add_f32_e32 v56, v78, v56
	v_add_f32_e32 v56, v79, v56
	s_waitcnt vmcnt(8)
	v_add_f32_e32 v57, v80, v81
	v_add_f32_e32 v57, v82, v57
	v_add_f32_e32 v57, v83, v57
	v_add_f32_e32 v57, v84, v57
	v_add_f32_e32 v57, v85, v57
	v_add_f32_e32 v57, v86, v57
	v_add_f32_e32 v57, v87, v57
	v_add_f32_e32 v57, v88, v57
	v_add_f32_e32 v57, v89, v57
	v_add_f32_e32 v57, v90, v57
	v_add_f32_e32 v57, v91, v57
	v_add_f32_e32 v57, v92, v57
	v_add_f32_e32 v57, v93, v57
	v_add_f32_e32 v57, v94, v57
	v_add_f32_e32 v57, v95, v57
	s_waitcnt vmcnt(4)
	v_add_f32_e32 v58, v96, v97
	v_add_f32_e32 v58, v98, v58
	v_add_f32_e32 v58, v99, v58
	v_add_f32_e32 v58, v100, v58
	v_add_f32_e32 v58, v101, v58
	v_add_f32_e32 v58, v102, v58
	v_add_f32_e32 v58, v103, v58
	v_add_f32_e32 v58, v104, v58
	v_add_f32_e32 v58, v105, v58
	v_add_f32_e32 v58, v106, v58
	v_add_f32_e32 v58, v107, v58
	v_add_f32_e32 v58, v108, v58
	v_add_f32_e32 v58, v109, v58
	v_add_f32_e32 v58, v110, v58
	v_add_f32_e32 v58, v111, v58
	s_waitcnt vmcnt(0)
	v_add_f32_e32 v59, v112, v113
	v_add_f32_e32 v59, v114, v59
	v_add_f32_e32 v59, v115, v59
	v_add_f32_e32 v59, v116, v59
	v_add_f32_e32 v59, v117, v59
	v_add_f32_e32 v59, v118, v59
	v_add_f32_e32 v59, v119, v59
	v_add_f32_e32 v59, v120, v59
	v_add_f32_e32 v59, v121, v59
	v_add_f32_e32 v59, v122, v59
	v_add_f32_e32 v59, v123, v59
	v_add_f32_e32 v59, v124, v59
	v_add_f32_e32 v59, v125, v59
	v_add_f32_e32 v59, v126, v59
	v_add_f32_e32 v59, v127, v59
	ds_bpermute_b32 v60, v4, v56
	ds_bpermute_b32 v61, v4, v57
	ds_bpermute_b32 v62, v4, v58
	ds_bpermute_b32 v63, v4, v59
	s_waitcnt lgkmcnt(3)
	v_add_f32_e32 v56, v56, v60
	s_waitcnt lgkmcnt(2)
	v_add_f32_e32 v57, v57, v61
	s_waitcnt lgkmcnt(1)
	v_add_f32_e32 v58, v58, v62
	s_waitcnt lgkmcnt(0)
	v_add_f32_e32 v59, v59, v63
	ds_bpermute_b32 v60, v5, v56
	ds_bpermute_b32 v61, v5, v57
	ds_bpermute_b32 v62, v5, v58
	ds_bpermute_b32 v63, v5, v59
	s_waitcnt lgkmcnt(3)
	v_add_f32_e32 v56, v56, v60
	s_waitcnt lgkmcnt(2)
	v_add_f32_e32 v57, v57, v61
	s_waitcnt lgkmcnt(1)
	v_add_f32_e32 v58, v58, v62
	s_waitcnt lgkmcnt(0)
	v_add_f32_e32 v59, v59, v63
	ds_bpermute_b32 v60, v6, v56
	ds_bpermute_b32 v61, v6, v57
	ds_bpermute_b32 v62, v6, v58
	ds_bpermute_b32 v63, v6, v59
	s_waitcnt lgkmcnt(3)
	v_add_f32_e32 v56, v56, v60
	s_waitcnt lgkmcnt(2)
	v_add_f32_e32 v57, v57, v61
	s_waitcnt lgkmcnt(1)
	v_add_f32_e32 v58, v58, v62
	s_waitcnt lgkmcnt(0)
	v_add_f32_e32 v59, v59, v63
	ds_bpermute_b32 v60, v7, v56
	ds_bpermute_b32 v61, v7, v57
	ds_bpermute_b32 v62, v7, v58
	ds_bpermute_b32 v63, v7, v59
	s_waitcnt lgkmcnt(3)
	v_add_f32_e32 v56, v56, v60
	s_waitcnt lgkmcnt(2)
	v_add_f32_e32 v57, v57, v61
	s_waitcnt lgkmcnt(1)
	v_add_f32_e32 v58, v58, v62
	s_waitcnt lgkmcnt(0)
	v_add_f32_e32 v59, v59, v63
	ds_bpermute_b32 v60, v8, v56
	ds_bpermute_b32 v61, v8, v57
	ds_bpermute_b32 v62, v8, v58
	ds_bpermute_b32 v63, v8, v59
	s_waitcnt lgkmcnt(3)
	v_add_f32_e32 v56, v56, v60
	s_waitcnt lgkmcnt(2)
	v_add_f32_e32 v57, v57, v61
	s_waitcnt lgkmcnt(1)
	v_add_f32_e32 v58, v58, v62
	s_waitcnt lgkmcnt(0)
	v_add_f32_e32 v59, v59, v63
	ds_bpermute_b32 v60, v9, v56
	ds_bpermute_b32 v61, v9, v57
	ds_bpermute_b32 v62, v9, v58
	ds_bpermute_b32 v63, v9, v59
	s_waitcnt lgkmcnt(3)
	v_add_f32_e32 v56, v56, v60
	s_waitcnt lgkmcnt(2)
	v_add_f32_e32 v57, v57, v61
	s_waitcnt lgkmcnt(1)
	v_add_f32_e32 v58, v58, v62
	s_waitcnt lgkmcnt(0)
	v_add_f32_e32 v59, v59, v63
	v_mul_f32_e32 v60, 0x3a800000, v56
	v_sub_f32_e32 v64, v64, v60
	v_sub_f32_e32 v65, v65, v60
	v_sub_f32_e32 v66, v66, v60
	v_sub_f32_e32 v67, v67, v60
	v_sub_f32_e32 v68, v68, v60
	v_sub_f32_e32 v69, v69, v60
	v_sub_f32_e32 v70, v70, v60
	v_sub_f32_e32 v71, v71, v60
	v_sub_f32_e32 v72, v72, v60
	v_sub_f32_e32 v73, v73, v60
	v_sub_f32_e32 v74, v74, v60
	v_sub_f32_e32 v75, v75, v60
	v_sub_f32_e32 v76, v76, v60
	v_sub_f32_e32 v77, v77, v60
	v_sub_f32_e32 v78, v78, v60
	v_sub_f32_e32 v79, v79, v60
	v_mul_f32_e32 v56, v64, v64
	v_fmac_f32_e32 v56, v65, v65
	v_fmac_f32_e32 v56, v66, v66
	v_fmac_f32_e32 v56, v67, v67
	v_fmac_f32_e32 v56, v68, v68
	v_fmac_f32_e32 v56, v69, v69
	v_fmac_f32_e32 v56, v70, v70
	v_fmac_f32_e32 v56, v71, v71
	v_fmac_f32_e32 v56, v72, v72
	v_fmac_f32_e32 v56, v73, v73
	v_fmac_f32_e32 v56, v74, v74
	v_fmac_f32_e32 v56, v75, v75
	v_fmac_f32_e32 v56, v76, v76
	v_fmac_f32_e32 v56, v77, v77
	v_fmac_f32_e32 v56, v78, v78
	v_fmac_f32_e32 v56, v79, v79
	v_mul_f32_e32 v61, 0x3a800000, v57
	v_sub_f32_e32 v80, v80, v61
	v_sub_f32_e32 v81, v81, v61
	v_sub_f32_e32 v82, v82, v61
	v_sub_f32_e32 v83, v83, v61
	v_sub_f32_e32 v84, v84, v61
	v_sub_f32_e32 v85, v85, v61
	v_sub_f32_e32 v86, v86, v61
	v_sub_f32_e32 v87, v87, v61
	v_sub_f32_e32 v88, v88, v61
	v_sub_f32_e32 v89, v89, v61
	v_sub_f32_e32 v90, v90, v61
	v_sub_f32_e32 v91, v91, v61
	v_sub_f32_e32 v92, v92, v61
	v_sub_f32_e32 v93, v93, v61
	v_sub_f32_e32 v94, v94, v61
	v_sub_f32_e32 v95, v95, v61
	v_mul_f32_e32 v57, v80, v80
	v_fmac_f32_e32 v57, v81, v81
	v_fmac_f32_e32 v57, v82, v82
	v_fmac_f32_e32 v57, v83, v83
	v_fmac_f32_e32 v57, v84, v84
	v_fmac_f32_e32 v57, v85, v85
	v_fmac_f32_e32 v57, v86, v86
	v_fmac_f32_e32 v57, v87, v87
	v_fmac_f32_e32 v57, v88, v88
	v_fmac_f32_e32 v57, v89, v89
	v_fmac_f32_e32 v57, v90, v90
	v_fmac_f32_e32 v57, v91, v91
	v_fmac_f32_e32 v57, v92, v92
	v_fmac_f32_e32 v57, v93, v93
	v_fmac_f32_e32 v57, v94, v94
	v_fmac_f32_e32 v57, v95, v95
	v_mul_f32_e32 v62, 0x3a800000, v58
	v_sub_f32_e32 v96, v96, v62
	v_sub_f32_e32 v97, v97, v62
	v_sub_f32_e32 v98, v98, v62
	v_sub_f32_e32 v99, v99, v62
	v_sub_f32_e32 v100, v100, v62
	v_sub_f32_e32 v101, v101, v62
	v_sub_f32_e32 v102, v102, v62
	v_sub_f32_e32 v103, v103, v62
	v_sub_f32_e32 v104, v104, v62
	v_sub_f32_e32 v105, v105, v62
	v_sub_f32_e32 v106, v106, v62
	v_sub_f32_e32 v107, v107, v62
	v_sub_f32_e32 v108, v108, v62
	v_sub_f32_e32 v109, v109, v62
	v_sub_f32_e32 v110, v110, v62
	v_sub_f32_e32 v111, v111, v62
	v_mul_f32_e32 v58, v96, v96
	v_fmac_f32_e32 v58, v97, v97
	v_fmac_f32_e32 v58, v98, v98
	v_fmac_f32_e32 v58, v99, v99
	v_fmac_f32_e32 v58, v100, v100
	v_fmac_f32_e32 v58, v101, v101
	v_fmac_f32_e32 v58, v102, v102
	v_fmac_f32_e32 v58, v103, v103
	v_fmac_f32_e32 v58, v104, v104
	v_fmac_f32_e32 v58, v105, v105
	v_fmac_f32_e32 v58, v106, v106
	v_fmac_f32_e32 v58, v107, v107
	v_fmac_f32_e32 v58, v108, v108
	v_fmac_f32_e32 v58, v109, v109
	v_fmac_f32_e32 v58, v110, v110
	v_fmac_f32_e32 v58, v111, v111
	v_mul_f32_e32 v63, 0x3a800000, v59
	v_sub_f32_e32 v112, v112, v63
	v_sub_f32_e32 v113, v113, v63
	v_sub_f32_e32 v114, v114, v63
	v_sub_f32_e32 v115, v115, v63
	v_sub_f32_e32 v116, v116, v63
	v_sub_f32_e32 v117, v117, v63
	v_sub_f32_e32 v118, v118, v63
	v_sub_f32_e32 v119, v119, v63
	v_sub_f32_e32 v120, v120, v63
	v_sub_f32_e32 v121, v121, v63
	v_sub_f32_e32 v122, v122, v63
	v_sub_f32_e32 v123, v123, v63
	v_sub_f32_e32 v124, v124, v63
	v_sub_f32_e32 v125, v125, v63
	v_sub_f32_e32 v126, v126, v63
	v_sub_f32_e32 v127, v127, v63
	v_mul_f32_e32 v59, v112, v112
	v_fmac_f32_e32 v59, v113, v113
	v_fmac_f32_e32 v59, v114, v114
	v_fmac_f32_e32 v59, v115, v115
	v_fmac_f32_e32 v59, v116, v116
	v_fmac_f32_e32 v59, v117, v117
	v_fmac_f32_e32 v59, v118, v118
	v_fmac_f32_e32 v59, v119, v119
	v_fmac_f32_e32 v59, v120, v120
	v_fmac_f32_e32 v59, v121, v121
	v_fmac_f32_e32 v59, v122, v122
	v_fmac_f32_e32 v59, v123, v123
	v_fmac_f32_e32 v59, v124, v124
	v_fmac_f32_e32 v59, v125, v125
	v_fmac_f32_e32 v59, v126, v126
	v_fmac_f32_e32 v59, v127, v127
	ds_bpermute_b32 v60, v4, v56
	ds_bpermute_b32 v61, v4, v57
	ds_bpermute_b32 v62, v4, v58
	ds_bpermute_b32 v63, v4, v59
	s_waitcnt lgkmcnt(3)
	v_add_f32_e32 v56, v56, v60
	s_waitcnt lgkmcnt(2)
	v_add_f32_e32 v57, v57, v61
	s_waitcnt lgkmcnt(1)
	v_add_f32_e32 v58, v58, v62
	s_waitcnt lgkmcnt(0)
	v_add_f32_e32 v59, v59, v63
	ds_bpermute_b32 v60, v5, v56
	ds_bpermute_b32 v61, v5, v57
	ds_bpermute_b32 v62, v5, v58
	ds_bpermute_b32 v63, v5, v59
	s_waitcnt lgkmcnt(3)
	v_add_f32_e32 v56, v56, v60
	s_waitcnt lgkmcnt(2)
	v_add_f32_e32 v57, v57, v61
	s_waitcnt lgkmcnt(1)
	v_add_f32_e32 v58, v58, v62
	s_waitcnt lgkmcnt(0)
	v_add_f32_e32 v59, v59, v63
	ds_bpermute_b32 v60, v6, v56
	ds_bpermute_b32 v61, v6, v57
	ds_bpermute_b32 v62, v6, v58
	ds_bpermute_b32 v63, v6, v59
	s_waitcnt lgkmcnt(3)
	v_add_f32_e32 v56, v56, v60
	s_waitcnt lgkmcnt(2)
	v_add_f32_e32 v57, v57, v61
	s_waitcnt lgkmcnt(1)
	v_add_f32_e32 v58, v58, v62
	s_waitcnt lgkmcnt(0)
	v_add_f32_e32 v59, v59, v63
	ds_bpermute_b32 v60, v7, v56
	ds_bpermute_b32 v61, v7, v57
	ds_bpermute_b32 v62, v7, v58
	ds_bpermute_b32 v63, v7, v59
	s_waitcnt lgkmcnt(3)
	v_add_f32_e32 v56, v56, v60
	s_waitcnt lgkmcnt(2)
	v_add_f32_e32 v57, v57, v61
	s_waitcnt lgkmcnt(1)
	v_add_f32_e32 v58, v58, v62
	s_waitcnt lgkmcnt(0)
	v_add_f32_e32 v59, v59, v63
	ds_bpermute_b32 v60, v8, v56
	ds_bpermute_b32 v61, v8, v57
	ds_bpermute_b32 v62, v8, v58
	ds_bpermute_b32 v63, v8, v59
	s_waitcnt lgkmcnt(3)
	v_add_f32_e32 v56, v56, v60
	s_waitcnt lgkmcnt(2)
	v_add_f32_e32 v57, v57, v61
	s_waitcnt lgkmcnt(1)
	v_add_f32_e32 v58, v58, v62
	s_waitcnt lgkmcnt(0)
	v_add_f32_e32 v59, v59, v63
	ds_bpermute_b32 v60, v9, v56
	ds_bpermute_b32 v61, v9, v57
	ds_bpermute_b32 v62, v9, v58
	ds_bpermute_b32 v63, v9, v59
	s_waitcnt lgkmcnt(3)
	v_add_f32_e32 v56, v56, v60
	s_waitcnt lgkmcnt(2)
	v_add_f32_e32 v57, v57, v61
	s_waitcnt lgkmcnt(1)
	v_add_f32_e32 v58, v58, v62
	s_waitcnt lgkmcnt(0)
	v_add_f32_e32 v59, v59, v63
	v_fmamk_f32 v56, v56, 0x3a800000, v10
	v_fmamk_f32 v57, v57, 0x3a800000, v10
	v_fmamk_f32 v58, v58, 0x3a800000, v10
	v_fmamk_f32 v59, v59, 0x3a800000, v10
	v_rsq_f32_e32 v56, v56
	v_rsq_f32_e32 v57, v57
	v_rsq_f32_e32 v58, v58
	v_rsq_f32_e32 v59, v59
	s_nop 1
	s_waitcnt vmcnt(0)
	v_mul_f32_e32 v64, v64, v56
	v_mul_f32_e32 v65, v65, v56
	v_mul_f32_e32 v66, v66, v56
	v_mul_f32_e32 v67, v67, v56
	v_mul_f32_e32 v68, v68, v56
	v_mul_f32_e32 v69, v69, v56
	v_mul_f32_e32 v70, v70, v56
	v_mul_f32_e32 v71, v71, v56
	v_mul_f32_e32 v72, v72, v56
	v_mul_f32_e32 v73, v73, v56
	v_mul_f32_e32 v74, v74, v56
	v_mul_f32_e32 v75, v75, v56
	v_mul_f32_e32 v76, v76, v56
	v_mul_f32_e32 v77, v77, v56
	v_mul_f32_e32 v78, v78, v56
	v_mul_f32_e32 v79, v79, v56
	v_fma_f32 v64, v64, v16, v32
	v_fma_f32 v65, v65, v17, v33
	v_fma_f32 v66, v66, v18, v34
	v_fma_f32 v67, v67, v19, v35
	v_fma_f32 v68, v68, v20, v36
	v_fma_f32 v69, v69, v21, v37
	v_fma_f32 v70, v70, v22, v38
	v_fma_f32 v71, v71, v23, v39
	v_fma_f32 v72, v72, v24, v40
	v_fma_f32 v73, v73, v25, v41
	v_fma_f32 v74, v74, v26, v42
	v_fma_f32 v75, v75, v27, v43
	v_fma_f32 v76, v76, v28, v44
	v_fma_f32 v77, v77, v29, v45
	v_fma_f32 v78, v78, v30, v46
	v_fma_f32 v79, v79, v31, v47
	global_store_dwordx4 v48, v[64:67], s[64:65]
	global_store_dwordx4 v48, v[68:71], s[64:65] offset:16
	global_store_dwordx4 v48, v[72:75], s[64:65] offset:32
	global_store_dwordx4 v48, v[76:79], s[64:65] offset:48
	v_mul_f32_e32 v80, v80, v57
	v_mul_f32_e32 v81, v81, v57
	v_mul_f32_e32 v82, v82, v57
	v_mul_f32_e32 v83, v83, v57
	v_mul_f32_e32 v84, v84, v57
	v_mul_f32_e32 v85, v85, v57
	v_mul_f32_e32 v86, v86, v57
	v_mul_f32_e32 v87, v87, v57
	v_mul_f32_e32 v88, v88, v57
	v_mul_f32_e32 v89, v89, v57
	v_mul_f32_e32 v90, v90, v57
	v_mul_f32_e32 v91, v91, v57
	v_mul_f32_e32 v92, v92, v57
	v_mul_f32_e32 v93, v93, v57
	v_mul_f32_e32 v94, v94, v57
	v_mul_f32_e32 v95, v95, v57
	v_fma_f32 v80, v80, v16, v32
	v_fma_f32 v81, v81, v17, v33
	v_fma_f32 v82, v82, v18, v34
	v_fma_f32 v83, v83, v19, v35
	v_fma_f32 v84, v84, v20, v36
	v_fma_f32 v85, v85, v21, v37
	v_fma_f32 v86, v86, v22, v38
	v_fma_f32 v87, v87, v23, v39
	v_fma_f32 v88, v88, v24, v40
	v_fma_f32 v89, v89, v25, v41
	v_fma_f32 v90, v90, v26, v42
	v_fma_f32 v91, v91, v27, v43
	v_fma_f32 v92, v92, v28, v44
	v_fma_f32 v93, v93, v29, v45
	v_fma_f32 v94, v94, v30, v46
	v_fma_f32 v95, v95, v31, v47
	global_store_dwordx4 v49, v[80:83], s[64:65]
	global_store_dwordx4 v49, v[84:87], s[64:65] offset:16
	global_store_dwordx4 v49, v[88:91], s[64:65] offset:32
	global_store_dwordx4 v49, v[92:95], s[64:65] offset:48
	v_mul_f32_e32 v96, v96, v58
	v_mul_f32_e32 v97, v97, v58
	v_mul_f32_e32 v98, v98, v58
	v_mul_f32_e32 v99, v99, v58
	v_mul_f32_e32 v100, v100, v58
	v_mul_f32_e32 v101, v101, v58
	v_mul_f32_e32 v102, v102, v58
	v_mul_f32_e32 v103, v103, v58
	v_mul_f32_e32 v104, v104, v58
	v_mul_f32_e32 v105, v105, v58
	v_mul_f32_e32 v106, v106, v58
	v_mul_f32_e32 v107, v107, v58
	v_mul_f32_e32 v108, v108, v58
	v_mul_f32_e32 v109, v109, v58
	v_mul_f32_e32 v110, v110, v58
	v_mul_f32_e32 v111, v111, v58
	v_fma_f32 v96, v96, v16, v32
	v_fma_f32 v97, v97, v17, v33
	v_fma_f32 v98, v98, v18, v34
	v_fma_f32 v99, v99, v19, v35
	v_fma_f32 v100, v100, v20, v36
	v_fma_f32 v101, v101, v21, v37
	v_fma_f32 v102, v102, v22, v38
	v_fma_f32 v103, v103, v23, v39
	v_fma_f32 v104, v104, v24, v40
	v_fma_f32 v105, v105, v25, v41
	v_fma_f32 v106, v106, v26, v42
	v_fma_f32 v107, v107, v27, v43
	v_fma_f32 v108, v108, v28, v44
	v_fma_f32 v109, v109, v29, v45
	v_fma_f32 v110, v110, v30, v46
	v_fma_f32 v111, v111, v31, v47
	global_store_dwordx4 v50, v[96:99], s[64:65]
	global_store_dwordx4 v50, v[100:103], s[64:65] offset:16
	global_store_dwordx4 v50, v[104:107], s[64:65] offset:32
	global_store_dwordx4 v50, v[108:111], s[64:65] offset:48
	v_mul_f32_e32 v112, v112, v59
	v_mul_f32_e32 v113, v113, v59
	v_mul_f32_e32 v114, v114, v59
	v_mul_f32_e32 v115, v115, v59
	v_mul_f32_e32 v116, v116, v59
	v_mul_f32_e32 v117, v117, v59
	v_mul_f32_e32 v118, v118, v59
	v_mul_f32_e32 v119, v119, v59
	v_mul_f32_e32 v120, v120, v59
	v_mul_f32_e32 v121, v121, v59
	v_mul_f32_e32 v122, v122, v59
	v_mul_f32_e32 v123, v123, v59
	v_mul_f32_e32 v124, v124, v59
	v_mul_f32_e32 v125, v125, v59
	v_mul_f32_e32 v126, v126, v59
	v_mul_f32_e32 v127, v127, v59
	v_fma_f32 v112, v112, v16, v32
	v_fma_f32 v113, v113, v17, v33
	v_fma_f32 v114, v114, v18, v34
	v_fma_f32 v115, v115, v19, v35
	v_fma_f32 v116, v116, v20, v36
	v_fma_f32 v117, v117, v21, v37
	v_fma_f32 v118, v118, v22, v38
	v_fma_f32 v119, v119, v23, v39
	v_fma_f32 v120, v120, v24, v40
	v_fma_f32 v121, v121, v25, v41
	v_fma_f32 v122, v122, v26, v42
	v_fma_f32 v123, v123, v27, v43
	v_fma_f32 v124, v124, v28, v44
	v_fma_f32 v125, v125, v29, v45
	v_fma_f32 v126, v126, v30, v46
	v_fma_f32 v127, v127, v31, v47
	global_store_dwordx4 v51, v[112:115], s[64:65]
	global_store_dwordx4 v51, v[116:119], s[64:65] offset:16
	global_store_dwordx4 v51, v[120:123], s[64:65] offset:32
	global_store_dwordx4 v51, v[124:127], s[64:65] offset:48
	s_nop 1
	v_cvt_pk_bf16_f32 v128, v64, v65
	v_cvt_pk_bf16_f32 v129, v66, v67
	v_cvt_pk_bf16_f32 v130, v68, v69
	v_cvt_pk_bf16_f32 v131, v70, v71
	v_cvt_pk_bf16_f32 v132, v72, v73
	v_cvt_pk_bf16_f32 v133, v74, v75
	v_cvt_pk_bf16_f32 v134, v76, v77
	v_cvt_pk_bf16_f32 v135, v78, v79
	global_store_dwordx4 v52, v[128:131], s[66:67]
	global_store_dwordx4 v52, v[132:135], s[66:67] offset:16
	v_cvt_pk_bf16_f32 v136, v80, v81
	v_cvt_pk_bf16_f32 v137, v82, v83
	v_cvt_pk_bf16_f32 v138, v84, v85
	v_cvt_pk_bf16_f32 v139, v86, v87
	v_cvt_pk_bf16_f32 v140, v88, v89
	v_cvt_pk_bf16_f32 v141, v90, v91
	v_cvt_pk_bf16_f32 v142, v92, v93
	v_cvt_pk_bf16_f32 v143, v94, v95
	global_store_dwordx4 v53, v[136:139], s[66:67]
	global_store_dwordx4 v53, v[140:143], s[66:67] offset:16
	v_cvt_pk_bf16_f32 v144, v96, v97
	v_cvt_pk_bf16_f32 v145, v98, v99
	v_cvt_pk_bf16_f32 v146, v100, v101
	v_cvt_pk_bf16_f32 v147, v102, v103
	v_cvt_pk_bf16_f32 v148, v104, v105
	v_cvt_pk_bf16_f32 v149, v106, v107
	v_cvt_pk_bf16_f32 v150, v108, v109
	v_cvt_pk_bf16_f32 v151, v110, v111
	global_store_dwordx4 v54, v[144:147], s[66:67]
	global_store_dwordx4 v54, v[148:151], s[66:67] offset:16
	v_cvt_pk_bf16_f32 v152, v112, v113
	v_cvt_pk_bf16_f32 v153, v114, v115
	v_cvt_pk_bf16_f32 v154, v116, v117
	v_cvt_pk_bf16_f32 v155, v118, v119
	v_cvt_pk_bf16_f32 v156, v120, v121
	v_cvt_pk_bf16_f32 v157, v122, v123
	v_cvt_pk_bf16_f32 v158, v124, v125
	v_cvt_pk_bf16_f32 v159, v126, v127
	global_store_dwordx4 v55, v[152:155], s[66:67]
	global_store_dwordx4 v55, v[156:159], s[66:67] offset:16
	s_add_u32 s22, s22, s26
	s_cmp_lt_u32 s22, 0x8000
	s_cbranch_scc1 .Lgl2_loop

.LBB0_249:
	v_readlane_b32 s64, v255, 45
	v_readlane_b32 s65, v255, 46
	v_readlane_b32 s0, v255, 47
	v_readlane_b32 s1, v255, 63
	s_and_b32 s0, s0, 0xff
	s_cmp_eq_u32 s0, 7
	s_cselect_b32 s0, 1, 0
	s_cmp_lt_u32 s1, 4
	s_cselect_b32 s0, s0, 0
	s_add_i32 s1, s1, 1
	s_cmp_eq_u32 s0, 1
	s_cselect_b32 s1, s1, 0
	s_nop 0
	v_writelane_b32 v255, s1, 63
	s_xor_b32 s0, s0, 1
	s_add_i32 s64, s64, s0
	v_readlane_b32 s30, v255, 17
	v_readlane_b32 s40, v255, 19
	v_readlane_b32 s66, v255, 21
	v_readlane_b32 s68, v255, 23
	v_readlane_b32 s70, v255, 25
	v_readlane_b32 s76, v255, 27
	v_readlane_b32 s78, v255, 29
	v_readlane_b32 s80, v255, 31
	v_readlane_b32 s82, v255, 33
	v_readlane_b32 s84, v255, 35
	v_readlane_b32 s86, v255, 37
	v_readlane_b32 s88, v255, 39
	v_readlane_b32 s90, v255, 41
	v_readlane_b32 s92, v255, 43
	s_cmp_ge_i32 s64, s65
	s_mov_b64 s[0:1], -1
	v_readlane_b32 s31, v255, 18
	v_readlane_b32 s41, v255, 20
	v_readlane_b32 s67, v255, 22
	v_readlane_b32 s69, v255, 24
	v_readlane_b32 s71, v255, 26
	v_readlane_b32 s77, v255, 28
	v_readlane_b32 s79, v255, 30
	v_readlane_b32 s81, v255, 32
	v_readlane_b32 s83, v255, 34
	v_readlane_b32 s85, v255, 36
	v_readlane_b32 s87, v255, 38
	v_readlane_b32 s89, v255, 40
	v_readlane_b32 s91, v255, 42
	v_readlane_b32 s93, v255, 44
	s_cbranch_scc0 .LBB0_250
	s_getpc_b64 s[98:99]

.LBB0_346:
	v_lshl_add_u64 v[0:1], v[58:59], 0, s[34:35]
	v_add_co_u32_e32 v2, vcc, 0xffffd000, v58
	global_load_dwordx4 v[70:73], v[0:1], off offset:32
	global_load_dwordx4 v[74:77], v[0:1], off offset:16
	v_addc_co_u32_e32 v3, vcc, -1, v59, vcc
	global_load_dwordx4 v[78:81], v[2:3], off offset:-60
	global_load_dwordx4 v[82:85], v[0:1], off offset:48
	v_add_co_u32_e32 v28, vcc, s3, v58
	v_lshl_add_u64 v[20:21], v[58:59], 0, s[36:37]
	s_nop 0
	v_addc_co_u32_e32 v29, vcc, -1, v59, vcc
	v_lshl_add_u64 v[22:23], v[58:59], 0, s[38:39]
	global_load_dwordx4 v[0:3], v[58:59], off offset:-12
	global_load_dwordx4 v[4:7], v[58:59], off offset:-28
	global_load_dwordx4 v[8:11], v[58:59], off offset:-44
	global_load_dwordx4 v[12:15], v[58:59], off offset:-60
	global_load_dwordx4 v[36:39], v[20:21], off offset:32
	global_load_dwordx4 v[40:43], v[20:21], off offset:16
	global_load_dwordx4 v[16:19], v[22:23], off offset:32
	global_load_dwordx4 v[24:27], v[22:23], off offset:16
	v_add_co_u32_e32 v30, vcc, s11, v58
	global_load_dwordx4 v[44:47], v[28:29], off offset:-60
	global_load_dwordx4 v[32:35], v[20:21], off offset:48
	v_addc_co_u32_e32 v31, vcc, -1, v59, vcc
	global_load_dwordx4 v[28:31], v[30:31], off offset:-60
	s_nop 0
	global_load_dwordx4 v[20:23], v[22:23], off offset:48
	s_mov_b32 s8, 0
	s_load_dwordx16 s[40:55], s[0:1], 0x40
	v_mbcnt_lo_u32_b32 v64, -1, s8
	v_mbcnt_hi_u32_b32 v64, -1, v64
	v_lshlrev_b32_e32 v64, 2, v64
	v_xor_b32_e32 v65, 4, v64
	s_waitcnt lgkmcnt(0)
	s_mov_b64 s[40:41], s[44:45]
	s_mov_b64 s[42:43], s[46:47]
	s_mov_b64 s[44:45], s[48:49]
	s_mov_b64 s[46:47], s[50:51]
	s_mov_b64 s[48:49], s[52:53]
	s_mov_b64 s[50:51], s[54:55]
	s_waitcnt vmcnt(15)
	v_max_f32_e64 v68, |v71|, |v71|
	s_waitcnt vmcnt(14)
	v_max_f32_e64 v66, |v77|, |v77|
	v_max_f32_e64 v67, |v76|, |v76|
	v_max_f32_e64 v69, |v70|, |v70|
	v_max_f32_e64 v86, |v73|, |v73|
	v_max_f32_e64 v87, |v72|, |v72|
	v_max_f32_e32 v66, v67, v66
	v_max_f32_e32 v67, v69, v68
	v_max_f32_e32 v68, v87, v86
	s_waitcnt vmcnt(12)
	v_max_f32_e64 v69, |v85|, |v85|
	v_max_f32_e64 v86, |v84|, |v84|
	v_max_f32_e64 v88, |v81|, |v81|
	v_max_f32_e64 v89, |v80|, |v80|
	v_max_f32_e32 v69, v86, v69
	v_max_f32_e32 v87, v89, v88
	v_max3_f32 v69, |v82|, |v83|, v69
	v_max3_f32 v66, |v74|, |v75|, v66
	v_max3_f32 v86, |v78|, |v79|, v87
	v_max3_f32 v67, v67, v68, v69
	v_max3_f32 v66, v86, v66, v67
	ds_bpermute_b32 v65, v65, v66
	v_xor_b32_e32 v67, 8, v64
	v_mov_b32_e32 v86, 0
	v_mov_b32_e32 v87, 0
	v_mov_b32_e32 v88, 0
	s_waitcnt lgkmcnt(0)
	v_max_f32_e32 v65, v65, v65
	v_max_f32_e32 v65, v66, v65
	ds_bpermute_b32 v66, v67, v65
	v_xor_b32_e32 v67, 16, v64
	v_mov_b32_e32 v89, 0
	s_waitcnt lgkmcnt(0)
	v_max_f32_e32 v66, v66, v66
	v_max_f32_e32 v65, v65, v66
	ds_bpermute_b32 v66, v67, v65
	v_xor_b32_e32 v67, 32, v64
	s_waitcnt lgkmcnt(0)
	v_max_f32_e32 v66, v66, v66
	v_max_f32_e32 v65, v65, v66
	ds_bpermute_b32 v66, v67, v65
	v_xor_b32_e32 v67, 64, v64
	v_xor_b32_e32 v64, 0x80, v64
	s_waitcnt lgkmcnt(0)
	v_max_f32_e32 v66, v66, v66
	v_max_f32_e32 v65, v65, v66
	ds_bpermute_b32 v66, v67, v65
	s_waitcnt lgkmcnt(0)
	v_max_f32_e32 v66, v66, v66
	v_max_f32_e32 v65, v65, v66
	ds_bpermute_b32 v64, v64, v65
	s_waitcnt lgkmcnt(0)
	v_max_f32_e32 v64, v64, v64
	v_max_f32_e32 v68, v65, v64
	v_div_scale_f32 v66, s[8:9], v68, v68, s14
	v_rcp_f32_e32 v67, v66
	v_div_scale_f32 v69, vcc, s14, v68, s14
	v_cmp_lt_f32_e64 s[8:9], 0, v68
	v_fma_f32 v90, -v66, v67, 1.0
	v_fmac_f32_e32 v67, v90, v67
	v_mul_f32_e32 v90, v69, v67
	v_fma_f32 v91, -v66, v90, v69
	v_fmac_f32_e32 v90, v91, v67
	v_fma_f32 v66, -v66, v90, v69
	v_div_fmas_f32 v67, v66, v67, v90
	v_div_fixup_f32 v67, v67, v68, s14
	v_cndmask_b32_e64 v67, 1.0, v67, s[8:9]
	v_mul_f32_e32 v69, v78, v67
	v_mul_f32_e32 v78, v79, v67
	v_mul_f32_e32 v79, v80, v67
	v_mul_f32_e32 v80, v81, v67
	v_mul_f32_e32 v74, v74, v67
	v_mul_f32_e32 v75, v75, v67
	v_mul_f32_e32 v70, v70, v67
	v_mul_f32_e32 v71, v71, v67
	v_mul_f32_e32 v81, v82, v67
	v_mul_f32_e32 v82, v83, v67
	v_cvt_pk_fp8_f32 v86, v69, v78
	v_cvt_pk_fp8_f32 v87, v74, v75
	v_cvt_pk_fp8_f32 v88, v70, v71
	v_cvt_pk_fp8_f32 v89, v81, v82
	v_mul_f32_e32 v76, v76, v67
	v_mul_f32_e32 v77, v77, v67
	v_mul_f32_e32 v72, v72, v67
	v_mul_f32_e32 v73, v73, v67
	v_mul_f32_e32 v83, v84, v67
	v_mul_f32_e32 v67, v85, v67
	v_cvt_pk_fp8_f32 v86, v79, v80 op_sel:[0,0,1]
	v_cvt_pk_fp8_f32 v87, v76, v77 op_sel:[0,0,1]
	v_cvt_pk_fp8_f32 v88, v72, v73 op_sel:[0,0,1]
	v_cvt_pk_fp8_f32 v89, v83, v67 op_sel:[0,0,1]
	v_lshl_add_u64 v[64:65], s[50:51], 0, v[60:61]
	v_add_co_u32_e32 v66, vcc, 0x4100000, v64
	s_nop 1
	v_addc_co_u32_e32 v67, vcc, 0, v65, vcc
	s_load_dwordx2 s[98:99], s[0:1], 0x78
	s_waitcnt lgkmcnt(0)
	s_add_u32 s98, s98, 0x4100000
	s_addc_u32 s99, s99, 0
	v_subrev_u32_e32 v100, s98, v66
	v_lshrrev_b32_e32 v100, 10, v100
	v_mbcnt_lo_u32_b32 v101, -1, 0
	v_mbcnt_hi_u32_b32 v101, -1, v101
	v_and_b32_e32 v102, 7, v101
	v_lshrrev_b32_e32 v101, 3, v101
	v_lshlrev_b32_e32 v101, 21, v101
	v_lshl_or_b32 v101, v102, 4, v101
	v_lshl_add_u32 v100, v100, 7, v101
	global_store_dwordx4 v100, v[86:89], s[98:99]
	v_lshl_add_u64 v[66:67], s[50:51], 0, v[62:63]
	s_and_saveexec_b64 s[12:13], s[6:7]
	s_cbranch_execz .LBB0_348
	v_mul_f32_e32 v68, 0x3b124925, v68
	v_cndmask_b32_e64 v70, 1.0, v68, s[8:9]
	v_add_co_u32_e32 v68, vcc, 0x4040000, v66
	s_nop 1
	v_addc_co_u32_e32 v69, vcc, 0, v67, vcc
	global_store_dword v[68:69], v70, off
.LBB0_348:
	s_or_b64 exec, exec, s[12:13]
	s_waitcnt vmcnt(4)
	v_max_f32_e64 v68, |v47|, |v47|
	v_max_f32_e64 v69, |v46|, |v46|
	v_max_f32_e32 v68, v69, v68
	v_max_f32_e64 v69, |v43|, |v43|
	v_max_f32_e64 v70, |v42|, |v42|
	v_max_f32_e32 v69, v70, v69
	v_max_f32_e64 v70, |v37|, |v37|
	v_max_f32_e64 v71, |v36|, |v36|
	v_max_f32_e32 v70, v71, v70
	v_max_f32_e64 v71, |v39|, |v39|
	v_max_f32_e64 v72, |v38|, |v38|
	v_max_f32_e32 v71, v72, v71
	s_waitcnt vmcnt(3)
	v_max_f32_e64 v72, |v35|, |v35|
	v_max_f32_e64 v73, |v34|, |v34|
	v_max_f32_e32 v72, v73, v72
	v_max3_f32 v72, |v32|, |v33|, v72
	v_max3_f32 v68, |v44|, |v45|, v68
	v_max3_f32 v69, |v40|, |v41|, v69
	v_max3_f32 v70, v70, v71, v72
	s_mov_b32 s8, 0
	v_max3_f32 v68, v68, v69, v70
	s_nop 0
	v_mbcnt_lo_u32_b32 v69, -1, s8
	v_mbcnt_hi_u32_b32 v69, -1, v69
	v_lshlrev_b32_e32 v69, 2, v69
	v_xor_b32_e32 v70, 4, v69
	ds_bpermute_b32 v70, v70, v68
	s_waitcnt lgkmcnt(0)
	v_max_f32_e32 v70, v70, v70
	v_max_f32_e32 v68, v68, v70
	v_xor_b32_e32 v70, 8, v69
	ds_bpermute_b32 v70, v70, v68
	s_waitcnt lgkmcnt(0)
	v_max_f32_e32 v70, v70, v70
	v_max_f32_e32 v68, v68, v70
	v_xor_b32_e32 v70, 16, v69
	ds_bpermute_b32 v70, v70, v68
	s_waitcnt lgkmcnt(0)
	v_max_f32_e32 v70, v70, v70
	v_max_f32_e32 v68, v68, v70
	v_xor_b32_e32 v70, 32, v69
	ds_bpermute_b32 v70, v70, v68
	s_waitcnt lgkmcnt(0)
	v_max_f32_e32 v70, v70, v70
	v_max_f32_e32 v68, v68, v70
	v_xor_b32_e32 v70, 64, v69
	ds_bpermute_b32 v70, v70, v68
	v_xor_b32_e32 v69, 0x80, v69
	s_waitcnt lgkmcnt(0)
	v_max_f32_e32 v70, v70, v70
	v_max_f32_e32 v68, v68, v70
	ds_bpermute_b32 v69, v69, v68
	s_waitcnt lgkmcnt(0)
	v_max_f32_e32 v69, v69, v69
	v_max_f32_e32 v68, v68, v69
	v_div_scale_f32 v69, s[8:9], v68, v68, s14
	v_rcp_f32_e32 v70, v69
	v_cmp_lt_f32_e64 s[8:9], 0, v68
	v_fma_f32 v71, -v69, v70, 1.0
	v_fmac_f32_e32 v70, v71, v70
	v_div_scale_f32 v71, vcc, s14, v68, s14
	v_mul_f32_e32 v72, v71, v70
	v_fma_f32 v73, -v69, v72, v71
	v_fmac_f32_e32 v72, v73, v70
	v_fma_f32 v69, -v69, v72, v71
	v_div_fmas_f32 v69, v69, v70, v72
	v_div_fixup_f32 v69, v69, v68, s14
	v_cndmask_b32_e64 v69, 1.0, v69, s[8:9]
	v_mul_f32_e32 v70, v44, v69
	v_mul_f32_e32 v45, v45, v69
	v_mov_b32_e32 v44, 0
	v_cvt_pk_fp8_f32 v44, v70, v45
	v_mul_f32_e32 v46, v46, v69
	v_mul_f32_e32 v47, v47, v69
	v_mul_f32_e32 v40, v40, v69
	v_mul_f32_e32 v41, v41, v69
	v_mov_b32_e32 v45, 0
	v_cvt_pk_fp8_f32 v44, v46, v47 op_sel:[0,0,1]
	v_mul_f32_e32 v36, v36, v69
	v_mul_f32_e32 v37, v37, v69
	v_mov_b32_e32 v46, 0
	v_mul_f32_e32 v32, v32, v69
	v_mul_f32_e32 v33, v33, v69
	v_mov_b32_e32 v47, 0
	v_cvt_pk_fp8_f32 v45, v40, v41
	v_cvt_pk_fp8_f32 v46, v36, v37
	v_cvt_pk_fp8_f32 v47, v32, v33
	v_mul_f32_e32 v40, v42, v69
	v_mul_f32_e32 v41, v43, v69
	v_mul_f32_e32 v36, v38, v69
	v_mul_f32_e32 v37, v39, v69
	v_mul_f32_e32 v32, v34, v69
	v_mul_f32_e32 v33, v35, v69
	v_cvt_pk_fp8_f32 v45, v40, v41 op_sel:[0,0,1]
	v_cvt_pk_fp8_f32 v46, v36, v37 op_sel:[0,0,1]
	v_cvt_pk_fp8_f32 v47, v32, v33 op_sel:[0,0,1]
	v_add_co_u32_e32 v32, vcc, 0x4100000, v64
	s_nop 1
	v_addc_co_u32_e32 v33, vcc, 0, v65, vcc
	s_load_dwordx2 s[98:99], s[0:1], 0x78
	s_waitcnt lgkmcnt(0)
	s_add_u32 s98, s98, 0x4100000
	s_addc_u32 s99, s99, 0
	v_subrev_u32_e32 v100, s98, v32
	v_lshrrev_b32_e32 v100, 10, v100
	v_mbcnt_lo_u32_b32 v101, -1, 0
	v_mbcnt_hi_u32_b32 v101, -1, v101
	v_and_b32_e32 v102, 7, v101
	v_lshrrev_b32_e32 v101, 3, v101
	v_lshlrev_b32_e32 v101, 21, v101
	v_lshl_or_b32 v101, v102, 4, v101
	v_lshl_add_u32 v100, v100, 7, v101
	global_store_dwordx4 v100, v[44:47], s[98:99] offset:128
	s_and_saveexec_b64 s[12:13], s[6:7]
	s_cbranch_execz .LBB0_350
	v_mul_f32_e32 v32, 0x3b124925, v68
	v_cndmask_b32_e64 v34, 1.0, v32, s[8:9]
	v_add_co_u32_e32 v32, vcc, 0x4040000, v66
	s_nop 1
	v_addc_co_u32_e32 v33, vcc, 0, v67, vcc
	global_store_dword v[32:33], v34, off offset:4
.LBB0_350:
	s_or_b64 exec, exec, s[12:13]
	s_waitcnt vmcnt(3)
	v_max_f32_e64 v32, |v31|, |v31|
	v_max_f32_e64 v33, |v30|, |v30|
	v_max_f32_e32 v32, v33, v32
	v_max_f32_e64 v33, |v27|, |v27|
	v_max_f32_e64 v34, |v26|, |v26|
	v_max_f32_e32 v33, v34, v33
	v_max_f32_e64 v34, |v17|, |v17|
	v_max_f32_e64 v35, |v16|, |v16|
	v_max_f32_e32 v34, v35, v34
	v_max_f32_e64 v35, |v19|, |v19|
	v_max_f32_e64 v36, |v18|, |v18|
	v_max_f32_e32 v35, v36, v35
	s_waitcnt vmcnt(2)
	v_max_f32_e64 v36, |v23|, |v23|
	v_max_f32_e64 v37, |v22|, |v22|
	v_max_f32_e32 v36, v37, v36
	v_max3_f32 v36, |v20|, |v21|, v36
	v_max3_f32 v32, |v28|, |v29|, v32
	v_max3_f32 v33, |v24|, |v25|, v33
	v_max3_f32 v34, v34, v35, v36
	s_mov_b32 s8, 0
	v_max3_f32 v32, v32, v33, v34
	s_nop 0
	v_mbcnt_lo_u32_b32 v33, -1, s8
	v_mbcnt_hi_u32_b32 v33, -1, v33
	v_lshlrev_b32_e32 v33, 2, v33
	v_xor_b32_e32 v34, 4, v33
	ds_bpermute_b32 v34, v34, v32
	s_waitcnt lgkmcnt(0)
	v_max_f32_e32 v34, v34, v34
	v_max_f32_e32 v32, v32, v34
	v_xor_b32_e32 v34, 8, v33
	ds_bpermute_b32 v34, v34, v32
	s_waitcnt lgkmcnt(0)
	v_max_f32_e32 v34, v34, v34
	v_max_f32_e32 v32, v32, v34
	v_xor_b32_e32 v34, 16, v33
	ds_bpermute_b32 v34, v34, v32
	s_waitcnt lgkmcnt(0)
	v_max_f32_e32 v34, v34, v34
	v_max_f32_e32 v32, v32, v34
	v_xor_b32_e32 v34, 32, v33
	ds_bpermute_b32 v34, v34, v32
	s_waitcnt lgkmcnt(0)
	v_max_f32_e32 v34, v34, v34
	v_max_f32_e32 v32, v32, v34
	v_xor_b32_e32 v34, 64, v33
	ds_bpermute_b32 v34, v34, v32
	v_xor_b32_e32 v33, 0x80, v33
	s_waitcnt lgkmcnt(0)
	v_max_f32_e32 v34, v34, v34
	v_max_f32_e32 v32, v32, v34
	ds_bpermute_b32 v33, v33, v32
	s_waitcnt lgkmcnt(0)
	v_max_f32_e32 v33, v33, v33
	v_max_f32_e32 v32, v32, v33
	v_div_scale_f32 v33, s[8:9], v32, v32, s14
	v_rcp_f32_e32 v34, v33
	v_cmp_lt_f32_e64 s[8:9], 0, v32
	v_fma_f32 v35, -v33, v34, 1.0
	v_fmac_f32_e32 v34, v35, v34
	v_div_scale_f32 v35, vcc, s14, v32, s14
	v_mul_f32_e32 v36, v35, v34
	v_fma_f32 v37, -v33, v36, v35
	v_fmac_f32_e32 v36, v37, v34
	v_fma_f32 v33, -v33, v36, v35
	v_div_fmas_f32 v33, v33, v34, v36
	v_div_fixup_f32 v33, v33, v32, s14
	v_cndmask_b32_e64 v33, 1.0, v33, s[8:9]
	v_mul_f32_e32 v34, v28, v33
	v_mul_f32_e32 v29, v29, v33
	v_mov_b32_e32 v28, 0
	v_cvt_pk_fp8_f32 v28, v34, v29
	v_mul_f32_e32 v30, v30, v33
	v_mul_f32_e32 v31, v31, v33
	v_mul_f32_e32 v16, v16, v33
	v_cvt_pk_fp8_f32 v28, v30, v31 op_sel:[0,0,1]
	v_mul_f32_e32 v17, v17, v33
	v_mov_b32_e32 v30, 0
	v_mul_f32_e32 v24, v24, v33
	v_mul_f32_e32 v25, v25, v33
	v_mov_b32_e32 v29, 0
	v_cvt_pk_fp8_f32 v30, v16, v17
	v_mul_f32_e32 v16, v18, v33
	v_mul_f32_e32 v17, v19, v33
	v_mul_f32_e32 v18, v20, v33
	v_mul_f32_e32 v19, v21, v33
	v_mov_b32_e32 v31, 0
	v_cvt_pk_fp8_f32 v29, v24, v25
	v_cvt_pk_fp8_f32 v31, v18, v19
	v_mul_f32_e32 v24, v26, v33
	v_mul_f32_e32 v25, v27, v33
	v_cvt_pk_fp8_f32 v30, v16, v17 op_sel:[0,0,1]
	v_mul_f32_e32 v16, v22, v33
	v_mul_f32_e32 v17, v23, v33
	v_cvt_pk_fp8_f32 v29, v24, v25 op_sel:[0,0,1]
	v_cvt_pk_fp8_f32 v31, v16, v17 op_sel:[0,0,1]
	v_add_co_u32_e32 v16, vcc, 0x4100000, v64
	s_nop 1
	v_addc_co_u32_e32 v17, vcc, 0, v65, vcc
	s_load_dwordx2 s[98:99], s[0:1], 0x78
	s_waitcnt lgkmcnt(0)
	s_add_u32 s98, s98, 0x4100000
	s_addc_u32 s99, s99, 0
	v_subrev_u32_e32 v100, s98, v16
	v_lshrrev_b32_e32 v100, 10, v100
	v_mbcnt_lo_u32_b32 v101, -1, 0
	v_mbcnt_hi_u32_b32 v101, -1, v101
	v_and_b32_e32 v102, 7, v101
	v_lshrrev_b32_e32 v101, 3, v101
	v_lshlrev_b32_e32 v101, 21, v101
	v_lshl_or_b32 v101, v102, 4, v101
	v_lshl_add_u32 v100, v100, 7, v101
	global_store_dwordx4 v100, v[28:31], s[98:99] offset:256
	s_and_saveexec_b64 s[12:13], s[6:7]
	s_cbranch_execz .LBB0_352
	v_mul_f32_e32 v16, 0x3b124925, v32
	v_cndmask_b32_e64 v18, 1.0, v16, s[8:9]
	v_add_co_u32_e32 v16, vcc, 0x4040000, v66
	s_nop 1
	v_addc_co_u32_e32 v17, vcc, 0, v67, vcc
	global_store_dword v[16:17], v18, off offset:8
.LBB0_352:
	s_or_b64 exec, exec, s[12:13]
	v_max_f32_e64 v16, |v15|, |v15|
	v_max_f32_e64 v17, |v14|, |v14|
	v_max_f32_e32 v16, v17, v16
	v_max_f32_e64 v17, |v11|, |v11|
	v_max_f32_e64 v18, |v10|, |v10|
	v_max_f32_e32 v17, v18, v17
	v_max_f32_e64 v18, |v5|, |v5|
	v_max_f32_e64 v19, |v4|, |v4|
	v_max_f32_e32 v18, v19, v18
	v_max_f32_e64 v19, |v7|, |v7|
	v_max_f32_e64 v20, |v6|, |v6|
	v_max_f32_e32 v19, v20, v19
	v_max_f32_e64 v20, |v3|, |v3|
	v_max_f32_e64 v21, |v2|, |v2|
	v_max_f32_e32 v20, v21, v20
	v_max3_f32 v20, |v0|, |v1|, v20
	v_max3_f32 v16, |v12|, |v13|, v16
	v_max3_f32 v17, |v8|, |v9|, v17
	v_max3_f32 v18, v18, v19, v20
	s_mov_b32 s8, 0
	v_max3_f32 v16, v16, v17, v18
	s_nop 0
	v_mbcnt_lo_u32_b32 v17, -1, s8
	v_mbcnt_hi_u32_b32 v17, -1, v17
	v_lshlrev_b32_e32 v17, 2, v17
	v_xor_b32_e32 v18, 4, v17
	ds_bpermute_b32 v18, v18, v16
	s_waitcnt lgkmcnt(0)
	v_max_f32_e32 v18, v18, v18
	v_max_f32_e32 v16, v16, v18
	v_xor_b32_e32 v18, 8, v17
	ds_bpermute_b32 v18, v18, v16
	s_waitcnt lgkmcnt(0)
	v_max_f32_e32 v18, v18, v18
	v_max_f32_e32 v16, v16, v18
	v_xor_b32_e32 v18, 16, v17
	ds_bpermute_b32 v18, v18, v16
	s_waitcnt lgkmcnt(0)
	v_max_f32_e32 v18, v18, v18
	v_max_f32_e32 v16, v16, v18
	v_xor_b32_e32 v18, 32, v17
	ds_bpermute_b32 v18, v18, v16
	s_waitcnt lgkmcnt(0)
	v_max_f32_e32 v18, v18, v18
	v_max_f32_e32 v16, v16, v18
	v_xor_b32_e32 v18, 64, v17
	ds_bpermute_b32 v18, v18, v16
	v_xor_b32_e32 v17, 0x80, v17
	s_waitcnt lgkmcnt(0)
	v_max_f32_e32 v18, v18, v18
	v_max_f32_e32 v16, v16, v18
	ds_bpermute_b32 v17, v17, v16
	s_waitcnt lgkmcnt(0)
	v_max_f32_e32 v17, v17, v17
	v_max_f32_e32 v16, v16, v17
	v_div_scale_f32 v17, s[8:9], v16, v16, s14
	v_rcp_f32_e32 v18, v17
	v_cmp_lt_f32_e64 s[8:9], 0, v16
	v_fma_f32 v19, -v17, v18, 1.0
	v_fmac_f32_e32 v18, v19, v18
	v_div_scale_f32 v19, vcc, s14, v16, s14
	v_mul_f32_e32 v20, v19, v18
	v_fma_f32 v21, -v17, v20, v19
	v_fmac_f32_e32 v20, v21, v18
	v_fma_f32 v17, -v17, v20, v19
	v_div_fmas_f32 v17, v17, v18, v20
	v_div_fixup_f32 v17, v17, v16, s14
	v_cndmask_b32_e64 v17, 1.0, v17, s[8:9]
	v_mul_f32_e32 v18, v12, v17
	v_mul_f32_e32 v13, v13, v17
	v_mov_b32_e32 v12, 0
	v_cvt_pk_fp8_f32 v12, v18, v13
	v_mul_f32_e32 v14, v14, v17
	v_mul_f32_e32 v15, v15, v17
	v_mul_f32_e32 v8, v8, v17
	v_mul_f32_e32 v9, v9, v17
	v_mov_b32_e32 v13, 0
	v_cvt_pk_fp8_f32 v12, v14, v15 op_sel:[0,0,1]
	v_mul_f32_e32 v4, v4, v17
	v_mul_f32_e32 v5, v5, v17
	v_mov_b32_e32 v14, 0
	v_mul_f32_e32 v0, v0, v17
	v_mul_f32_e32 v1, v1, v17
	v_mov_b32_e32 v15, 0
	v_cvt_pk_fp8_f32 v13, v8, v9
	v_cvt_pk_fp8_f32 v14, v4, v5
	v_cvt_pk_fp8_f32 v15, v0, v1
	v_mul_f32_e32 v8, v10, v17
	v_mul_f32_e32 v9, v11, v17
	v_mul_f32_e32 v4, v6, v17
	v_mul_f32_e32 v5, v7, v17
	v_mul_f32_e32 v0, v2, v17
	v_mul_f32_e32 v1, v3, v17
	v_cvt_pk_fp8_f32 v13, v8, v9 op_sel:[0,0,1]
	v_cvt_pk_fp8_f32 v14, v4, v5 op_sel:[0,0,1]
	v_cvt_pk_fp8_f32 v15, v0, v1 op_sel:[0,0,1]
	v_add_co_u32_e32 v0, vcc, 0x4100000, v64
	s_nop 1
	v_addc_co_u32_e32 v1, vcc, 0, v65, vcc
	s_load_dwordx2 s[98:99], s[0:1], 0x78
	s_waitcnt lgkmcnt(0)
	s_add_u32 s98, s98, 0x4100000
	s_addc_u32 s99, s99, 0
	v_subrev_u32_e32 v100, s98, v0
	v_lshrrev_b32_e32 v100, 10, v100
	v_mbcnt_lo_u32_b32 v101, -1, 0
	v_mbcnt_hi_u32_b32 v101, -1, v101
	v_and_b32_e32 v102, 7, v101
	v_lshrrev_b32_e32 v101, 3, v101
	v_lshlrev_b32_e32 v101, 21, v101
	v_lshl_or_b32 v101, v102, 4, v101
	v_lshl_add_u32 v100, v100, 7, v101
	global_store_dwordx4 v100, v[12:15], s[98:99] offset:384
	s_and_saveexec_b64 s[12:13], s[6:7]
	s_cbranch_execz .LBB0_345
	v_mul_f32_e32 v0, 0x3b124925, v16
	v_cndmask_b32_e64 v2, 1.0, v0, s[8:9]
	v_add_co_u32_e32 v0, vcc, 0x4040000, v66
	s_nop 1
	v_addc_co_u32_e32 v1, vcc, 0, v67, vcc
	global_store_dword v[0:1], v2, off offset:12
	s_branch .LBB0_345

.LBB0_357:
	v_lshl_add_u64 v[0:1], v[56:57], 0, s[34:35]
	v_add_co_u32_e32 v2, vcc, 0xffffd000, v56
	global_load_dwordx4 v[60:63], v[0:1], off offset:32
	global_load_dwordx4 v[64:67], v[0:1], off offset:16
	v_addc_co_u32_e32 v3, vcc, -1, v57, vcc
	global_load_dwordx4 v[68:71], v[2:3], off offset:-60
	global_load_dwordx4 v[72:75], v[0:1], off offset:48
	v_add_co_u32_e32 v28, vcc, s3, v56
	v_lshl_add_u64 v[20:21], v[56:57], 0, s[36:37]
	s_nop 0
	v_addc_co_u32_e32 v29, vcc, -1, v57, vcc
	v_lshl_add_u64 v[22:23], v[56:57], 0, s[38:39]
	global_load_dwordx4 v[0:3], v[56:57], off offset:-12
	global_load_dwordx4 v[4:7], v[56:57], off offset:-28
	global_load_dwordx4 v[8:11], v[56:57], off offset:-44
	global_load_dwordx4 v[12:15], v[56:57], off offset:-60
	global_load_dwordx4 v[36:39], v[20:21], off offset:32
	global_load_dwordx4 v[40:43], v[20:21], off offset:16
	global_load_dwordx4 v[16:19], v[22:23], off offset:32
	global_load_dwordx4 v[24:27], v[22:23], off offset:16
	v_add_co_u32_e32 v30, vcc, s11, v56
	global_load_dwordx4 v[44:47], v[28:29], off offset:-60
	global_load_dwordx4 v[32:35], v[20:21], off offset:48
	v_addc_co_u32_e32 v31, vcc, -1, v57, vcc
	global_load_dwordx4 v[28:31], v[30:31], off offset:-60
	s_nop 0
	global_load_dwordx4 v[20:23], v[22:23], off offset:48
	s_mov_b32 s8, 0
	s_load_dwordx16 s[40:55], s[0:1], 0x40
	v_mbcnt_lo_u32_b32 v51, -1, s8
	v_mbcnt_hi_u32_b32 v51, -1, v51
	v_lshlrev_b32_e32 v51, 2, v51
	v_xor_b32_e32 v58, 4, v51
	s_waitcnt lgkmcnt(0)
	s_mov_b64 s[40:41], s[44:45]
	s_mov_b64 s[42:43], s[46:47]
	s_mov_b64 s[44:45], s[48:49]
	s_mov_b64 s[46:47], s[50:51]
	s_mov_b64 s[48:49], s[52:53]
	s_mov_b64 s[50:51], s[54:55]
	s_waitcnt vmcnt(15)
	v_max_f32_e64 v77, |v61|, |v61|
	s_waitcnt vmcnt(14)
	v_max_f32_e64 v59, |v67|, |v67|
	v_max_f32_e64 v76, |v66|, |v66|
	v_max_f32_e64 v78, |v60|, |v60|
	v_max_f32_e64 v79, |v63|, |v63|
	v_max_f32_e64 v80, |v62|, |v62|
	v_max_f32_e32 v59, v76, v59
	v_max_f32_e32 v76, v78, v77
	v_max_f32_e32 v77, v80, v79
	s_waitcnt vmcnt(12)
	v_max_f32_e64 v78, |v75|, |v75|
	v_max_f32_e64 v79, |v74|, |v74|
	v_max_f32_e64 v81, |v71|, |v71|
	v_max_f32_e64 v82, |v70|, |v70|
	v_max_f32_e32 v78, v79, v78
	v_max_f32_e32 v80, v82, v81
	v_max3_f32 v78, |v72|, |v73|, v78
	v_max3_f32 v59, |v64|, |v65|, v59
	v_max3_f32 v79, |v68|, |v69|, v80
	v_max3_f32 v76, v76, v77, v78
	v_max3_f32 v59, v79, v59, v76
	ds_bpermute_b32 v58, v58, v59
	v_xor_b32_e32 v76, 8, v51
	v_mov_b32_e32 v77, 0
	v_mov_b32_e32 v78, 0
	v_mov_b32_e32 v79, 0
	s_waitcnt lgkmcnt(0)
	v_max_f32_e32 v58, v58, v58
	v_max_f32_e32 v58, v59, v58
	ds_bpermute_b32 v59, v76, v58
	v_xor_b32_e32 v76, 16, v51
	s_waitcnt lgkmcnt(0)
	v_max_f32_e32 v59, v59, v59
	v_max_f32_e32 v58, v58, v59
	ds_bpermute_b32 v59, v76, v58
	v_xor_b32_e32 v76, 32, v51
	s_waitcnt lgkmcnt(0)
	v_max_f32_e32 v59, v59, v59
	v_max_f32_e32 v58, v58, v59
	ds_bpermute_b32 v59, v76, v58
	v_xor_b32_e32 v76, 64, v51
	v_xor_b32_e32 v51, 0x80, v51
	s_waitcnt lgkmcnt(0)
	v_max_f32_e32 v59, v59, v59
	v_max_f32_e32 v58, v58, v59
	ds_bpermute_b32 v59, v76, v58
	v_mov_b32_e32 v76, 0
	s_waitcnt lgkmcnt(0)
	v_max_f32_e32 v59, v59, v59
	v_max_f32_e32 v58, v58, v59
	ds_bpermute_b32 v51, v51, v58
	s_waitcnt lgkmcnt(0)
	v_max_f32_e32 v51, v51, v51
	v_max_f32_e32 v51, v58, v51
	v_div_scale_f32 v80, s[8:9], v51, v51, s14
	v_rcp_f32_e32 v81, v80
	v_div_scale_f32 v82, vcc, s14, v51, s14
	v_cmp_lt_f32_e64 s[8:9], 0, v51
	v_fma_f32 v83, -v80, v81, 1.0
	v_fmac_f32_e32 v81, v83, v81
	v_mul_f32_e32 v83, v82, v81
	v_fma_f32 v84, -v80, v83, v82
	v_fmac_f32_e32 v83, v84, v81
	v_fma_f32 v80, -v80, v83, v82
	v_div_fmas_f32 v81, v80, v81, v83
	v_div_fixup_f32 v81, v81, v51, s14
	v_cndmask_b32_e64 v81, 1.0, v81, s[8:9]
	v_mul_f32_e32 v68, v68, v81
	v_mul_f32_e32 v69, v69, v81
	v_mul_f32_e32 v64, v64, v81
	v_mul_f32_e32 v65, v65, v81
	v_mul_f32_e32 v60, v60, v81
	v_mul_f32_e32 v61, v61, v81
	v_mul_f32_e32 v72, v72, v81
	v_mul_f32_e32 v73, v73, v81
	v_cvt_pk_fp8_f32 v76, v68, v69
	v_cvt_pk_fp8_f32 v77, v64, v65
	v_cvt_pk_fp8_f32 v78, v60, v61
	v_cvt_pk_fp8_f32 v79, v72, v73
	v_mul_f32_e32 v70, v70, v81
	v_mul_f32_e32 v71, v71, v81
	v_mul_f32_e32 v66, v66, v81
	v_mul_f32_e32 v67, v67, v81
	v_mul_f32_e32 v62, v62, v81
	v_mul_f32_e32 v63, v63, v81
	v_mul_f32_e32 v74, v74, v81
	v_mul_f32_e32 v75, v75, v81
	v_cvt_pk_fp8_f32 v76, v70, v71 op_sel:[0,0,1]
	v_cvt_pk_fp8_f32 v77, v66, v67 op_sel:[0,0,1]
	v_cvt_pk_fp8_f32 v78, v62, v63 op_sel:[0,0,1]
	v_cvt_pk_fp8_f32 v79, v74, v75 op_sel:[0,0,1]
	v_lshl_add_u64 v[58:59], s[50:51], 0, v[54:55]
	v_add_co_u32_e32 v80, vcc, 0x6100000, v58
	v_lshl_add_u64 v[60:61], s[50:51], 0, v[52:53]
	s_nop 0
	v_addc_co_u32_e32 v81, vcc, 0, v59, vcc
	s_load_dwordx2 s[98:99], s[0:1], 0x78
	s_waitcnt lgkmcnt(0)
	s_add_u32 s98, s98, 0x6100000
	s_addc_u32 s99, s99, 0
	v_subrev_u32_e32 v100, s98, v80
	v_lshrrev_b32_e32 v100, 10, v100
	v_mbcnt_lo_u32_b32 v101, -1, 0
	v_mbcnt_hi_u32_b32 v101, -1, v101
	v_and_b32_e32 v102, 7, v101
	v_lshrrev_b32_e32 v101, 3, v101
	v_lshlrev_b32_e32 v101, 21, v101
	v_lshl_or_b32 v101, v102, 4, v101
	v_lshl_add_u32 v100, v100, 7, v101
	global_store_dwordx4 v100, v[76:79], s[98:99]
	s_and_saveexec_b64 s[12:13], s[6:7]
	s_cbranch_execz .LBB0_359
	v_mul_f32_e32 v51, 0x3b124925, v51
	v_add_co_u32_e32 v62, vcc, 0x4080000, v60
	v_cndmask_b32_e64 v51, 1.0, v51, s[8:9]
	s_nop 0
	v_addc_co_u32_e32 v63, vcc, 0, v61, vcc
	global_store_dword v[62:63], v51, off
.LBB0_359:
	s_or_b64 exec, exec, s[12:13]
	s_waitcnt vmcnt(4)
	v_max_f32_e64 v51, |v47|, |v47|
	v_max_f32_e64 v62, |v46|, |v46|
	v_max_f32_e32 v51, v62, v51
	v_max_f32_e64 v62, |v43|, |v43|
	v_max_f32_e64 v63, |v42|, |v42|
	v_max_f32_e32 v62, v63, v62
	v_max_f32_e64 v63, |v37|, |v37|
	v_max_f32_e64 v64, |v36|, |v36|
	v_max_f32_e32 v63, v64, v63
	v_max_f32_e64 v64, |v39|, |v39|
	v_max_f32_e64 v65, |v38|, |v38|
	v_max_f32_e32 v64, v65, v64
	s_waitcnt vmcnt(3)
	v_max_f32_e64 v65, |v35|, |v35|
	v_max_f32_e64 v66, |v34|, |v34|
	v_max_f32_e32 v65, v66, v65
	v_max3_f32 v65, |v32|, |v33|, v65
	v_max3_f32 v51, |v44|, |v45|, v51
	v_max3_f32 v62, |v40|, |v41|, v62
	v_max3_f32 v63, v63, v64, v65
	s_mov_b32 s8, 0
	v_max3_f32 v51, v51, v62, v63
	s_nop 0
	v_mbcnt_lo_u32_b32 v62, -1, s8
	v_mbcnt_hi_u32_b32 v62, -1, v62
	v_lshlrev_b32_e32 v62, 2, v62
	v_xor_b32_e32 v63, 4, v62
	ds_bpermute_b32 v63, v63, v51
	s_waitcnt lgkmcnt(0)
	v_max_f32_e32 v63, v63, v63
	v_max_f32_e32 v51, v51, v63
	v_xor_b32_e32 v63, 8, v62
	ds_bpermute_b32 v63, v63, v51
	s_waitcnt lgkmcnt(0)
	v_max_f32_e32 v63, v63, v63
	v_max_f32_e32 v51, v51, v63
	v_xor_b32_e32 v63, 16, v62
	ds_bpermute_b32 v63, v63, v51
	s_waitcnt lgkmcnt(0)
	v_max_f32_e32 v63, v63, v63
	v_max_f32_e32 v51, v51, v63
	v_xor_b32_e32 v63, 32, v62
	ds_bpermute_b32 v63, v63, v51
	s_waitcnt lgkmcnt(0)
	v_max_f32_e32 v63, v63, v63
	v_max_f32_e32 v51, v51, v63
	v_xor_b32_e32 v63, 64, v62
	ds_bpermute_b32 v63, v63, v51
	v_xor_b32_e32 v62, 0x80, v62
	s_waitcnt lgkmcnt(0)
	v_max_f32_e32 v63, v63, v63
	v_max_f32_e32 v51, v51, v63
	ds_bpermute_b32 v62, v62, v51
	s_waitcnt lgkmcnt(0)
	v_max_f32_e32 v62, v62, v62
	v_max_f32_e32 v51, v51, v62
	v_div_scale_f32 v62, s[8:9], v51, v51, s14
	v_rcp_f32_e32 v63, v62
	v_cmp_lt_f32_e64 s[8:9], 0, v51
	v_fma_f32 v64, -v62, v63, 1.0
	v_fmac_f32_e32 v63, v64, v63
	v_div_scale_f32 v64, vcc, s14, v51, s14
	v_mul_f32_e32 v65, v64, v63
	v_fma_f32 v66, -v62, v65, v64
	v_fmac_f32_e32 v65, v66, v63
	v_fma_f32 v62, -v62, v65, v64
	v_div_fmas_f32 v62, v62, v63, v65
	v_div_fixup_f32 v62, v62, v51, s14
	v_cndmask_b32_e64 v62, 1.0, v62, s[8:9]
	v_mul_f32_e32 v63, v44, v62
	v_mul_f32_e32 v45, v45, v62
	v_mov_b32_e32 v44, 0
	v_cvt_pk_fp8_f32 v44, v63, v45
	v_mul_f32_e32 v46, v46, v62
	v_mul_f32_e32 v47, v47, v62
	v_mul_f32_e32 v40, v40, v62
	v_mul_f32_e32 v41, v41, v62
	v_mov_b32_e32 v45, 0
	v_cvt_pk_fp8_f32 v44, v46, v47 op_sel:[0,0,1]
	v_mul_f32_e32 v36, v36, v62
	v_mul_f32_e32 v37, v37, v62
	v_mov_b32_e32 v46, 0
	v_mul_f32_e32 v32, v32, v62
	v_mul_f32_e32 v33, v33, v62
	v_mov_b32_e32 v47, 0
	v_cvt_pk_fp8_f32 v45, v40, v41
	v_cvt_pk_fp8_f32 v46, v36, v37
	v_cvt_pk_fp8_f32 v47, v32, v33
	v_mul_f32_e32 v40, v42, v62
	v_mul_f32_e32 v41, v43, v62
	v_mul_f32_e32 v36, v38, v62
	v_mul_f32_e32 v37, v39, v62
	v_mul_f32_e32 v32, v34, v62
	v_mul_f32_e32 v33, v35, v62
	v_cvt_pk_fp8_f32 v45, v40, v41 op_sel:[0,0,1]
	v_cvt_pk_fp8_f32 v46, v36, v37 op_sel:[0,0,1]
	v_cvt_pk_fp8_f32 v47, v32, v33 op_sel:[0,0,1]
	v_add_co_u32_e32 v32, vcc, 0x6100000, v58
	s_nop 1
	v_addc_co_u32_e32 v33, vcc, 0, v59, vcc
	s_load_dwordx2 s[98:99], s[0:1], 0x78
	s_waitcnt lgkmcnt(0)
	s_add_u32 s98, s98, 0x6100000
	s_addc_u32 s99, s99, 0
	v_subrev_u32_e32 v100, s98, v32
	v_lshrrev_b32_e32 v100, 10, v100
	v_mbcnt_lo_u32_b32 v101, -1, 0
	v_mbcnt_hi_u32_b32 v101, -1, v101
	v_and_b32_e32 v102, 7, v101
	v_lshrrev_b32_e32 v101, 3, v101
	v_lshlrev_b32_e32 v101, 21, v101
	v_lshl_or_b32 v101, v102, 4, v101
	v_lshl_add_u32 v100, v100, 7, v101
	global_store_dwordx4 v100, v[44:47], s[98:99] offset:128
	s_and_saveexec_b64 s[12:13], s[6:7]
	s_cbranch_execz .LBB0_361
	v_mul_f32_e32 v32, 0x3b124925, v51
	v_cndmask_b32_e64 v34, 1.0, v32, s[8:9]
	v_add_co_u32_e32 v32, vcc, 0x4080000, v60
	s_nop 1
	v_addc_co_u32_e32 v33, vcc, 0, v61, vcc
	global_store_dword v[32:33], v34, off offset:4
.LBB0_361:
	s_or_b64 exec, exec, s[12:13]
	s_waitcnt vmcnt(3)
	v_max_f32_e64 v32, |v31|, |v31|
	v_max_f32_e64 v33, |v30|, |v30|
	v_max_f32_e32 v32, v33, v32
	v_max_f32_e64 v33, |v27|, |v27|
	v_max_f32_e64 v34, |v26|, |v26|
	v_max_f32_e32 v33, v34, v33
	v_max_f32_e64 v34, |v17|, |v17|
	v_max_f32_e64 v35, |v16|, |v16|
	v_max_f32_e32 v34, v35, v34
	v_max_f32_e64 v35, |v19|, |v19|
	v_max_f32_e64 v36, |v18|, |v18|
	v_max_f32_e32 v35, v36, v35
	s_waitcnt vmcnt(2)
	v_max_f32_e64 v36, |v23|, |v23|
	v_max_f32_e64 v37, |v22|, |v22|
	v_max_f32_e32 v36, v37, v36
	v_max3_f32 v36, |v20|, |v21|, v36
	v_max3_f32 v32, |v28|, |v29|, v32
	v_max3_f32 v33, |v24|, |v25|, v33
	v_max3_f32 v34, v34, v35, v36
	s_mov_b32 s8, 0
	v_max3_f32 v32, v32, v33, v34
	s_nop 0
	v_mbcnt_lo_u32_b32 v33, -1, s8
	v_mbcnt_hi_u32_b32 v33, -1, v33
	v_lshlrev_b32_e32 v33, 2, v33
	v_xor_b32_e32 v34, 4, v33
	ds_bpermute_b32 v34, v34, v32
	s_waitcnt lgkmcnt(0)
	v_max_f32_e32 v34, v34, v34
	v_max_f32_e32 v32, v32, v34
	v_xor_b32_e32 v34, 8, v33
	ds_bpermute_b32 v34, v34, v32
	s_waitcnt lgkmcnt(0)
	v_max_f32_e32 v34, v34, v34
	v_max_f32_e32 v32, v32, v34
	v_xor_b32_e32 v34, 16, v33
	ds_bpermute_b32 v34, v34, v32
	s_waitcnt lgkmcnt(0)
	v_max_f32_e32 v34, v34, v34
	v_max_f32_e32 v32, v32, v34
	v_xor_b32_e32 v34, 32, v33
	ds_bpermute_b32 v34, v34, v32
	s_waitcnt lgkmcnt(0)
	v_max_f32_e32 v34, v34, v34
	v_max_f32_e32 v32, v32, v34
	v_xor_b32_e32 v34, 64, v33
	ds_bpermute_b32 v34, v34, v32
	v_xor_b32_e32 v33, 0x80, v33
	s_waitcnt lgkmcnt(0)
	v_max_f32_e32 v34, v34, v34
	v_max_f32_e32 v32, v32, v34
	ds_bpermute_b32 v33, v33, v32
	s_waitcnt lgkmcnt(0)
	v_max_f32_e32 v33, v33, v33
	v_max_f32_e32 v32, v32, v33
	v_div_scale_f32 v33, s[8:9], v32, v32, s14
	v_rcp_f32_e32 v34, v33
	v_cmp_lt_f32_e64 s[8:9], 0, v32
	v_fma_f32 v35, -v33, v34, 1.0
	v_fmac_f32_e32 v34, v35, v34
	v_div_scale_f32 v35, vcc, s14, v32, s14
	v_mul_f32_e32 v36, v35, v34
	v_fma_f32 v37, -v33, v36, v35
	v_fmac_f32_e32 v36, v37, v34
	v_fma_f32 v33, -v33, v36, v35
	v_div_fmas_f32 v33, v33, v34, v36
	v_div_fixup_f32 v33, v33, v32, s14
	v_cndmask_b32_e64 v33, 1.0, v33, s[8:9]
	v_mul_f32_e32 v34, v28, v33
	v_mul_f32_e32 v29, v29, v33
	v_mov_b32_e32 v28, 0
	v_cvt_pk_fp8_f32 v28, v34, v29
	v_mul_f32_e32 v30, v30, v33
	v_mul_f32_e32 v31, v31, v33
	v_mul_f32_e32 v16, v16, v33
	v_cvt_pk_fp8_f32 v28, v30, v31 op_sel:[0,0,1]
	v_mul_f32_e32 v17, v17, v33
	v_mov_b32_e32 v30, 0
	v_mul_f32_e32 v24, v24, v33
	v_mul_f32_e32 v25, v25, v33
	v_mov_b32_e32 v29, 0
	v_cvt_pk_fp8_f32 v30, v16, v17
	v_mul_f32_e32 v16, v18, v33
	v_mul_f32_e32 v17, v19, v33
	v_mul_f32_e32 v18, v20, v33
	v_mul_f32_e32 v19, v21, v33
	v_mov_b32_e32 v31, 0
	v_cvt_pk_fp8_f32 v29, v24, v25
	v_cvt_pk_fp8_f32 v31, v18, v19
	v_mul_f32_e32 v24, v26, v33
	v_mul_f32_e32 v25, v27, v33
	v_cvt_pk_fp8_f32 v30, v16, v17 op_sel:[0,0,1]
	v_mul_f32_e32 v16, v22, v33
	v_mul_f32_e32 v17, v23, v33
	v_cvt_pk_fp8_f32 v29, v24, v25 op_sel:[0,0,1]
	v_cvt_pk_fp8_f32 v31, v16, v17 op_sel:[0,0,1]
	v_add_co_u32_e32 v16, vcc, 0x6100000, v58
	s_nop 1
	v_addc_co_u32_e32 v17, vcc, 0, v59, vcc
	s_load_dwordx2 s[98:99], s[0:1], 0x78
	s_waitcnt lgkmcnt(0)
	s_add_u32 s98, s98, 0x6100000
	s_addc_u32 s99, s99, 0
	v_subrev_u32_e32 v100, s98, v16
	v_lshrrev_b32_e32 v100, 10, v100
	v_mbcnt_lo_u32_b32 v101, -1, 0
	v_mbcnt_hi_u32_b32 v101, -1, v101
	v_and_b32_e32 v102, 7, v101
	v_lshrrev_b32_e32 v101, 3, v101
	v_lshlrev_b32_e32 v101, 21, v101
	v_lshl_or_b32 v101, v102, 4, v101
	v_lshl_add_u32 v100, v100, 7, v101
	global_store_dwordx4 v100, v[28:31], s[98:99] offset:256
	s_and_saveexec_b64 s[12:13], s[6:7]
	s_cbranch_execz .LBB0_363
	v_mul_f32_e32 v16, 0x3b124925, v32
	v_cndmask_b32_e64 v18, 1.0, v16, s[8:9]
	v_add_co_u32_e32 v16, vcc, 0x4080000, v60
	s_nop 1
	v_addc_co_u32_e32 v17, vcc, 0, v61, vcc
	global_store_dword v[16:17], v18, off offset:8
.LBB0_363:
	s_or_b64 exec, exec, s[12:13]
	v_max_f32_e64 v16, |v15|, |v15|
	v_max_f32_e64 v17, |v14|, |v14|
	v_max_f32_e32 v16, v17, v16
	v_max_f32_e64 v17, |v11|, |v11|
	v_max_f32_e64 v18, |v10|, |v10|
	v_max_f32_e32 v17, v18, v17
	v_max_f32_e64 v18, |v5|, |v5|
	v_max_f32_e64 v19, |v4|, |v4|
	v_max_f32_e32 v18, v19, v18
	v_max_f32_e64 v19, |v7|, |v7|
	v_max_f32_e64 v20, |v6|, |v6|
	v_max_f32_e32 v19, v20, v19
	v_max_f32_e64 v20, |v3|, |v3|
	v_max_f32_e64 v21, |v2|, |v2|
	v_max_f32_e32 v20, v21, v20
	v_max3_f32 v20, |v0|, |v1|, v20
	v_max3_f32 v16, |v12|, |v13|, v16
	v_max3_f32 v17, |v8|, |v9|, v17
	v_max3_f32 v18, v18, v19, v20
	s_mov_b32 s8, 0
	v_max3_f32 v16, v16, v17, v18
	s_nop 0
	v_mbcnt_lo_u32_b32 v17, -1, s8
	v_mbcnt_hi_u32_b32 v17, -1, v17
	v_lshlrev_b32_e32 v17, 2, v17
	v_xor_b32_e32 v18, 4, v17
	ds_bpermute_b32 v18, v18, v16
	s_waitcnt lgkmcnt(0)
	v_max_f32_e32 v18, v18, v18
	v_max_f32_e32 v16, v16, v18
	v_xor_b32_e32 v18, 8, v17
	ds_bpermute_b32 v18, v18, v16
	s_waitcnt lgkmcnt(0)
	v_max_f32_e32 v18, v18, v18
	v_max_f32_e32 v16, v16, v18
	v_xor_b32_e32 v18, 16, v17
	ds_bpermute_b32 v18, v18, v16
	s_waitcnt lgkmcnt(0)
	v_max_f32_e32 v18, v18, v18
	v_max_f32_e32 v16, v16, v18
	v_xor_b32_e32 v18, 32, v17
	ds_bpermute_b32 v18, v18, v16
	s_waitcnt lgkmcnt(0)
	v_max_f32_e32 v18, v18, v18
	v_max_f32_e32 v16, v16, v18
	v_xor_b32_e32 v18, 64, v17
	ds_bpermute_b32 v18, v18, v16
	v_xor_b32_e32 v17, 0x80, v17
	s_waitcnt lgkmcnt(0)
	v_max_f32_e32 v18, v18, v18
	v_max_f32_e32 v16, v16, v18
	ds_bpermute_b32 v17, v17, v16
	s_waitcnt lgkmcnt(0)
	v_max_f32_e32 v17, v17, v17
	v_max_f32_e32 v16, v16, v17
	v_div_scale_f32 v17, s[8:9], v16, v16, s14
	v_rcp_f32_e32 v18, v17
	v_cmp_lt_f32_e64 s[8:9], 0, v16
	v_fma_f32 v19, -v17, v18, 1.0
	v_fmac_f32_e32 v18, v19, v18
	v_div_scale_f32 v19, vcc, s14, v16, s14
	v_mul_f32_e32 v20, v19, v18
	v_fma_f32 v21, -v17, v20, v19
	v_fmac_f32_e32 v20, v21, v18
	v_fma_f32 v17, -v17, v20, v19
	v_div_fmas_f32 v17, v17, v18, v20
	v_div_fixup_f32 v17, v17, v16, s14
	v_cndmask_b32_e64 v17, 1.0, v17, s[8:9]
	v_mul_f32_e32 v18, v12, v17
	v_mul_f32_e32 v13, v13, v17
	v_mov_b32_e32 v12, 0
	v_cvt_pk_fp8_f32 v12, v18, v13
	v_mul_f32_e32 v14, v14, v17
	v_mul_f32_e32 v15, v15, v17
	v_mul_f32_e32 v8, v8, v17
	v_mul_f32_e32 v9, v9, v17
	v_mov_b32_e32 v13, 0
	v_cvt_pk_fp8_f32 v12, v14, v15 op_sel:[0,0,1]
	v_mul_f32_e32 v4, v4, v17
	v_mul_f32_e32 v5, v5, v17
	v_mov_b32_e32 v14, 0
	v_mul_f32_e32 v0, v0, v17
	v_mul_f32_e32 v1, v1, v17
	v_mov_b32_e32 v15, 0
	v_cvt_pk_fp8_f32 v13, v8, v9
	v_cvt_pk_fp8_f32 v14, v4, v5
	v_cvt_pk_fp8_f32 v15, v0, v1
	v_mul_f32_e32 v8, v10, v17
	v_mul_f32_e32 v9, v11, v17
	v_mul_f32_e32 v4, v6, v17
	v_mul_f32_e32 v5, v7, v17
	v_mul_f32_e32 v0, v2, v17
	v_mul_f32_e32 v1, v3, v17
	v_cvt_pk_fp8_f32 v13, v8, v9 op_sel:[0,0,1]
	v_cvt_pk_fp8_f32 v14, v4, v5 op_sel:[0,0,1]
	v_cvt_pk_fp8_f32 v15, v0, v1 op_sel:[0,0,1]
	v_add_co_u32_e32 v0, vcc, 0x6100000, v58
	s_nop 1
	v_addc_co_u32_e32 v1, vcc, 0, v59, vcc
	s_load_dwordx2 s[98:99], s[0:1], 0x78
	s_waitcnt lgkmcnt(0)
	s_add_u32 s98, s98, 0x6100000
	s_addc_u32 s99, s99, 0
	v_subrev_u32_e32 v100, s98, v0
	v_lshrrev_b32_e32 v100, 10, v100
	v_mbcnt_lo_u32_b32 v101, -1, 0
	v_mbcnt_hi_u32_b32 v101, -1, v101
	v_and_b32_e32 v102, 7, v101
	v_lshrrev_b32_e32 v101, 3, v101
	v_lshlrev_b32_e32 v101, 21, v101
	v_lshl_or_b32 v101, v102, 4, v101
	v_lshl_add_u32 v100, v100, 7, v101
	global_store_dwordx4 v100, v[12:15], s[98:99] offset:384
	s_and_saveexec_b64 s[12:13], s[6:7]
	s_cbranch_execz .LBB0_356
	v_mul_f32_e32 v0, 0x3b124925, v16
	v_cndmask_b32_e64 v2, 1.0, v0, s[8:9]
	v_add_co_u32_e32 v0, vcc, 0x4080000, v60
	s_nop 1
	v_addc_co_u32_e32 v1, vcc, 0, v61, vcc
	global_store_dword v[0:1], v2, off offset:12
	s_branch .LBB0_356
